# v18: attention K/V/rope-K tile staging by direct HBM->LDS loads (global_load_lds, swizzles folded into the per-lane source offsets); ds_write staging and the mid-segment vmcnt(0) removed
# speedup vs baseline: 1.0451x; 1.0120x over previous
; #define LAS __attribute__((address_space(3)))
; __device__ __forceinline__ int opaque_tid(int wv) { return wv * 64 + opaque_lane(); }
; __device__ __forceinline__ int v_st(int k, int c) { const int kk = (k & ~0xC) | ((k & 4) << 1) | ((k & 8) >> 1); return ((kk >> 3) * 4 + (c >> 5)) * 512 + ((kk & 7) * 32 + (c & 31)) * 2; }
; __device__ __forceinline__ int v_rd_base(int lane) { return ((lane & 3) << 3) | (((lane >> 2) & 3) << 6) | (((lane >> 4) & 1) << 5) | (((lane >> 5) & 1) << 8); }
; #define SWRITE(b) do { *(bf16x8*)(V_lds + (b) * SHM_V + vst0) = vs0; *(bf16x8*)(V_lds + (b) * SHM_V + vst1) = vs1; const int kc = sc * 2; \
;     *(bf16x8*)(K_lds + (b) * SHM_K + KSWZ(sr, kc)) = ks0; *(bf16x8*)(K_lds + (b) * SHM_K + KSWZ(32 + sr, kc)) = ks1; \
;     *(bf16x8*)(R_lds + (b) * SHM_R + RSWZ(rr, rc * 2)) = rs0; } while (0)
; #define SWAIT() asm volatile("s_waitcnt vmcnt(0)" ::: "memory")
; __device__ __forceinline__ void attn_body(const bf16_t* __restrict__ Qb, const bf16_t* __restrict__ Kh, const bf16_t* __restrict__ Vh, const bf16_t* __restrict__ Rh,
;                                           bf16_t* __restrict__ Zb, int seq, char* lds, int wv, bool nowrite) {
;     const int tid = opaque_tid(wv), wid = wv, lane = tid & 63, r32 = lane & 31, hi = lane >> 5;
;     char* V_lds = lds + OFF_V; char* K_lds = lds + OFF_K; char* R_lds = lds + OFF_R;
;     float* ws = (float*)(lds + OFF_WS) + wid * 64; float* li_l = ws; float* al_l = ws + 32;
;     float m_reg = -1e30f, l_reg = 0; f32x16 o[4] = {}; bf16x8 qr[8];
;     const bf16_t* Qw = Qb + (long)(wid * QBLK + r32) * LDQ + hi * 8;
;     char* Qp = lds + OFF_QR + wid * 4096;
; #pragma unroll
;     for (int d0 = 0; d0 < 8; ++d0) qr[d0] = *reinterpret_cast<const bf16x8*>(Qw + d0 * 16);
; #pragma unroll
;     for (int d0 = 0; d0 < 4; ++d0) *reinterpret_cast<bf16x8*>(Qp + RSWZ(r32, (d0 * 16 + hi * 8) * 2)) = *reinterpret_cast<const bf16x8*>(Qw + 128 + d0 * 16);
;     const int sr = tid >> 4, sc = (tid & 15) * 8, vst0 = v_st(sr, sc), vst1 = v_st(32 + sr, sc);
;     const int rr = tid >> 3, rc = (tid & 7) * 8;
;     const int vb0 = (int)(uintptr_t)(LAS char*)V_lds + v_rd_base(lane);
;     bf16x8 vs0, vs1, ks0, ks1, rs0;
;     ...
;     f32x16 pA0, pA1, pB0, pB1; float mnA, mnB, alA, alB; bf16x8 pa0, pa1, pa2, pa3; const int NT = seq / KVBLK;
;     SLOAD(0); SWAIT(); SWRITE(0); __syncthreads();
.LBB0_607:
	s_ashr_i32 s56, s3, 4
	s_ashr_i32 s57, s56, 31
	s_and_b32 s8, s3, 15
	s_lshl_b64 s[6:7], s[56:57], 11
	s_add_u32 s42, s6, s68
	s_addc_u32 s43, s7, 0
	s_lshl_b32 s2, s2, 8
	s_and_b32 s24, s2, 0x700
	s_or_b32 s2, s6, s24
	s_mul_i32 s3, s7, 0x1800
	s_mul_hi_u32 s6, s2, 0x1800
	s_add_i32 s6, s6, s3
	s_mulk_i32 s2, 0x1800
	s_add_u32 s2, s35, s2
	s_addc_u32 s3, s50, s6
	s_mul_i32 s6, s8, 0x180
	s_add_u32 s2, s2, s6
	v_mov_b32_e32 v57, v233
	s_addc_u32 s3, s3, 0
	v_mov_b64_e32 v[0:1], s[2:3]
	v_and_b32_e32 v164, 31, v57
	v_bfe_u32 v165, v57, 5, 1
	v_or_b32_e32 v2, s52, v164
	v_mad_u64_u32 v[0:1], s[2:3], v2, s85, v[0:1]
	v_lshlrev_b32_e32 v212, 4, v165
	v_lshl_add_u64 v[36:37], v[0:1], 0, v[212:213]
	global_load_dwordx4 v[0:3], v[36:37], off offset:256
	global_load_dwordx4 v[4:7], v[36:37], off offset:288
	global_load_dwordx4 v[8:11], v[36:37], off offset:320
	global_load_dwordx4 v[12:15], v[36:37], off offset:352
	s_lshl_b64 s[60:61], s[56:57], 23
	s_add_u32 s6, s51, s60
	s_addc_u32 s7, s64, s61
	s_lshl_b32 s2, s8, 7
	s_lshl_b32 s3, s8, 8
	s_add_u32 s6, s6, s3
	s_addc_u32 s7, s7, 0
	s_add_u32 s8, s65, s60
	v_add_u32_e32 v56, s75, v57
	s_addc_u32 s9, s70, s61
	v_ashrrev_i32_e32 v38, 4, v56
	s_add_u32 s62, s8, s3
	v_lshlrev_b32_e32 v46, 3, v56
	v_add_u32_e32 v40, 32, v38
	s_addc_u32 s63, s9, 0
	s_lshl_b64 s[8:9], s[42:43], 7
	v_and_b32_e32 v16, 0x78, v46
	v_ashrrev_i32_e32 v39, 31, v38
	v_ashrrev_i32_e32 v41, 31, v40
	v_ashrrev_i32_e32 v42, 3, v56
	s_add_u32 s8, s71, s8
	v_lshlrev_b32_e32 v47, 1, v16
	v_lshlrev_b64 v[48:49], 12, v[38:39]
	v_lshlrev_b64 v[24:25], 12, v[40:41]
	v_ashrrev_i32_e32 v43, 31, v42
	v_or_b32_e32 v52, v48, v47
	v_mov_b32_e32 v53, v49
	v_or_b32_e32 v24, v24, v47
	s_addc_u32 s9, s76, s9
	v_lshlrev_b64 v[50:51], 7, v[42:43]
	v_lshlrev_b32_e32 v75, 4, v56
	v_lshl_add_u64 v[16:17], s[62:63], 0, v[52:53]
	v_lshl_add_u64 v[20:21], s[62:63], 0, v[24:25]
	v_lshl_add_u64 v[26:27], s[6:7], 0, v[52:53]
	v_lshl_add_u64 v[28:29], s[6:7], 0, v[24:25]
	v_lshl_add_u64 v[32:33], s[8:9], 0, v[50:51]
	v_and_b32_e32 v44, 0x70, v75
	v_mov_b32_e32 v45, v213
	global_load_dwordx4 v[16:19], v[16:17], off
	v_lshl_add_u64 v[54:55], v[32:33], 0, v[44:45]
	global_load_dwordx4 v[20:23], v[20:21], off
	s_nop 0
	global_load_dwordx4 v[24:27], v[26:27], off
	s_nop 0
	global_load_dwordx4 v[28:31], v[28:29], off
	s_nop 0
	global_load_dwordx4 v[32:35], v[54:55], off
	global_load_dwordx4 v[120:123], v[36:37], off
	global_load_dwordx4 v[124:127], v[36:37], off offset:32
	global_load_dwordx4 v[116:119], v[36:37], off offset:64
	global_load_dwordx4 v[112:115], v[36:37], off offset:96
	global_load_dwordx4 v[108:111], v[36:37], off offset:128
	global_load_dwordx4 v[104:107], v[36:37], off offset:160
	global_load_dwordx4 v[100:103], v[36:37], off offset:192
	global_load_dwordx4 v[96:99], v[36:37], off offset:224
	v_lshlrev_b32_e32 v39, 3, v57
	v_lshlrev_b32_e32 v58, 7, v164
	v_and_b32_e32 v59, 0x70, v39
	v_add_u32_e32 v41, s96, v58
	v_bitop3_b32 v39, v212, v39, s66 bitop3:0x78
	v_bitop3_b32 v43, v212, v59, 32 bitop3:0x36
	v_bitop3_b32 v45, v212, v59, 64 bitop3:0x36
	v_add_u32_e32 v39, v41, v39
	v_add_u32_e32 v43, v41, v43
	v_add_u32_e32 v45, v41, v45
	v_lshlrev_b32_e32 v60, 4, v57
	s_add_i32 s8, 0, 0x10000
	v_or_b32_e32 v61, 64, v212
	v_or_b32_e32 v62, 0x60, v212
	v_bitop3_b32 v186, v212, v58, v59 bitop3:0xde
	v_add_u32_e32 v187, s8, v186
	v_add_u32_e32 v177, s96, v186
	v_and_b32_e32 v77, 63, v57
	v_bitop3_b32 v190, v61, v58, v59 bitop3:0xde
	v_add_u32_e32 v191, s8, v190
	v_add_u32_e32 v178, s96, v190
	v_bitop3_b32 v192, v62, v58, v59 bitop3:0xde
	s_waitcnt vmcnt(0)
	ds_write_b128 v39, v[0:3]
	ds_write_b128 v43, v[4:7]
	ds_write_b128 v45, v[8:11]
	v_bitop3_b32 v0, v212, v59, s31 bitop3:0x36
	v_add_u32_e32 v0, v41, v0
	ds_write_b128 v0, v[12:15]
	v_and_b32_e32 v0, 0xfffff0, v38
	v_lshlrev_b32_e32 v1, 1, v38
	v_and_b32_e32 v4, 0xfffff0, v40
	v_lshlrev_b32_e32 v5, 1, v40
	v_and_or_b32 v0, v1, 8, v0
	v_and_or_b32 v4, v5, 8, v4
	v_lshrrev_b32_e32 v1, 1, v38
	v_lshrrev_b32_e32 v0, 1, v0
	v_bfe_u32 v2, v46, 5, 2
	v_and_b32_e32 v3, 3, v38
	v_lshrrev_b32_e32 v4, 1, v4
	v_or_b32_e32 v0, v0, v2
	v_and_or_b32 v1, v1, 4, v3
	v_or_b32_e32 v2, v4, v2
	v_lshlrev_b32_e32 v0, 9, v0
	v_lshlrev_b32_e32 v1, 6, v1
	v_and_b32_e32 v3, 48, v47
	v_lshlrev_b32_e32 v2, 9, v2
	v_or3_b32 v0, v0, v1, v3
	v_or3_b32 v1, v2, v1, v3
	v_add_u32_e32 v170, 0, v0
	v_add_u32_e32 v171, 0, v1
	v_lshlrev_b32_e32 v0, 8, v38
	v_and_b32_e32 v1, 0x70, v56
	v_bitop3_b32 v0, v47, v0, v1 bitop3:0xde
	v_add_u32_e32 v172, 0, v0
	v_lshlrev_b32_e32 v0, 8, v40
	v_bitop3_b32 v0, v47, v0, v1 bitop3:0xde
	v_add_u32_e32 v173, 0, v0
	v_lshlrev_b32_e32 v0, 7, v42
	v_bitop3_b32 v76, v44, v0, v1 bitop3:0xde
	v_add_u32_e32 v0, s8, v76
	v_lshlrev_b32_e32 v8, 8, v164
	v_and_b32_e32 v9, 0x70, v60
	s_waitcnt vmcnt(0)
	v_or_b32_e32 v12, 32, v212
	ds_write_b128 v170, v[16:19]
	v_bitop3_b32 v188, v12, v58, v59 bitop3:0xde
	ds_write_b128 v171, v[20:23]
	ds_write_b128 v172, v[24:27] offset:32768
	ds_write_b128 v173, v[28:31] offset:32768
	ds_write_b128 v0, v[32:35]
	v_bitop3_b32 v0, v212, v8, v9 bitop3:0xde
	v_add_u32_e32 v174, 0, v0
	s_waitcnt lgkmcnt(0)
	s_barrier
; __device__ __forceinline__ void qkt(f32x16& p0, f32x16& p1, const char* Ks, const char* Rs, const bf16x8* qr, const char* Qp, int r32, int hi) {
;     p0 = f32x16{}; p1 = f32x16{};
; #pragma unroll
;     for (int d0 = 0; d0 < 8; ++d0) { const int cb = (d0 * 16 + hi * 8) * 2;
;         const bf16x8 b0 = *reinterpret_cast<const bf16x8*>(Ks + KSWZ(r32, cb));
;         const bf16x8 b1 = *reinterpret_cast<const bf16x8*>(Ks + KSWZ(32 + r32, cb));
;         p0 = __builtin_amdgcn_mfma_f32_32x32x16_bf16(b0, qr[d0], p0, 0, 0, 0);
;         p1 = __builtin_amdgcn_mfma_f32_32x32x16_bf16(b1, qr[d0], p1, 0, 0, 0); }
; #pragma unroll
;     for (int d0 = 0; d0 < 4; ++d0) { const int cb = (d0 * 16 + hi * 8) * 2;
;         const bf16x8 b0 = *reinterpret_cast<const bf16x8*>(Rs + RSWZ(r32, cb));
;         const bf16x8 b1 = *reinterpret_cast<const bf16x8*>(Rs + RSWZ(32 + r32, cb));
;         const bf16x8 qq = *reinterpret_cast<const bf16x8*>(Qp + RSWZ(r32, cb));
;         p0 = __builtin_amdgcn_mfma_f32_32x32x16_bf16(b0, qq, p0, 0, 0, 0);
;         p1 = __builtin_amdgcn_mfma_f32_32x32x16_bf16(b1, qq, p1, 0, 0, 0); }
; }
	ds_read_b128 v[0:3], v174 offset:32768
	ds_read_b128 v[4:7], v174 offset:40960
	s_waitcnt lgkmcnt(1)
	v_mfma_f32_32x32x16_bf16 v[32:47], v[0:3], v[120:123], 0
	v_bitop3_b32 v0, v12, v8, v9 bitop3:0xde
	v_add_u32_e32 v180, 0, v0
	v_add_u32_e32 v189, s8, v188
	v_add_u32_e32 v175, s96, v188
	v_add_u32_e32 v193, s8, v192
	v_add_u32_e32 v176, s96, v192
	s_mov_b32 s8, s25
	s_waitcnt lgkmcnt(0)
	v_mfma_f32_32x32x16_bf16 v[16:31], v[4:7], v[120:123], 0
	ds_read_b128 v[0:3], v180 offset:32768
	ds_read_b128 v[4:7], v180 offset:40960
	s_mov_b32 s9, s25
	s_mov_b32 s10, s25
	s_mov_b32 s11, s25
	s_mov_b32 s12, s25
	s_mov_b32 s13, s25
	s_mov_b32 s14, s25
	s_waitcnt lgkmcnt(1)
	v_mfma_f32_32x32x16_bf16 v[32:47], v[0:3], v[124:127], v[32:47]
	v_bitop3_b32 v0, v61, v8, v9 bitop3:0xde
	v_add_u32_e32 v182, 0, v0
	s_mov_b32 s15, s25
	s_mov_b32 s16, s25
	s_mov_b32 s17, s25
	s_mov_b32 s18, s25
	s_mov_b32 s19, s25
	s_waitcnt lgkmcnt(0)
	v_mfma_f32_32x32x16_bf16 v[16:31], v[4:7], v[124:127], v[16:31]
	ds_read_b128 v[0:3], v182 offset:32768
	ds_read_b128 v[4:7], v182 offset:40960
	s_mov_b32 s20, s25
	s_mov_b32 s21, s25
	s_mov_b32 s22, s25
	s_mov_b32 s23, s25
	v_add_u32_e32 v195, 0, v76
	v_add_u32_e32 v196, 0x12000, v195
	s_waitcnt lgkmcnt(1)
	v_mfma_f32_32x32x16_bf16 v[32:47], v[0:3], v[116:119], v[32:47]
	v_bitop3_b32 v0, v62, v8, v9 bitop3:0xde
	v_add_u32_e32 v184, 0, v0
	v_lshl_add_u64 v[158:159], s[60:61], 0, v[48:49]
	v_lshl_add_u32 v166, v164, 2, s1
	v_mov_b32_e32 v167, 0
	s_waitcnt lgkmcnt(0)
	v_mfma_f32_32x32x16_bf16 v[16:31], v[4:7], v[116:119], v[16:31]
	ds_read_b128 v[0:3], v184 offset:32768
	ds_read_b128 v[4:7], v184 offset:40960
	s_waitcnt lgkmcnt(1)
	v_mfma_f32_32x32x16_bf16 v[32:47], v[0:3], v[112:115], v[32:47]
	v_or_b32_e32 v0, 0x80, v212
	v_bitop3_b32 v0, v0, v8, v9 bitop3:0xde
	v_add_u32_e32 v185, 0, v0
	s_waitcnt lgkmcnt(0)
	v_mfma_f32_32x32x16_bf16 v[16:31], v[4:7], v[112:115], v[16:31]
	ds_read_b128 v[0:3], v185 offset:32768
	ds_read_b128 v[4:7], v185 offset:40960
	s_waitcnt lgkmcnt(1)
	v_mfma_f32_32x32x16_bf16 v[32:47], v[0:3], v[108:111], v[32:47]
	v_or_b32_e32 v0, 0xa0, v212
	v_bitop3_b32 v0, v0, v8, v9 bitop3:0xde
	v_add_u32_e32 v183, 0, v0
	s_waitcnt lgkmcnt(0)
	v_mfma_f32_32x32x16_bf16 v[16:31], v[4:7], v[108:111], v[16:31]
	ds_read_b128 v[0:3], v183 offset:32768
	ds_read_b128 v[4:7], v183 offset:40960
	s_waitcnt lgkmcnt(1)
	v_mfma_f32_32x32x16_bf16 v[32:47], v[0:3], v[104:107], v[32:47]
	v_or_b32_e32 v0, 0xc0, v212
	v_bitop3_b32 v0, v0, v8, v9 bitop3:0xde
	v_add_u32_e32 v181, 0, v0
	s_waitcnt lgkmcnt(0)
	v_mfma_f32_32x32x16_bf16 v[16:31], v[4:7], v[104:107], v[16:31]
	ds_read_b128 v[0:3], v181 offset:32768
	ds_read_b128 v[4:7], v181 offset:40960
	s_waitcnt lgkmcnt(1)
	v_mfma_f32_32x32x16_bf16 v[32:47], v[0:3], v[100:103], v[32:47]
	v_or_b32_e32 v0, 0xe0, v212
	v_bitop3_b32 v0, v0, v8, v9 bitop3:0xde
	v_add_u32_e32 v179, 0, v0
	s_waitcnt lgkmcnt(0)
	v_mfma_f32_32x32x16_bf16 v[16:31], v[4:7], v[100:103], v[16:31]
	ds_read_b128 v[0:3], v179 offset:32768
	ds_read_b128 v[4:7], v179 offset:40960
	s_waitcnt lgkmcnt(1)
	v_mfma_f32_32x32x16_bf16 v[32:47], v[0:3], v[96:99], v[32:47]
	ds_read_b128 v[0:3], v187
	s_waitcnt lgkmcnt(1)
	v_mfma_f32_32x32x16_bf16 v[16:31], v[4:7], v[96:99], v[16:31]
	ds_read_b128 v[4:7], v177
	ds_read_b128 v[8:11], v187 offset:4096
	ds_read_b128 v[12:15], v189
	s_waitcnt lgkmcnt(2)
	v_mfma_f32_32x32x16_bf16 v[32:47], v[0:3], v[4:7], v[32:47]
	s_waitcnt lgkmcnt(1)
	v_mfma_f32_32x32x16_bf16 v[16:31], v[8:11], v[4:7], v[16:31]
	ds_read_b128 v[0:3], v175
	ds_read_b128 v[4:7], v189 offset:4096
	v_lshlrev_b32_e32 v8, 3, v77
	v_and_b32_e32 v9, 0xc0, v60
	s_waitcnt lgkmcnt(1)
	v_mfma_f32_32x32x16_bf16 v[32:47], v[12:15], v[0:3], v[32:47]
	v_and_or_b32 v12, v8, 24, v9
	v_lshlrev_b32_e32 v9, 1, v57
	v_and_b32_e32 v13, 32, v9
	v_and_b32_e32 v14, 0x100, v8
	ds_read_b128 v[8:11], v191
	v_or3_b32 v57, v12, v13, v14
	v_add_u32_e32 v169, 0, v57
	s_waitcnt lgkmcnt(1)
	v_mfma_f32_32x32x16_bf16 v[16:31], v[4:7], v[0:3], v[16:31]
	ds_read_b128 v[0:3], v178
	ds_read_b128 v[4:7], v191 offset:4096
	ds_read_b128 v[12:15], v193
	ds_read_b128 v[58:61], v193 offset:4096
	ds_read_b128 v[62:65], v176
	s_waitcnt lgkmcnt(4)
	v_mfma_f32_32x32x16_bf16 v[32:47], v[8:11], v[0:3], v[32:47]
	s_waitcnt lgkmcnt(3)
	v_mfma_f32_32x32x16_bf16 v[16:31], v[4:7], v[0:3], v[16:31]
	s_waitcnt lgkmcnt(0)
; #define SWRITE(b) do { *(bf16x8*)(V_lds + (b) * SHM_V + vst0) = vs0; *(bf16x8*)(V_lds + (b) * SHM_V + vst1) = vs1; const int kc = sc * 2; \
;     *(bf16x8*)(K_lds + (b) * SHM_K + KSWZ(sr, kc)) = ks0; *(bf16x8*)(K_lds + (b) * SHM_K + KSWZ(32 + sr, kc)) = ks1; \
;     *(bf16x8*)(R_lds + (b) * SHM_R + RSWZ(rr, rc * 2)) = rs0; } while (0)
; #define SWAIT() asm volatile("s_waitcnt vmcnt(0)" ::: "memory")
; __device__ __forceinline__ void partialSM(f32x16& p0, f32x16& p1, float& m_reg, float& mn, float& alpha) {
;     constexpr float C = SCALE * 1.4426950408889634f;
;     float pmax = p0[0];
; #pragma unroll
;     for (int r = 1; r < 16; ++r) pmax = fmaxf(pmax, p0[r]);
; #pragma unroll
;     for (int r = 0; r < 16; ++r) pmax = fmaxf(pmax, p1[r]);
;     { auto rr = __builtin_amdgcn_permlane32_swap(__float_as_uint(pmax), __float_as_uint(pmax), false, false);
;       pmax = fmaxf(__uint_as_float(rr[0]), __uint_as_float(rr[1])); }
;     if (__builtin_expect(__all(pmax - m_reg <= THR / SCALE), 1)) { mn = m_reg; alpha = 1.f; }
;     else { mn = fmaxf(m_reg, pmax); alpha = __builtin_amdgcn_exp2f((m_reg - mn) * C); m_reg = mn; }
;     const float mnC = -mn * C;
; #pragma unroll
;     for (int r = 0; r < 16; ++r) p0[r] = fmaf(p0[r], C, mnC);
; #pragma unroll
;     for (int r = 0; r < 16; ++r) p1[r] = fmaf(p1[r], C, mnC);
; #pragma unroll
;     for (int r = 0; r < 16; ++r) p0[r] = __builtin_amdgcn_exp2f(p0[r]);
; }
; __device__ __forceinline__ void attn_body(const bf16_t* __restrict__ Qb, const bf16_t* __restrict__ Kh, const bf16_t* __restrict__ Vh, const bf16_t* __restrict__ Rh,
;                                           bf16_t* __restrict__ Zb, int seq, char* lds, int wv, bool nowrite) {
;     ...
;     f32x16 pA0, pA1, pB0, pB1; float mnA, mnB, alA, alB; bf16x8 pa0, pa1, pa2, pa3; const int NT = seq / KVBLK;
;     SLOAD(0); SWAIT(); SWRITE(0); __syncthreads();
;     qkt(pA0, pA1, K_lds, R_lds, qr, Qp, r32, hi); partialSM(pA0, pA1, m_reg, mnA, alA);
;     SLOAD(KVBLK);
;     SWAIT(); SWRITE(1); __syncthreads();
;     for (int j = 1; j + 1 < NT; j += 2) {
	v_mfma_f32_32x32x16_bf16 v[32:47], v[12:15], v[62:65], v[32:47]
	v_mov_b64_e32 v[0:1], s[8:9]
	v_mov_b64_e32 v[2:3], s[10:11]
	v_mov_b64_e32 v[4:5], s[12:13]
	v_mov_b64_e32 v[6:7], s[14:15]
	v_mov_b64_e32 v[8:9], s[16:17]
	v_mov_b64_e32 v[10:11], s[18:19]
	v_mov_b64_e32 v[12:13], s[20:21]
	v_mov_b64_e32 v[14:15], s[22:23]
	s_mov_b64 s[8:9], 0x40000
	v_mfma_f32_32x32x16_bf16 v[16:31], v[58:61], v[62:65], v[16:31]
	s_nop 1
	v_max_f32_e32 v58, v33, v33
	v_max_f32_e32 v59, v32, v32
	v_lshl_add_u64 v[66:67], v[52:53], 0, s[8:9]
	s_mov_b64 s[8:9], 0x60000
	v_max_f32_e32 v58, v59, v58
	v_lshl_add_u64 v[52:53], v[52:53], 0, s[8:9]
	v_max3_f32 v74, v58, v34, v35
	v_lshl_add_u64 v[58:59], s[62:63], 0, v[66:67]
	v_lshl_add_u64 v[62:63], s[62:63], 0, v[52:53]
	v_lshl_add_u64 v[66:67], s[6:7], 0, v[66:67]
	v_lshl_add_u64 v[52:53], s[6:7], 0, v[52:53]
	s_movk_i32 s6, 0x2000
	global_load_dwordx4 v[58:61], v[58:59], off
	s_nop 0
	global_load_dwordx4 v[62:65], v[62:63], off
	s_nop 0
	global_load_dwordx4 v[66:69], v[66:67], off
	s_nop 0
	global_load_dwordx4 v[70:73], v[52:53], off
	v_add_co_u32_e32 v52, vcc, s6, v54
	v_max3_f32 v74, v74, v36, v37
	s_nop 0
	v_addc_co_u32_e32 v53, vcc, 0, v55, vcc
	global_load_dwordx4 v[52:55], v[52:53], off
	v_max3_f32 v74, v74, v38, v39
	v_max3_f32 v74, v74, v40, v41
	v_max3_f32 v74, v74, v42, v43
	v_max3_f32 v74, v74, v44, v45
	v_max3_f32 v74, v74, v46, v47
	v_max3_f32 v74, v74, v16, v17
	v_max3_f32 v74, v74, v18, v19
	v_max3_f32 v74, v74, v20, v21
	v_max3_f32 v74, v74, v22, v23
	v_max3_f32 v74, v74, v24, v25
	v_max3_f32 v74, v74, v26, v27
	v_max3_f32 v74, v74, v28, v29
	v_max3_f32 v74, v74, v30, v31
	v_mov_b32_e32 v78, v74
	s_nop 1
	v_permlane32_swap_b32_e32 v74, v78
	v_max_f32_e32 v78, v78, v78
	v_max_f32_e32 v74, v74, v74
	v_max_f32_e32 v74, v74, v78
	v_add_f32_e32 v78, 0x7149f2ca, v74
	v_max_f32_e32 v74, 0xf149f2ca, v74
	v_cmp_ge_f32_e32 vcc, s88, v78
	v_sub_f32_e32 v78, 0xf149f2ca, v74
	v_mul_f32_e32 v78, 0x3dd53b94, v78
	v_exp_f32_e32 v78, v78
	s_cmp_eq_u64 vcc, exec
	s_cselect_b64 vcc, -1, 0
	v_cndmask_b32_e32 v197, v74, v235, vcc
	s_add_i32 s8, 0, 0x4000
	v_mul_f32_e32 v74, 0xbdd53b94, v197
	v_add_u32_e32 v168, s8, v57
	s_lshl_b64 s[8:9], s[56:57], 18
	v_cndmask_b32_e64 v194, v78, 1.0, vcc
	v_mov_b32_e32 v78, v74
	s_add_u32 s8, s72, s8
	v_fmamk_f32 v32, v32, 0x3dd53b94, v74
	v_fmamk_f32 v33, v33, 0x3dd53b94, v74
	v_fmamk_f32 v34, v34, 0x3dd53b94, v74
	v_fmamk_f32 v35, v35, 0x3dd53b94, v74
	v_fmamk_f32 v36, v36, 0x3dd53b94, v74
	v_fmamk_f32 v37, v37, 0x3dd53b94, v74
	v_fmamk_f32 v38, v38, 0x3dd53b94, v74
	v_fmamk_f32 v39, v39, 0x3dd53b94, v74
	v_fmamk_f32 v40, v40, 0x3dd53b94, v74
	v_fmamk_f32 v41, v41, 0x3dd53b94, v74
	v_fmamk_f32 v42, v42, 0x3dd53b94, v74
	v_fmamk_f32 v43, v43, 0x3dd53b94, v74
	v_fmamk_f32 v44, v44, 0x3dd53b94, v74
	v_fmamk_f32 v45, v45, 0x3dd53b94, v74
	v_fmamk_f32 v46, v46, 0x3dd53b94, v74
	v_fmac_f32_e32 v78, 0x3dd53b94, v47
	v_pk_fma_f32 v[138:139], v[18:19], s[36:37], v[74:75] op_sel_hi:[1,0,0]
	s_addc_u32 s9, s73, s9
	v_and_b32_e32 v18, 7, v56
	v_pk_fma_f32 v[140:141], v[16:17], s[36:37], v[74:75] op_sel_hi:[1,0,0]
	v_exp_f32_e32 v162, v32
	v_exp_f32_e32 v205, v33
	v_exp_f32_e32 v149, v34
	v_exp_f32_e32 v163, v35
	v_exp_f32_e32 v150, v36
	v_exp_f32_e32 v161, v37
	v_exp_f32_e32 v151, v38
	v_exp_f32_e32 v160, v39
	v_exp_f32_e32 v152, v40
	v_exp_f32_e32 v155, v41
	v_exp_f32_e32 v153, v42
	v_exp_f32_e32 v154, v43
	v_exp_f32_e32 v145, v44
	v_exp_f32_e32 v147, v45
	v_exp_f32_e32 v144, v46
	v_exp_f32_e32 v146, v78
	v_lshl_add_u64 v[16:17], s[8:9], 0, v[50:51]
	v_lshlrev_b32_e32 v18, 4, v18
	v_mov_b32_e32 v19, v213
	s_waitcnt vmcnt(0)
	v_lshl_add_u64 v[156:157], v[16:17], 0, v[18:19]
	v_and_b32_e32 v16, 0xf0, v75
	v_pk_fma_f32 v[134:135], v[30:31], s[36:37], v[74:75] op_sel_hi:[1,0,0]
	v_pk_fma_f32 v[136:137], v[28:29], s[36:37], v[74:75] op_sel_hi:[1,0,0]
	v_pk_fma_f32 v[142:143], v[26:27], s[36:37], v[74:75] op_sel_hi:[1,0,0]
	v_pk_fma_f32 v[128:129], v[24:25], s[36:37], v[74:75] op_sel_hi:[1,0,0]
	v_pk_fma_f32 v[130:131], v[22:23], s[36:37], v[74:75] op_sel_hi:[1,0,0]
	v_pk_fma_f32 v[132:133], v[20:21], s[36:37], v[74:75] op_sel_hi:[1,0,0]
	s_waitcnt vmcnt(4)
	ds_write_b128 v170, v[58:61] offset:16384
	s_waitcnt vmcnt(3)
	ds_write_b128 v171, v[62:65] offset:16384
	s_waitcnt vmcnt(2)
	ds_write_b128 v172, v[66:69] offset:49152
	s_waitcnt vmcnt(1)
	ds_write_b128 v173, v[70:73] offset:49152
	s_waitcnt vmcnt(0)
	ds_write_b128 v196, v[52:55]
	v_or3_b32 v158, v158, s3, v16
	v_mov_b64_e32 v[62:63], v[14:15]
	v_mov_b64_e32 v[46:47], v[14:15]
	v_mov_b64_e32 v[30:31], v[14:15]
	v_cmp_gt_u32_e64 s[6:7], 32, v77
	s_mov_b32 s3, -1
	v_mov_b64_e32 v[60:61], v[12:13]
	v_mov_b64_e32 v[58:59], v[10:11]
	v_mov_b64_e32 v[56:57], v[8:9]
	v_mov_b64_e32 v[54:55], v[6:7]
	v_mov_b64_e32 v[52:53], v[4:5]
	v_mov_b64_e32 v[50:51], v[2:3]
	v_mov_b64_e32 v[48:49], v[0:1]
	v_mov_b64_e32 v[44:45], v[12:13]
	v_mov_b64_e32 v[42:43], v[10:11]
	v_mov_b64_e32 v[40:41], v[8:9]
	v_mov_b64_e32 v[38:39], v[6:7]
	v_mov_b64_e32 v[36:37], v[4:5]
	v_mov_b64_e32 v[34:35], v[2:3]
	v_mov_b64_e32 v[32:33], v[0:1]
	v_mov_b64_e32 v[28:29], v[12:13]
	v_mov_b64_e32 v[26:27], v[10:11]
	v_mov_b64_e32 v[24:25], v[8:9]
	v_mov_b64_e32 v[22:23], v[6:7]
	v_mov_b64_e32 v[20:21], v[4:5]
	v_mov_b64_e32 v[18:19], v[2:3]
	v_mov_b64_e32 v[16:17], v[0:1]
	v_add_u32_e32 v228, s75, v233
	v_bfe_u32 v229, v228, 4, 3
	v_lshlrev_b32_e32 v229, 4, v229
	v_add_u32_e32 v244, 0x28080000, v158
	v_add_u32_e32 v245, 0x280a0000, v158
	v_add_u32_e32 v246, 0x3e004000, v156
	v_xor_b32_e32 v244, v229, v244
	v_xor_b32_e32 v245, v229, v245
	v_xor_b32_e32 v246, v229, v246
	v_lshrrev_b32_e32 v236, 4, v228
	v_lshlrev_b32_e32 v236, 12, v236
	v_and_b32_e32 v237, 15, v228
	v_lshl_add_u32 v236, v237, 4, v236
	v_sub_u32_e32 v242, v158, v236
	v_lshrrev_b32_e32 v236, 7, v228
	v_bfe_u32 v237, v228, 2, 3
	v_lshl_or_b32 v236, v236, 3, v237
	v_and_b32_e32 v237, 4, v236
	v_lshlrev_b32_e32 v237, 1, v237
	v_and_b32_e32 v252, 8, v236
	v_lshrrev_b32_e32 v252, 1, v252
	v_and_b32_e32 v236, 0xfffffff3, v236
	v_or3_b32 v236, v236, v237, v252
	v_bfe_u32 v237, v228, 5, 2
	v_and_b32_e32 v252, 3, v228
	v_lshlrev_b32_e32 v252, 4, v252
	v_lshl_or_b32 v237, v237, 6, v252
	v_lshl_add_u32 v236, v236, 12, v237
	v_add_u32_e32 v242, v242, v236
	v_add_u32_e32 v243, 0x300a0000, v242
	v_add_u32_e32 v242, 0x30080000, v242
	v_add_u32_e32 v247, 0x1c800, v169
	v_add_u32_e32 v248, 0x1c800, v170
	v_add_u32_e32 v249, 0x1c800, v171
	s_waitcnt lgkmcnt(0)
	s_barrier
; __device__ __forceinline__ void finishSM(f32x16& p0, f32x16& p1, float alpha, float& l_reg, bf16x8& pa0, bf16x8& pa1, bf16x8& pa2, bf16x8& pa3) {
; #pragma unroll
;     for (int r = 0; r < 16; ++r) p1[r] = __builtin_amdgcn_exp2f(p1[r]);
;     float ps = 0;
; #pragma unroll
;     for (int r = 0; r < 16; ++r) ps += p0[r];
; #pragma unroll
;     for (int r = 0; r < 16; ++r) ps += p1[r];
;     { auto rr = __builtin_amdgcn_permlane32_swap(__float_as_uint(ps), __float_as_uint(ps), false, false);
;       ps = __uint_as_float(rr[0]) + __uint_as_float(rr[1]); }
;     l_reg = l_reg * alpha + ps;
;     ...
;     PK4(p0, 0, pa0); PK4(p0, 8, pa1); PK4(p1, 0, pa2); PK4(p1, 8, pa3);
;     ...
; }
; __device__ __forceinline__ void qkt(f32x16& p0, f32x16& p1, const char* Ks, const char* Rs, const bf16x8* qr, const char* Qp, int r32, int hi) {
;     p0 = f32x16{}; p1 = f32x16{};
; #pragma unroll
;     for (int d0 = 0; d0 < 8; ++d0) { const int cb = (d0 * 16 + hi * 8) * 2;
;         const bf16x8 b0 = *reinterpret_cast<const bf16x8*>(Ks + KSWZ(r32, cb));
;         const bf16x8 b1 = *reinterpret_cast<const bf16x8*>(Ks + KSWZ(32 + r32, cb));
;         p0 = __builtin_amdgcn_mfma_f32_32x32x16_bf16(b0, qr[d0], p0, 0, 0, 0);
;         p1 = __builtin_amdgcn_mfma_f32_32x32x16_bf16(b1, qr[d0], p1, 0, 0, 0); }
; #pragma unroll
;     for (int d0 = 0; d0 < 4; ++d0) { const int cb = (d0 * 16 + hi * 8) * 2;
;         const bf16x8 b0 = *reinterpret_cast<const bf16x8*>(Rs + RSWZ(r32, cb));
;         const bf16x8 b1 = *reinterpret_cast<const bf16x8*>(Rs + RSWZ(32 + r32, cb));
;         const bf16x8 qq = *reinterpret_cast<const bf16x8*>(Qp + RSWZ(r32, cb));
;         p0 = __builtin_amdgcn_mfma_f32_32x32x16_bf16(b0, qq, p0, 0, 0, 0);
;         p1 = __builtin_amdgcn_mfma_f32_32x32x16_bf16(b1, qq, p1, 0, 0, 0); }
; }
.LBB0_608:
	ds_read_b128 v[64:67], v174 offset:49152
	ds_read_b128 v[68:71], v174 offset:57344
	ds_read_b128 v[198:201], v180 offset:49152
	ds_read_b128 v[206:209], v180 offset:57344
	s_add_i32 s8, 0, 0x12000
	v_add_f32_e32 v148, 0, v162
	s_waitcnt lgkmcnt(3)
	v_mfma_f32_32x32x16_bf16 v[80:95], v[64:67], v[120:123], 0
	v_add_f32_e32 v148, v205, v148
	v_add_f32_e32 v148, v149, v148
	v_add_f32_e32 v148, v163, v148
	v_add_f32_e32 v148, v150, v148
	v_add_f32_e32 v148, v161, v148
	v_add_f32_e32 v148, v151, v148
	v_add_f32_e32 v148, v160, v148
	s_waitcnt lgkmcnt(2)
	v_mfma_f32_32x32x16_bf16 v[64:79], v[68:71], v[120:123], 0
	v_add_f32_e32 v148, v152, v148
	v_add_f32_e32 v148, v155, v148
	v_add_f32_e32 v148, v153, v148
	v_add_f32_e32 v148, v154, v148
	v_exp_f32_e32 v140, v140
	v_add_f32_e32 v148, v145, v148
	v_exp_f32_e32 v141, v141
	s_waitcnt lgkmcnt(1)
	v_mfma_f32_32x32x16_bf16 v[80:95], v[198:201], v[124:127], v[80:95]
	v_add_f32_e32 v148, v147, v148
	v_exp_f32_e32 v138, v138
	v_add_f32_e32 v148, v144, v148
	v_exp_f32_e32 v139, v139
	v_add_f32_e32 v148, v146, v148
	v_exp_f32_e32 v132, v132
	v_add_f32_e32 v148, v140, v148
	s_waitcnt lgkmcnt(0)
	v_mfma_f32_32x32x16_bf16 v[64:79], v[206:209], v[124:127], v[64:79]
	ds_read_b128 v[198:201], v182 offset:49152
	ds_read_b128 v[206:209], v182 offset:57344
	v_exp_f32_e32 v133, v133
	v_add_f32_e32 v148, v141, v148
	v_exp_f32_e32 v130, v130
	v_add_f32_e32 v148, v138, v148
	v_exp_f32_e32 v131, v131
	v_add_f32_e32 v148, v139, v148
	s_waitcnt lgkmcnt(1)
	v_mfma_f32_32x32x16_bf16 v[80:95], v[198:201], v[116:119], v[80:95]
	v_exp_f32_e32 v128, v128
	v_add_f32_e32 v148, v132, v148
	v_exp_f32_e32 v129, v129
	v_add_f32_e32 v148, v133, v148
	v_exp_f32_e32 v142, v142
	v_add_f32_e32 v148, v130, v148
	v_exp_f32_e32 v143, v143
	s_waitcnt lgkmcnt(0)
	v_mfma_f32_32x32x16_bf16 v[64:79], v[206:209], v[116:119], v[64:79]
	ds_read_b128 v[198:201], v184 offset:49152
	ds_read_b128 v[206:209], v184 offset:57344
	v_add_f32_e32 v148, v131, v148
	v_exp_f32_e32 v136, v136
	v_add_f32_e32 v148, v128, v148
	v_exp_f32_e32 v137, v137
	v_add_f32_e32 v148, v129, v148
	v_exp_f32_e32 v134, v134
	s_waitcnt lgkmcnt(1)
	v_mfma_f32_32x32x16_bf16 v[80:95], v[198:201], v[112:115], v[80:95]
	v_add_f32_e32 v148, v142, v148
	v_exp_f32_e32 v135, v135
	v_add_f32_e32 v148, v143, v148
	v_add_f32_e32 v148, v136, v148
	v_add_f32_e32 v148, v137, v148
	v_add_f32_e32 v148, v134, v148
	s_waitcnt lgkmcnt(0)
	v_mfma_f32_32x32x16_bf16 v[64:79], v[206:209], v[112:115], v[64:79]
	ds_read_b128 v[198:201], v185 offset:49152
	ds_read_b128 v[206:209], v185 offset:57344
	s_waitcnt lgkmcnt(1)
	v_mfma_f32_32x32x16_bf16 v[80:95], v[198:201], v[108:111], v[80:95]
	s_waitcnt lgkmcnt(0)
	v_mfma_f32_32x32x16_bf16 v[64:79], v[206:209], v[108:111], v[64:79]
	ds_read_b128 v[198:201], v183 offset:49152
	ds_read_b128 v[206:209], v183 offset:57344
	s_waitcnt lgkmcnt(1)
	v_mfma_f32_32x32x16_bf16 v[80:95], v[198:201], v[104:107], v[80:95]
	s_waitcnt lgkmcnt(0)
	v_mfma_f32_32x32x16_bf16 v[64:79], v[206:209], v[104:107], v[64:79]
	ds_read_b128 v[198:201], v181 offset:49152
	ds_read_b128 v[206:209], v181 offset:57344
	s_waitcnt lgkmcnt(1)
	v_mfma_f32_32x32x16_bf16 v[80:95], v[198:201], v[100:103], v[80:95]
	s_waitcnt lgkmcnt(0)
	v_mfma_f32_32x32x16_bf16 v[64:79], v[206:209], v[100:103], v[64:79]
	ds_read_b128 v[198:201], v179 offset:49152
	ds_read_b128 v[206:209], v179 offset:57344
	s_waitcnt lgkmcnt(1)
	v_mfma_f32_32x32x16_bf16 v[80:95], v[198:201], v[96:99], v[80:95]
	v_add_u32_e32 v199, s8, v186
	v_add_u32_e32 v198, s8, v188
	s_waitcnt lgkmcnt(0)
	v_mfma_f32_32x32x16_bf16 v[64:79], v[206:209], v[96:99], v[64:79]
	ds_read_b128 v[200:203], v199
	ds_read_b128 v[206:209], v199 offset:4096
	ds_read_b128 v[214:217], v177
	s_waitcnt lgkmcnt(0)
	v_mfma_f32_32x32x16_bf16 v[80:95], v[200:203], v[214:217], v[80:95]
	v_mfma_f32_32x32x16_bf16 v[64:79], v[206:209], v[214:217], v[64:79]
	ds_read_b128 v[200:203], v198
	ds_read_b128 v[206:209], v198 offset:4096
	ds_read_b128 v[214:217], v175
	s_waitcnt lgkmcnt(0)
	v_mfma_f32_32x32x16_bf16 v[80:95], v[200:203], v[214:217], v[80:95]
	v_add_u32_e32 v200, s8, v190
	v_add_u32_e32 v201, s8, v192
	v_add_f32_e32 v202, v135, v148
	v_mov_b32_e32 v203, v202
	s_nop 1
	v_permlane32_swap_b32_e32 v202, v203
	v_mfma_f32_32x32x16_bf16 v[64:79], v[206:209], v[214:217], v[64:79]
	ds_read_b128 v[206:209], v200
	ds_read_b128 v[214:217], v200 offset:4096
	ds_read_b128 v[218:221], v178
	s_waitcnt lgkmcnt(0)
	v_mfma_f32_32x32x16_bf16 v[80:95], v[206:209], v[218:221], v[80:95]
	v_mfma_f32_32x32x16_bf16 v[64:79], v[214:217], v[218:221], v[64:79]
	ds_read_b128 v[206:209], v201
	ds_read_b128 v[214:217], v201 offset:4096
	ds_read_b128 v[218:221], v176
	v_cvt_pk_bf16_f32 v148, v162, v205
	v_cvt_pk_bf16_f32 v149, v149, v163
	v_cvt_pk_bf16_f32 v150, v150, v161
	v_cvt_pk_bf16_f32 v151, v151, v160
	v_cvt_pk_bf16_f32 v152, v152, v155
	v_cvt_pk_bf16_f32 v153, v153, v154
	s_waitcnt lgkmcnt(0)
; #define SBAR() __builtin_amdgcn_sched_barrier(0)
; __device__ __forceinline__ void partialSM(f32x16& p0, f32x16& p1, float& m_reg, float& mn, float& alpha) {
;     constexpr float C = SCALE * 1.4426950408889634f;
;     float pmax = p0[0];
; #pragma unroll
;     for (int r = 1; r < 16; ++r) pmax = fmaxf(pmax, p0[r]);
; #pragma unroll
;     for (int r = 0; r < 16; ++r) pmax = fmaxf(pmax, p1[r]);
;     { auto rr = __builtin_amdgcn_permlane32_swap(__float_as_uint(pmax), __float_as_uint(pmax), false, false);
;       pmax = fmaxf(__uint_as_float(rr[0]), __uint_as_float(rr[1])); }
;     if (__builtin_expect(__all(pmax - m_reg <= THR / SCALE), 1)) { mn = m_reg; alpha = 1.f; }
;     else { mn = fmaxf(m_reg, pmax); alpha = __builtin_amdgcn_exp2f((m_reg - mn) * C); m_reg = mn; }
; template <int OFF> __device__ __forceinline__ s16x4 tr_read(int vb) {
;     s16x4 r; asm volatile("ds_read_b64_tr_b16 %0, %1 offset:%2" : "=&v"(r) : "v"(vb), "i"(OFF) : "memory"); return r;
; }
; template <int D0> __device__ __forceinline__ void pv_one(f32x16& od, int vb, bf16x8 pa0, bf16x8 pa1, bf16x8 pa2, bf16x8 pa3) {
;     const s16x4 l0 = tr_read<v_rd_off(D0, 0, 0)>(vb), h0 = tr_read<v_rd_off(D0, 0, 1)>(vb), l1 = tr_read<v_rd_off(D0, 1, 0)>(vb), h1 = tr_read<v_rd_off(D0, 1, 1)>(vb);
;     const s16x4 l2 = tr_read<v_rd_off(D0, 2, 0)>(vb), h2 = tr_read<v_rd_off(D0, 2, 1)>(vb), l3 = tr_read<v_rd_off(D0, 3, 0)>(vb), h3 = tr_read<v_rd_off(D0, 3, 1)>(vb);
;     asm volatile("s_waitcnt lgkmcnt(0)" ::: "memory"); SBAR();
;     ...
;     od = __builtin_amdgcn_mfma_f32_32x32x16_bf16(pa0, PK(l0, h0), od, 0, 0, 0);
;     od = __builtin_amdgcn_mfma_f32_32x32x16_bf16(pa1, PK(l1, h1), od, 0, 0, 0);
;     od = __builtin_amdgcn_mfma_f32_32x32x16_bf16(pa2, PK(l2, h2), od, 0, 0, 0);
;     od = __builtin_amdgcn_mfma_f32_32x32x16_bf16(pa3, PK(l3, h3), od, 0, 0, 0);
;     ...
; }
; __device__ __forceinline__ void pv_d0(f32x16* o, int vb, bf16x8 pa0, bf16x8 pa1, bf16x8 pa2, bf16x8 pa3) {
;     pv_one<0>(o[0], vb, pa0, pa1, pa2, pa3); pv_one<1>(o[1], vb, pa0, pa1, pa2, pa3); pv_one<2>(o[2], vb, pa0, pa1, pa2, pa3); pv_one<3>(o[3], vb, pa0, pa1, pa2, pa3);
; }
	v_mfma_f32_32x32x16_bf16 v[80:95], v[206:209], v[218:221], v[80:95]
	v_cvt_pk_bf16_f32 v154, v145, v147
	v_cvt_pk_bf16_f32 v155, v144, v146
	v_cvt_pk_bf16_f32 v204, v140, v141
	v_cvt_pk_bf16_f32 v205, v138, v139
	v_cvt_pk_bf16_f32 v206, v132, v133
	v_permlane32_swap_b32_e32 v148, v150
	v_mfma_f32_32x32x16_bf16 v[64:79], v[214:217], v[218:221], v[64:79]
	v_cvt_pk_bf16_f32 v207, v130, v131
	v_permlane32_swap_b32_e32 v204, v206
	v_cvt_pk_bf16_f32 v208, v128, v129
	v_cvt_pk_bf16_f32 v209, v142, v143
	v_cvt_pk_bf16_f32 v210, v136, v137
	v_cvt_pk_bf16_f32 v211, v134, v135
	v_permlane32_swap_b32_e32 v149, v151
	v_permlane32_swap_b32_e32 v152, v154
	v_permlane32_swap_b32_e32 v153, v155
	v_permlane32_swap_b32_e32 v205, v207
	v_permlane32_swap_b32_e32 v208, v210
	v_permlane32_swap_b32_e32 v209, v211
	s_add_i32 m0, s37, 0x1c800
	s_nop 0
	global_load_lds_dwordx4 v242, s[44:45]
	s_add_i32 m0, s37, 0x1e800
	v_add_u32_e32 v242, 0x40000, v242
	global_load_lds_dwordx4 v243, s[44:45]
	s_add_i32 m0, s37, 0x8000
	v_add_u32_e32 v243, 0x40000, v243
	global_load_lds_dwordx4 v244, s[44:45]
	s_add_i32 m0, s37, 0xa000
	v_add_u32_e32 v244, 0x40000, v244
	global_load_lds_dwordx4 v245, s[44:45]
	s_add_i32 m0, s37, 0x10000
	v_add_u32_e32 v245, 0x40000, v245
	global_load_lds_dwordx4 v246, s[44:45]
	v_add_u32_e32 v246, 0x2000, v246
	ds_read_b64_tr_b16 v[214:215], v169 offset:0
	ds_read_b64_tr_b16 v[216:217], v169 offset:0x800
	ds_read_b64_tr_b16 v[218:219], v169 offset:0x1000
	ds_read_b64_tr_b16 v[220:221], v169 offset:0x1800
	ds_read_b64_tr_b16 v[224:225], v169 offset:0x2000
	ds_read_b64_tr_b16 v[226:227], v169 offset:0x2800
	ds_read_b64_tr_b16 v[238:239], v169 offset:0x3000
	ds_read_b64_tr_b16 v[240:241], v169 offset:0x3800
	s_waitcnt lgkmcnt(0)
	s_nop 0
	v_mfma_f32_32x32x16_bf16 v[0:15], v[148:151], v[214:217], v[0:15]
	ds_read_b64_tr_b16 v[214:215], v169 offset:0x200
	ds_read_b64_tr_b16 v[216:217], v169 offset:0xa00
	v_mfma_f32_32x32x16_bf16 v[0:15], v[152:155], v[218:221], v[0:15]
	ds_read_b64_tr_b16 v[218:219], v169 offset:0x1200
	ds_read_b64_tr_b16 v[220:221], v169 offset:0x1a00
	v_mfma_f32_32x32x16_bf16 v[0:15], v[204:207], v[224:227], v[0:15]
	ds_read_b64_tr_b16 v[224:225], v169 offset:0x2200
	ds_read_b64_tr_b16 v[226:227], v169 offset:0x2a00
	v_mfma_f32_32x32x16_bf16 v[0:15], v[208:211], v[238:241], v[0:15]
	ds_read_b64_tr_b16 v[238:239], v169 offset:0x3200
	ds_read_b64_tr_b16 v[240:241], v169 offset:0x3a00
	s_waitcnt lgkmcnt(0)
	v_mfma_f32_32x32x16_bf16 v[48:63], v[148:151], v[214:217], v[48:63]
	ds_read_b64_tr_b16 v[214:215], v169 offset:0x400
	ds_read_b64_tr_b16 v[216:217], v169 offset:0xc00
	v_mfma_f32_32x32x16_bf16 v[48:63], v[152:155], v[218:221], v[48:63]
	ds_read_b64_tr_b16 v[218:219], v169 offset:0x1400
	ds_read_b64_tr_b16 v[220:221], v169 offset:0x1c00
	v_mfma_f32_32x32x16_bf16 v[48:63], v[204:207], v[224:227], v[48:63]
	ds_read_b64_tr_b16 v[224:225], v169 offset:0x2400
	ds_read_b64_tr_b16 v[226:227], v169 offset:0x2c00
	v_mfma_f32_32x32x16_bf16 v[48:63], v[208:211], v[238:241], v[48:63]
	ds_read_b64_tr_b16 v[238:239], v169 offset:0x3400
	ds_read_b64_tr_b16 v[240:241], v169 offset:0x3c00
	s_waitcnt lgkmcnt(0)
	v_mfma_f32_32x32x16_bf16 v[32:47], v[148:151], v[214:217], v[32:47]
	ds_read_b64_tr_b16 v[214:215], v169 offset:0x600
	ds_read_b64_tr_b16 v[216:217], v169 offset:0xe00
	v_mfma_f32_32x32x16_bf16 v[32:47], v[152:155], v[218:221], v[32:47]
	ds_read_b64_tr_b16 v[218:219], v169 offset:0x1600
	ds_read_b64_tr_b16 v[220:221], v169 offset:0x1e00
	v_mfma_f32_32x32x16_bf16 v[32:47], v[204:207], v[224:227], v[32:47]
	ds_read_b64_tr_b16 v[224:225], v169 offset:0x2600
	ds_read_b64_tr_b16 v[226:227], v169 offset:0x2e00
	v_mfma_f32_32x32x16_bf16 v[32:47], v[208:211], v[238:241], v[32:47]
	ds_read_b64_tr_b16 v[238:239], v169 offset:0x3600
	ds_read_b64_tr_b16 v[240:241], v169 offset:0x3e00
	s_waitcnt lgkmcnt(0)
	v_mfma_f32_32x32x16_bf16 v[16:31], v[148:151], v[214:217], v[16:31]
	v_max_f32_e32 v148, v81, v81
	v_max_f32_e32 v149, v80, v80
	v_max_f32_e32 v148, v149, v148
	v_max3_f32 v148, v148, v82, v83
	v_max3_f32 v148, v148, v84, v85
	v_max3_f32 v148, v148, v86, v87
	v_max3_f32 v148, v148, v88, v89
	v_max3_f32 v148, v148, v90, v91
	v_max3_f32 v148, v148, v92, v93
	v_mfma_f32_32x32x16_bf16 v[16:31], v[152:155], v[218:221], v[16:31]
	v_max3_f32 v148, v148, v94, v95
	v_max3_f32 v148, v148, v64, v65
	v_max3_f32 v148, v148, v66, v67
	v_max3_f32 v148, v148, v68, v69
	v_max3_f32 v148, v148, v70, v71
	v_max3_f32 v148, v148, v72, v73
	v_max3_f32 v148, v148, v74, v75
	v_max3_f32 v148, v148, v76, v77
	v_mfma_f32_32x32x16_bf16 v[16:31], v[204:207], v[224:227], v[16:31]
	v_max3_f32 v148, v148, v78, v79
	v_mov_b32_e32 v149, v148
	s_nop 1
	v_permlane32_swap_b32_e32 v148, v149
	v_max_f32_e32 v149, v149, v149
	v_max_f32_e32 v148, v148, v148
	v_max_f32_e32 v148, v148, v149
	v_sub_f32_e32 v149, v148, v197
	v_cmp_ge_f32_e32 vcc, s88, v149
	v_max_f32_e32 v149, v197, v197
	v_max_f32_e32 v148, v149, v148
	v_mfma_f32_32x32x16_bf16 v[16:31], v[208:211], v[238:241], v[16:31]
	v_sub_f32_e32 v149, v197, v148
	v_mul_f32_e32 v149, 0x3dd53b94, v149
	v_exp_f32_e32 v149, v149
	s_cmp_eq_u64 vcc, exec
	s_cselect_b64 s[8:9], -1, 0
	v_cndmask_b32_e64 v204, v149, 1.0, s[8:9]
	v_cmp_gt_f32_e32 vcc, 1.0, v204
	s_cbranch_vccz .LBB0_612
; #define SBAR() __builtin_amdgcn_sched_barrier(0)
; #define RESC(a) do { if (__any((a) < 1.f)) { if (hi == 0) al_l[r32] = (a); asm volatile("s_waitcnt lgkmcnt(0)" ::: "memory"); \
;     _Pragma("unroll") for (int d = 0; d < 4; ++d) _Pragma("unroll") for (int r = 0; r < 16; ++r) o[d][r] *= al_l[crow(r, hi)]; } } while (0)
; __device__ __forceinline__ void partialSM(f32x16& p0, f32x16& p1, float& m_reg, float& mn, float& alpha) {
;     constexpr float C = SCALE * 1.4426950408889634f;
;     float pmax = p0[0];
; #pragma unroll
;     for (int r = 1; r < 16; ++r) pmax = fmaxf(pmax, p0[r]);
; #pragma unroll
;     for (int r = 0; r < 16; ++r) pmax = fmaxf(pmax, p1[r]);
;     { auto rr = __builtin_amdgcn_permlane32_swap(__float_as_uint(pmax), __float_as_uint(pmax), false, false);
;       pmax = fmaxf(__uint_as_float(rr[0]), __uint_as_float(rr[1])); }
;     if (__builtin_expect(__all(pmax - m_reg <= THR / SCALE), 1)) { mn = m_reg; alpha = 1.f; }
;     else { mn = fmaxf(m_reg, pmax); alpha = __builtin_amdgcn_exp2f((m_reg - mn) * C); m_reg = mn; }
;     const float mnC = -mn * C;
; #pragma unroll
;     for (int r = 0; r < 16; ++r) p0[r] = fmaf(p0[r], C, mnC);
; #pragma unroll
;     for (int r = 0; r < 16; ++r) p1[r] = fmaf(p1[r], C, mnC);
; #pragma unroll
;     for (int r = 0; r < 16; ++r) p0[r] = __builtin_amdgcn_exp2f(p0[r]);
; }
; __device__ __forceinline__ void attn_body(const bf16_t* __restrict__ Qb, const bf16_t* __restrict__ Kh, const bf16_t* __restrict__ Vh, const bf16_t* __restrict__ Rh,
;                                           bf16_t* __restrict__ Zb, int seq, char* lds, int wv, bool nowrite) {
;     ...
;         RESC(alB); __syncthreads();
;         SBAR(); qkt(pA0, pA1, K_lds, R_lds, qr, Qp, r32, hi);
	s_and_saveexec_b64 s[10:11], s[6:7]
	ds_write_b32 v166, v204 offset:128
	s_or_b64 exec, exec, s[10:11]
	s_waitcnt lgkmcnt(0)
	v_add_u32_e32 v140, s1, v212
	ds_read_b128 v[128:131], v140 offset:224
	ds_read_b128 v[132:135], v140 offset:192
	ds_read_b128 v[136:139], v140 offset:160
	ds_read_b128 v[140:143], v140 offset:128
	s_waitcnt lgkmcnt(3)
	v_pk_mul_f32 v[12:13], v[12:13], v[128:129]
	s_waitcnt lgkmcnt(2)
	v_pk_mul_f32 v[8:9], v[8:9], v[132:133]
	s_waitcnt lgkmcnt(1)
	v_pk_mul_f32 v[4:5], v[4:5], v[136:137]
	v_pk_mul_f32 v[14:15], v[14:15], v[130:131]
	v_pk_mul_f32 v[10:11], v[10:11], v[134:135]
	v_pk_mul_f32 v[6:7], v[6:7], v[138:139]
	s_waitcnt lgkmcnt(0)
	v_pk_mul_f32 v[2:3], v[2:3], v[142:143]
	v_pk_mul_f32 v[0:1], v[0:1], v[140:141]
	v_pk_mul_f32 v[60:61], v[60:61], v[128:129]
	v_pk_mul_f32 v[56:57], v[56:57], v[132:133]
	v_pk_mul_f32 v[52:53], v[52:53], v[136:137]
	v_pk_mul_f32 v[62:63], v[62:63], v[130:131]
	v_pk_mul_f32 v[58:59], v[58:59], v[134:135]
	v_pk_mul_f32 v[54:55], v[54:55], v[138:139]
	v_pk_mul_f32 v[50:51], v[50:51], v[142:143]
	v_pk_mul_f32 v[48:49], v[48:49], v[140:141]
	v_pk_mul_f32 v[44:45], v[44:45], v[128:129]
	v_pk_mul_f32 v[40:41], v[40:41], v[132:133]
	v_pk_mul_f32 v[36:37], v[36:37], v[136:137]
	v_pk_mul_f32 v[46:47], v[46:47], v[130:131]
	v_pk_mul_f32 v[42:43], v[42:43], v[134:135]
	v_pk_mul_f32 v[38:39], v[38:39], v[138:139]
	v_pk_mul_f32 v[34:35], v[34:35], v[142:143]
	v_pk_mul_f32 v[32:33], v[32:33], v[140:141]
	v_pk_mul_f32 v[28:29], v[28:29], v[128:129]
	v_pk_mul_f32 v[24:25], v[24:25], v[132:133]
	v_pk_mul_f32 v[20:21], v[20:21], v[136:137]
	v_pk_mul_f32 v[30:31], v[30:31], v[130:131]
	v_pk_mul_f32 v[26:27], v[26:27], v[134:135]
	v_pk_mul_f32 v[22:23], v[22:23], v[138:139]
	v_pk_mul_f32 v[18:19], v[18:19], v[142:143]
	v_pk_mul_f32 v[16:17], v[16:17], v[140:141]
.LBB0_612:
	v_cndmask_b32_e64 v197, v148, v197, s[8:9]
	v_mul_f32_e32 v144, 0xbdd53b94, v197
	v_fmamk_f32 v80, v80, 0x3dd53b94, v144
	v_fmamk_f32 v81, v81, 0x3dd53b94, v144
	v_fmamk_f32 v82, v82, 0x3dd53b94, v144
	v_fmamk_f32 v83, v83, 0x3dd53b94, v144
	v_fmamk_f32 v84, v84, 0x3dd53b94, v144
	v_fmamk_f32 v85, v85, 0x3dd53b94, v144
	v_fmamk_f32 v86, v86, 0x3dd53b94, v144
	v_fmamk_f32 v87, v87, 0x3dd53b94, v144
	v_fmamk_f32 v88, v88, 0x3dd53b94, v144
	v_fmamk_f32 v89, v89, 0x3dd53b94, v144
	v_fmamk_f32 v90, v90, 0x3dd53b94, v144
	v_fmamk_f32 v91, v91, 0x3dd53b94, v144
	v_fmamk_f32 v92, v92, 0x3dd53b94, v144
	v_fmamk_f32 v93, v93, 0x3dd53b94, v144
	v_fmamk_f32 v94, v94, 0x3dd53b94, v144
	v_fmamk_f32 v95, v95, 0x3dd53b94, v144
	v_fmamk_f32 v206, v68, 0x3dd53b94, v144
	v_fmamk_f32 v148, v71, 0x3dd53b94, v144
	v_fmamk_f32 v149, v72, 0x3dd53b94, v144
	v_fmamk_f32 v207, v77, 0x3dd53b94, v144
	v_fmamk_f32 v153, v64, 0x3dd53b94, v144
	v_fmamk_f32 v154, v65, 0x3dd53b94, v144
	v_fmamk_f32 v155, v66, 0x3dd53b94, v144
	v_fmamk_f32 v205, v67, 0x3dd53b94, v144
	v_fmamk_f32 v146, v69, 0x3dd53b94, v144
	v_fmamk_f32 v147, v70, 0x3dd53b94, v144
	v_fmamk_f32 v150, v73, 0x3dd53b94, v144
	v_fmamk_f32 v151, v74, 0x3dd53b94, v144
	v_fmamk_f32 v152, v75, 0x3dd53b94, v144
	v_fmamk_f32 v145, v76, 0x3dd53b94, v144
	v_exp_f32_e32 v141, v80
	v_exp_f32_e32 v143, v81
	v_exp_f32_e32 v139, v82
	v_exp_f32_e32 v142, v83
	v_exp_f32_e32 v138, v84
	v_exp_f32_e32 v140, v85
	v_exp_f32_e32 v136, v86
	v_exp_f32_e32 v137, v87
	v_exp_f32_e32 v133, v88
	v_exp_f32_e32 v135, v89
	v_exp_f32_e32 v132, v90
	v_exp_f32_e32 v134, v91
	v_exp_f32_e32 v129, v92
	v_exp_f32_e32 v131, v93
	v_exp_f32_e32 v128, v94
	v_exp_f32_e32 v130, v95
	v_fmamk_f32 v208, v78, 0x3dd53b94, v144
	v_fmac_f32_e32 v144, 0x3dd53b94, v79
	s_waitcnt vmcnt(0)
	s_waitcnt lgkmcnt(0)
	s_barrier
	ds_read_b128 v[64:67], v174 offset:32768
	ds_read_b128 v[68:71], v174 offset:40960
	ds_read_b128 v[214:217], v180 offset:32768
	ds_read_b128 v[218:221], v180 offset:40960
	v_exp_f32_e32 v209, v153
	v_exp_f32_e32 v210, v154
	s_waitcnt lgkmcnt(3)
	v_mfma_f32_32x32x16_bf16 v[80:95], v[64:67], v[120:123], 0
	v_exp_f32_e32 v211, v155
	v_exp_f32_e32 v205, v205
	v_exp_f32_e32 v146, v146
	v_exp_f32_e32 v147, v147
	v_exp_f32_e32 v145, v145
	v_exp_f32_e32 v144, v144
	s_waitcnt lgkmcnt(2)
	v_mfma_f32_32x32x16_bf16 v[64:79], v[68:71], v[120:123], 0
	s_waitcnt lgkmcnt(1)
	v_mfma_f32_32x32x16_bf16 v[80:95], v[214:217], v[124:127], v[80:95]
	s_waitcnt lgkmcnt(0)
	v_mfma_f32_32x32x16_bf16 v[64:79], v[218:221], v[124:127], v[64:79]
	ds_read_b128 v[214:217], v182 offset:32768
	ds_read_b128 v[218:221], v182 offset:40960
	s_waitcnt lgkmcnt(1)
	v_mfma_f32_32x32x16_bf16 v[80:95], v[214:217], v[116:119], v[80:95]
	s_waitcnt lgkmcnt(0)
	v_mfma_f32_32x32x16_bf16 v[64:79], v[218:221], v[116:119], v[64:79]
	ds_read_b128 v[214:217], v184 offset:32768
	ds_read_b128 v[218:221], v184 offset:40960
	s_waitcnt lgkmcnt(1)
	v_mfma_f32_32x32x16_bf16 v[80:95], v[214:217], v[112:115], v[80:95]
	s_waitcnt lgkmcnt(0)
	v_mfma_f32_32x32x16_bf16 v[64:79], v[218:221], v[112:115], v[64:79]
	ds_read_b128 v[214:217], v185 offset:32768
	ds_read_b128 v[218:221], v185 offset:40960
	s_waitcnt lgkmcnt(1)
	v_mfma_f32_32x32x16_bf16 v[80:95], v[214:217], v[108:111], v[80:95]
	s_waitcnt lgkmcnt(0)
	v_mfma_f32_32x32x16_bf16 v[64:79], v[218:221], v[108:111], v[64:79]
	ds_read_b128 v[214:217], v183 offset:32768
	ds_read_b128 v[218:221], v183 offset:40960
	s_waitcnt lgkmcnt(1)
	v_mfma_f32_32x32x16_bf16 v[80:95], v[214:217], v[104:107], v[80:95]
	s_waitcnt lgkmcnt(0)
	v_mfma_f32_32x32x16_bf16 v[64:79], v[218:221], v[104:107], v[64:79]
	ds_read_b128 v[214:217], v181 offset:32768
	ds_read_b128 v[218:221], v181 offset:40960
	s_waitcnt lgkmcnt(1)
	v_mfma_f32_32x32x16_bf16 v[80:95], v[214:217], v[100:103], v[80:95]
	s_waitcnt lgkmcnt(0)
; __device__ __forceinline__ void finishSM(f32x16& p0, f32x16& p1, float alpha, float& l_reg, bf16x8& pa0, bf16x8& pa1, bf16x8& pa2, bf16x8& pa3) {
; #pragma unroll
;     for (int r = 0; r < 16; ++r) p1[r] = __builtin_amdgcn_exp2f(p1[r]);
;     float ps = 0;
; #pragma unroll
;     for (int r = 0; r < 16; ++r) ps += p0[r];
; #pragma unroll
;     for (int r = 0; r < 16; ++r) ps += p1[r];
;     { auto rr = __builtin_amdgcn_permlane32_swap(__float_as_uint(ps), __float_as_uint(ps), false, false);
;       ps = __uint_as_float(rr[0]) + __uint_as_float(rr[1]); }
;     l_reg = l_reg * alpha + ps;
;     ...
;     PK4(p0, 0, pa0); PK4(p0, 8, pa1); PK4(p1, 0, pa2); PK4(p1, 8, pa3);
;     ...
; }
; __device__ __forceinline__ void qkt(f32x16& p0, f32x16& p1, const char* Ks, const char* Rs, const bf16x8* qr, const char* Qp, int r32, int hi) {
;     p0 = f32x16{}; p1 = f32x16{};
; #pragma unroll
;     for (int d0 = 0; d0 < 8; ++d0) { const int cb = (d0 * 16 + hi * 8) * 2;
;         const bf16x8 b0 = *reinterpret_cast<const bf16x8*>(Ks + KSWZ(r32, cb));
;         const bf16x8 b1 = *reinterpret_cast<const bf16x8*>(Ks + KSWZ(32 + r32, cb));
;         p0 = __builtin_amdgcn_mfma_f32_32x32x16_bf16(b0, qr[d0], p0, 0, 0, 0);
;         p1 = __builtin_amdgcn_mfma_f32_32x32x16_bf16(b1, qr[d0], p1, 0, 0, 0); }
; #pragma unroll
;     for (int d0 = 0; d0 < 4; ++d0) { const int cb = (d0 * 16 + hi * 8) * 2;
;         const bf16x8 b0 = *reinterpret_cast<const bf16x8*>(Rs + RSWZ(r32, cb));
;         const bf16x8 b1 = *reinterpret_cast<const bf16x8*>(Rs + RSWZ(32 + r32, cb));
;         const bf16x8 qq = *reinterpret_cast<const bf16x8*>(Qp + RSWZ(r32, cb));
;         p0 = __builtin_amdgcn_mfma_f32_32x32x16_bf16(b0, qq, p0, 0, 0, 0);
;         p1 = __builtin_amdgcn_mfma_f32_32x32x16_bf16(b1, qq, p1, 0, 0, 0); }
; }
; __device__ __forceinline__ int v_st(int k, int c) { const int kk = (k & ~0xC) | ((k & 4) << 1) | ((k & 8) >> 1); return ((kk >> 3) * 4 + (c >> 5)) * 512 + ((kk & 7) * 32 + (c & 31)) * 2; }
; __device__ __forceinline__ int v_rd_base(int lane) { return ((lane & 3) << 3) | (((lane >> 2) & 3) << 6) | (((lane >> 4) & 1) << 5) | (((lane >> 5) & 1) << 8); }
; template <int OFF> __device__ __forceinline__ s16x4 tr_read(int vb) {
;     s16x4 r; asm volatile("ds_read_b64_tr_b16 %0, %1 offset:%2" : "=&v"(r) : "v"(vb), "i"(OFF) : "memory"); return r;
; }
	v_mfma_f32_32x32x16_bf16 v[64:79], v[218:221], v[100:103], v[64:79]
	ds_read_b128 v[214:217], v179 offset:32768
	ds_read_b128 v[218:221], v179 offset:40960
	s_waitcnt lgkmcnt(1)
	v_mfma_f32_32x32x16_bf16 v[80:95], v[214:217], v[96:99], v[80:95]
	s_waitcnt lgkmcnt(0)
	v_mfma_f32_32x32x16_bf16 v[64:79], v[218:221], v[96:99], v[64:79]
	ds_read_b128 v[214:217], v187
	ds_read_b128 v[218:221], v187 offset:4096
	ds_read_b128 v[224:227], v177
	s_waitcnt lgkmcnt(0)
	v_mfma_f32_32x32x16_bf16 v[80:95], v[214:217], v[224:227], v[80:95]
	v_mfma_f32_32x32x16_bf16 v[64:79], v[218:221], v[224:227], v[64:79]
	ds_read_b128 v[214:217], v189
	ds_read_b128 v[218:221], v189 offset:4096
	ds_read_b128 v[224:227], v175
	s_waitcnt lgkmcnt(0)
	v_mfma_f32_32x32x16_bf16 v[80:95], v[214:217], v[224:227], v[80:95]
	v_mfma_f32_32x32x16_bf16 v[64:79], v[218:221], v[224:227], v[64:79]
	ds_read_b128 v[214:217], v191
	ds_read_b128 v[218:221], v191 offset:4096
	ds_read_b128 v[224:227], v178
	s_waitcnt lgkmcnt(0)
	v_mfma_f32_32x32x16_bf16 v[80:95], v[214:217], v[224:227], v[80:95]
	v_mfma_f32_32x32x16_bf16 v[64:79], v[218:221], v[224:227], v[64:79]
	ds_read_b128 v[214:217], v193
	ds_read_b128 v[218:221], v193 offset:4096
	ds_read_b128 v[224:227], v176
	s_waitcnt lgkmcnt(0)
	v_mfma_f32_32x32x16_bf16 v[80:95], v[214:217], v[224:227], v[80:95]
	v_exp_f32_e32 v215, v148
	v_add_f32_e32 v148, 0, v141
	v_add_f32_e32 v148, v143, v148
	v_add_f32_e32 v148, v139, v148
	v_add_f32_e32 v148, v142, v148
	v_add_f32_e32 v148, v138, v148
	v_add_f32_e32 v148, v140, v148
	v_add_f32_e32 v148, v136, v148
	v_add_f32_e32 v148, v137, v148
	v_add_f32_e32 v148, v133, v148
	v_add_f32_e32 v148, v135, v148
	v_add_f32_e32 v148, v132, v148
	v_add_f32_e32 v148, v134, v148
	v_add_f32_e32 v148, v129, v148
	v_add_f32_e32 v148, v131, v148
	v_add_f32_e32 v148, v128, v148
	v_add_f32_e32 v148, v130, v148
	v_exp_f32_e32 v214, v206
	v_add_f32_e32 v148, v209, v148
	v_add_f32_e32 v148, v210, v148
	v_add_f32_e32 v148, v211, v148
	v_add_f32_e32 v148, v205, v148
	v_exp_f32_e32 v216, v149
	v_add_f32_e32 v148, v214, v148
	v_exp_f32_e32 v217, v150
	v_add_f32_e32 v148, v146, v148
	v_mfma_f32_32x32x16_bf16 v[64:79], v[218:221], v[224:227], v[64:79]
	v_exp_f32_e32 v218, v151
	v_add_f32_e32 v148, v147, v148
	v_exp_f32_e32 v219, v152
	v_add_f32_e32 v148, v215, v148
	v_add_f32_e32 v148, v216, v148
	v_exp_f32_e32 v220, v207
	v_add_f32_e32 v148, v217, v148
	v_exp_f32_e32 v221, v208
	v_add_f32_e32 v148, v218, v148
	v_add_f32_e32 v148, v219, v148
	v_add_f32_e32 v148, v145, v148
	v_add_f32_e32 v148, v220, v148
	v_add_f32_e32 v148, v221, v148
	v_add_f32_e32 v206, v144, v148
	v_mov_b32_e32 v207, v206
	v_cvt_pk_bf16_f32 v148, v141, v143
	v_cvt_pk_bf16_f32 v149, v139, v142
	v_cvt_pk_bf16_f32 v150, v138, v140
	v_cvt_pk_bf16_f32 v151, v136, v137
	s_nop 1
	v_permlane32_swap_b32_e32 v206, v207
	v_permlane32_swap_b32_e32 v148, v150
	v_permlane32_swap_b32_e32 v149, v151
	v_cvt_pk_bf16_f32 v152, v133, v135
	v_cvt_pk_bf16_f32 v153, v132, v134
	v_cvt_pk_bf16_f32 v154, v129, v131
	v_cvt_pk_bf16_f32 v155, v128, v130
	v_cvt_pk_bf16_f32 v208, v209, v210
	v_cvt_pk_bf16_f32 v209, v211, v205
	v_cvt_pk_bf16_f32 v210, v214, v146
	v_cvt_pk_bf16_f32 v211, v147, v215
	v_cvt_pk_bf16_f32 v214, v216, v217
	v_cvt_pk_bf16_f32 v215, v218, v219
	v_cvt_pk_bf16_f32 v216, v145, v220
	v_cvt_pk_bf16_f32 v217, v221, v144
	s_nop 0
	v_permlane32_swap_b32_e32 v152, v154
	v_permlane32_swap_b32_e32 v153, v155
	v_permlane32_swap_b32_e32 v208, v210
	v_permlane32_swap_b32_e32 v209, v211
	v_permlane32_swap_b32_e32 v214, v216
	v_permlane32_swap_b32_e32 v215, v217
	s_add_i32 m0, s37, 0x0
	s_nop 0
	global_load_lds_dwordx4 v242, s[44:45]
	s_add_i32 m0, s37, 0x2000
	v_add_u32_e32 v242, 0x40000, v242
	global_load_lds_dwordx4 v243, s[44:45]
	s_add_i32 m0, s37, 0xc000
	v_add_u32_e32 v243, 0x40000, v243
	global_load_lds_dwordx4 v244, s[44:45]
	s_add_i32 m0, s37, 0xe000
	v_add_u32_e32 v244, 0x40000, v244
	global_load_lds_dwordx4 v245, s[44:45]
	s_add_i32 m0, s37, 0x12000
	v_add_u32_e32 v245, 0x40000, v245
	global_load_lds_dwordx4 v246, s[44:45]
	v_add_u32_e32 v246, 0x2000, v246
	ds_read_b64_tr_b16 v[160:161], v168 offset:0
	ds_read_b64_tr_b16 v[162:163], v168 offset:0x800
	ds_read_b64_tr_b16 v[218:219], v168 offset:0x1000
	ds_read_b64_tr_b16 v[220:221], v168 offset:0x1800
	ds_read_b64_tr_b16 v[224:225], v168 offset:0x2000
	ds_read_b64_tr_b16 v[226:227], v168 offset:0x2800
	ds_read_b64_tr_b16 v[238:239], v168 offset:0x3000
	ds_read_b64_tr_b16 v[240:241], v168 offset:0x3800
	s_waitcnt lgkmcnt(0)
	s_nop 0
	v_mfma_f32_32x32x16_bf16 v[0:15], v[148:151], v[160:163], v[0:15]
	ds_read_b64_tr_b16 v[160:161], v168 offset:0x200
	ds_read_b64_tr_b16 v[162:163], v168 offset:0xa00
	v_mfma_f32_32x32x16_bf16 v[0:15], v[152:155], v[218:221], v[0:15]
	ds_read_b64_tr_b16 v[218:219], v168 offset:0x1200
	ds_read_b64_tr_b16 v[220:221], v168 offset:0x1a00
	v_mfma_f32_32x32x16_bf16 v[0:15], v[208:211], v[224:227], v[0:15]
	ds_read_b64_tr_b16 v[224:225], v168 offset:0x2200
	ds_read_b64_tr_b16 v[226:227], v168 offset:0x2a00
	v_mfma_f32_32x32x16_bf16 v[0:15], v[214:217], v[238:241], v[0:15]
	ds_read_b64_tr_b16 v[238:239], v168 offset:0x3200
	ds_read_b64_tr_b16 v[240:241], v168 offset:0x3a00
	s_waitcnt lgkmcnt(0)
	v_mfma_f32_32x32x16_bf16 v[48:63], v[148:151], v[160:163], v[48:63]
	ds_read_b64_tr_b16 v[160:161], v168 offset:0x400
	ds_read_b64_tr_b16 v[162:163], v168 offset:0xc00
	v_mfma_f32_32x32x16_bf16 v[48:63], v[152:155], v[218:221], v[48:63]
	ds_read_b64_tr_b16 v[218:219], v168 offset:0x1400
	ds_read_b64_tr_b16 v[220:221], v168 offset:0x1c00
	v_mfma_f32_32x32x16_bf16 v[48:63], v[208:211], v[224:227], v[48:63]
	ds_read_b64_tr_b16 v[224:225], v168 offset:0x2400
	ds_read_b64_tr_b16 v[226:227], v168 offset:0x2c00
	v_mfma_f32_32x32x16_bf16 v[48:63], v[214:217], v[238:241], v[48:63]
	ds_read_b64_tr_b16 v[238:239], v168 offset:0x3400
	ds_read_b64_tr_b16 v[240:241], v168 offset:0x3c00
	s_waitcnt lgkmcnt(0)
; #define SWRITE(b) do { *(bf16x8*)(V_lds + (b) * SHM_V + vst0) = vs0; *(bf16x8*)(V_lds + (b) * SHM_V + vst1) = vs1; const int kc = sc * 2; \
;     *(bf16x8*)(K_lds + (b) * SHM_K + KSWZ(sr, kc)) = ks0; *(bf16x8*)(K_lds + (b) * SHM_K + KSWZ(32 + sr, kc)) = ks1; \
;     *(bf16x8*)(R_lds + (b) * SHM_R + RSWZ(rr, rc * 2)) = rs0; } while (0)
; #define SWAIT() asm volatile("s_waitcnt vmcnt(0)" ::: "memory")
; #define RESC(a) do { if (__any((a) < 1.f)) { if (hi == 0) al_l[r32] = (a); asm volatile("s_waitcnt lgkmcnt(0)" ::: "memory"); \
;     _Pragma("unroll") for (int d = 0; d < 4; ++d) _Pragma("unroll") for (int r = 0; r < 16; ++r) o[d][r] *= al_l[crow(r, hi)]; } } while (0)
; __device__ __forceinline__ void partialSM(f32x16& p0, f32x16& p1, float& m_reg, float& mn, float& alpha) {
;     constexpr float C = SCALE * 1.4426950408889634f;
;     float pmax = p0[0];
; #pragma unroll
;     for (int r = 1; r < 16; ++r) pmax = fmaxf(pmax, p0[r]);
; #pragma unroll
;     for (int r = 0; r < 16; ++r) pmax = fmaxf(pmax, p1[r]);
;     { auto rr = __builtin_amdgcn_permlane32_swap(__float_as_uint(pmax), __float_as_uint(pmax), false, false);
;       pmax = fmaxf(__uint_as_float(rr[0]), __uint_as_float(rr[1])); }
;     if (__builtin_expect(__all(pmax - m_reg <= THR / SCALE), 1)) { mn = m_reg; alpha = 1.f; }
;     else { mn = fmaxf(m_reg, pmax); alpha = __builtin_amdgcn_exp2f((m_reg - mn) * C); m_reg = mn; }
;     const float mnC = -mn * C;
; #pragma unroll
;     for (int r = 0; r < 16; ++r) p0[r] = fmaf(p0[r], C, mnC);
; #pragma unroll
;     for (int r = 0; r < 16; ++r) p1[r] = fmaf(p1[r], C, mnC);
; #pragma unroll
;     for (int r = 0; r < 16; ++r) p0[r] = __builtin_amdgcn_exp2f(p0[r]);
; }
; __device__ __forceinline__ void attn_body(const bf16_t* __restrict__ Qb, const bf16_t* __restrict__ Kh, const bf16_t* __restrict__ Vh, const bf16_t* __restrict__ Rh,
;                                           bf16_t* __restrict__ Zb, int seq, char* lds, int wv, bool nowrite) {
;     ...
;         pv_d0(o, vb0 + SHM_V, pa0, pa1, pa2, pa3); partialSM(pA0, pA1, m_reg, mnA, alA);
;         __syncthreads(); SWAIT(); SWRITE(1);
;         RESC(alA); __syncthreads();
	v_mfma_f32_32x32x16_bf16 v[32:47], v[148:151], v[160:163], v[32:47]
	ds_read_b64_tr_b16 v[160:161], v168 offset:0x600
	ds_read_b64_tr_b16 v[162:163], v168 offset:0xe00
	v_mfma_f32_32x32x16_bf16 v[32:47], v[152:155], v[218:221], v[32:47]
	ds_read_b64_tr_b16 v[218:219], v168 offset:0x1600
	ds_read_b64_tr_b16 v[220:221], v168 offset:0x1e00
	v_mfma_f32_32x32x16_bf16 v[32:47], v[208:211], v[224:227], v[32:47]
	ds_read_b64_tr_b16 v[224:225], v168 offset:0x2600
	ds_read_b64_tr_b16 v[226:227], v168 offset:0x2e00
	v_mfma_f32_32x32x16_bf16 v[32:47], v[214:217], v[238:241], v[32:47]
	ds_read_b64_tr_b16 v[238:239], v168 offset:0x3600
	ds_read_b64_tr_b16 v[240:241], v168 offset:0x3e00
	s_waitcnt lgkmcnt(0)
	v_mfma_f32_32x32x16_bf16 v[16:31], v[148:151], v[160:163], v[16:31]
	v_max_f32_e32 v148, v81, v81
	v_max_f32_e32 v149, v80, v80
	v_max_f32_e32 v148, v149, v148
	v_max3_f32 v148, v148, v82, v83
	v_max3_f32 v148, v148, v84, v85
	v_max3_f32 v148, v148, v86, v87
	v_max3_f32 v148, v148, v88, v89
	v_max3_f32 v148, v148, v90, v91
	v_max3_f32 v148, v148, v92, v93
	v_mfma_f32_32x32x16_bf16 v[16:31], v[152:155], v[218:221], v[16:31]
	v_max3_f32 v148, v148, v94, v95
	v_max3_f32 v148, v148, v64, v65
	v_max3_f32 v148, v148, v66, v67
	v_max3_f32 v148, v148, v68, v69
	v_max3_f32 v148, v148, v70, v71
	v_max3_f32 v148, v148, v72, v73
	v_max3_f32 v148, v148, v74, v75
	v_max3_f32 v148, v148, v76, v77
	v_mfma_f32_32x32x16_bf16 v[16:31], v[208:211], v[224:227], v[16:31]
	v_max3_f32 v148, v148, v78, v79
	v_mov_b32_e32 v149, v148
	s_nop 1
	v_permlane32_swap_b32_e32 v148, v149
	v_max_f32_e32 v149, v149, v149
	v_max_f32_e32 v148, v148, v148
	v_max_f32_e32 v148, v148, v149
	v_sub_f32_e32 v149, v148, v197
	v_cmp_ge_f32_e32 vcc, s88, v149
	v_max_f32_e32 v149, v197, v197
	v_max_f32_e32 v149, v149, v148
	v_mfma_f32_32x32x16_bf16 v[16:31], v[214:217], v[238:241], v[16:31]
	v_sub_f32_e32 v148, v197, v149
	v_mul_f32_e32 v148, 0x3dd53b94, v148
	v_exp_f32_e32 v148, v148
	s_cmp_eq_u64 vcc, exec
	s_cselect_b64 s[8:9], -1, 0
	v_cndmask_b32_e64 v148, v148, 1.0, s[8:9]
	v_cmp_gt_f32_e32 vcc, 1.0, v148
	s_cbranch_vccz .LBB0_616
	s_and_saveexec_b64 s[10:11], s[6:7]
	ds_write_b32 v166, v148 offset:128
	s_or_b64 exec, exec, s[10:11]
	s_waitcnt lgkmcnt(0)
	v_add_u32_e32 v140, s1, v212
	ds_read_b128 v[128:131], v140 offset:224
	ds_read_b128 v[132:135], v140 offset:192
	ds_read_b128 v[136:139], v140 offset:160
	ds_read_b128 v[140:143], v140 offset:128
	s_waitcnt lgkmcnt(3)
	v_pk_mul_f32 v[12:13], v[12:13], v[128:129]
	s_waitcnt lgkmcnt(2)
	v_pk_mul_f32 v[8:9], v[8:9], v[132:133]
	s_waitcnt lgkmcnt(1)
	v_pk_mul_f32 v[4:5], v[4:5], v[136:137]
	v_pk_mul_f32 v[14:15], v[14:15], v[130:131]
	v_pk_mul_f32 v[10:11], v[10:11], v[134:135]
	v_pk_mul_f32 v[6:7], v[6:7], v[138:139]
	s_waitcnt lgkmcnt(0)
	v_pk_mul_f32 v[2:3], v[2:3], v[142:143]
	v_pk_mul_f32 v[0:1], v[0:1], v[140:141]
	v_pk_mul_f32 v[60:61], v[60:61], v[128:129]
	v_pk_mul_f32 v[56:57], v[56:57], v[132:133]
	v_pk_mul_f32 v[52:53], v[52:53], v[136:137]
	v_pk_mul_f32 v[62:63], v[62:63], v[130:131]
	v_pk_mul_f32 v[58:59], v[58:59], v[134:135]
	v_pk_mul_f32 v[54:55], v[54:55], v[138:139]
	v_pk_mul_f32 v[50:51], v[50:51], v[142:143]
	v_pk_mul_f32 v[48:49], v[48:49], v[140:141]
	v_pk_mul_f32 v[44:45], v[44:45], v[128:129]
	v_pk_mul_f32 v[40:41], v[40:41], v[132:133]
	v_pk_mul_f32 v[36:37], v[36:37], v[136:137]
	v_pk_mul_f32 v[46:47], v[46:47], v[130:131]
	v_pk_mul_f32 v[42:43], v[42:43], v[134:135]
	v_pk_mul_f32 v[38:39], v[38:39], v[138:139]
	v_pk_mul_f32 v[34:35], v[34:35], v[142:143]
	v_pk_mul_f32 v[32:33], v[32:33], v[140:141]
	v_pk_mul_f32 v[28:29], v[28:29], v[128:129]
	v_pk_mul_f32 v[24:25], v[24:25], v[132:133]
	v_pk_mul_f32 v[20:21], v[20:21], v[136:137]
	v_pk_mul_f32 v[30:31], v[30:31], v[130:131]
	v_pk_mul_f32 v[26:27], v[26:27], v[134:135]
	v_pk_mul_f32 v[22:23], v[22:23], v[138:139]
	v_pk_mul_f32 v[18:19], v[18:19], v[142:143]
	v_pk_mul_f32 v[16:17], v[16:17], v[140:141]
.LBB0_616:
	v_cndmask_b32_e64 v197, v149, v197, s[8:9]
	v_mul_f32_e32 v134, 0xbdd53b94, v197
	v_mov_b32_e32 v135, v134
	v_fmamk_f32 v80, v80, 0x3dd53b94, v134
	v_fmamk_f32 v81, v81, 0x3dd53b94, v134
	v_fmamk_f32 v82, v82, 0x3dd53b94, v134
	v_fmamk_f32 v83, v83, 0x3dd53b94, v134
	v_fmamk_f32 v84, v84, 0x3dd53b94, v134
	v_fmamk_f32 v85, v85, 0x3dd53b94, v134
	v_fmamk_f32 v86, v86, 0x3dd53b94, v134
	v_fmamk_f32 v87, v87, 0x3dd53b94, v134
	v_fmamk_f32 v88, v88, 0x3dd53b94, v134
	v_fmamk_f32 v89, v89, 0x3dd53b94, v134
	v_fmamk_f32 v90, v90, 0x3dd53b94, v134
	v_fmamk_f32 v91, v91, 0x3dd53b94, v134
	v_fmamk_f32 v92, v92, 0x3dd53b94, v134
	v_fmamk_f32 v93, v93, 0x3dd53b94, v134
	v_fmamk_f32 v94, v94, 0x3dd53b94, v134
	v_fmac_f32_e32 v135, 0x3dd53b94, v95
	v_exp_f32_e32 v162, v80
	v_exp_f32_e32 v205, v81
	v_exp_f32_e32 v149, v82
	v_exp_f32_e32 v163, v83
	v_exp_f32_e32 v150, v84
	v_exp_f32_e32 v161, v85
	v_exp_f32_e32 v151, v86
	v_exp_f32_e32 v160, v87
	v_exp_f32_e32 v152, v88
	v_exp_f32_e32 v155, v89
	v_exp_f32_e32 v153, v90
	v_exp_f32_e32 v154, v91
	v_exp_f32_e32 v145, v92
	v_exp_f32_e32 v147, v93
	v_exp_f32_e32 v144, v94
	v_exp_f32_e32 v146, v135
	v_pk_fma_f32 v[140:141], v[64:65], s[36:37], v[134:135] op_sel_hi:[1,0,0]
	v_add_f32_e32 v64, v202, v203
	v_fmac_f32_e32 v64, v194, v167
	v_add_f32_e32 v167, v206, v207
	s_add_i32 s3, s3, 2
	v_pk_fma_f32 v[138:139], v[66:67], s[36:37], v[134:135] op_sel_hi:[1,0,0]
	v_pk_fma_f32 v[132:133], v[68:69], s[36:37], v[134:135] op_sel_hi:[1,0,0]
	v_pk_fma_f32 v[130:131], v[70:71], s[36:37], v[134:135] op_sel_hi:[1,0,0]
	v_pk_fma_f32 v[128:129], v[72:73], s[36:37], v[134:135] op_sel_hi:[1,0,0]
	v_pk_fma_f32 v[142:143], v[74:75], s[36:37], v[134:135] op_sel_hi:[1,0,0]
	v_pk_fma_f32 v[136:137], v[76:77], s[36:37], v[134:135] op_sel_hi:[1,0,0]
	v_pk_fma_f32 v[134:135], v[78:79], s[36:37], v[134:135] op_sel_hi:[1,0,0]
	v_fmac_f32_e32 v167, v64, v204
	s_cmp_gt_u32 s3, 28
	s_waitcnt vmcnt(0)
	s_waitcnt lgkmcnt(0)
	s_barrier
; __device__ __forceinline__ void finishSM(f32x16& p0, f32x16& p1, float alpha, float& l_reg, bf16x8& pa0, bf16x8& pa1, bf16x8& pa2, bf16x8& pa3) {
; #pragma unroll
;     for (int r = 0; r < 16; ++r) p1[r] = __builtin_amdgcn_exp2f(p1[r]);
;     float ps = 0;
; #pragma unroll
;     for (int r = 0; r < 16; ++r) ps += p0[r];
; #pragma unroll
;     for (int r = 0; r < 16; ++r) ps += p1[r];
;     { auto rr = __builtin_amdgcn_permlane32_swap(__float_as_uint(ps), __float_as_uint(ps), false, false);
;       ps = __uint_as_float(rr[0]) + __uint_as_float(rr[1]); }
;     l_reg = l_reg * alpha + ps;
;     ...
;     PK4(p0, 0, pa0); PK4(p0, 8, pa1); PK4(p1, 0, pa2); PK4(p1, 8, pa3);
;     ...
; }
; __device__ __forceinline__ void qkt(f32x16& p0, f32x16& p1, const char* Ks, const char* Rs, const bf16x8* qr, const char* Qp, int r32, int hi) {
;     p0 = f32x16{}; p1 = f32x16{};
; #pragma unroll
;     for (int d0 = 0; d0 < 8; ++d0) { const int cb = (d0 * 16 + hi * 8) * 2;
;         const bf16x8 b0 = *reinterpret_cast<const bf16x8*>(Ks + KSWZ(r32, cb));
;         const bf16x8 b1 = *reinterpret_cast<const bf16x8*>(Ks + KSWZ(32 + r32, cb));
;         p0 = __builtin_amdgcn_mfma_f32_32x32x16_bf16(b0, qr[d0], p0, 0, 0, 0);
;         p1 = __builtin_amdgcn_mfma_f32_32x32x16_bf16(b1, qr[d0], p1, 0, 0, 0); }
; #pragma unroll
;     for (int d0 = 0; d0 < 4; ++d0) { const int cb = (d0 * 16 + hi * 8) * 2;
;         const bf16x8 b0 = *reinterpret_cast<const bf16x8*>(Rs + RSWZ(r32, cb));
;         const bf16x8 b1 = *reinterpret_cast<const bf16x8*>(Rs + RSWZ(32 + r32, cb));
;         const bf16x8 qq = *reinterpret_cast<const bf16x8*>(Qp + RSWZ(r32, cb));
;         p0 = __builtin_amdgcn_mfma_f32_32x32x16_bf16(b0, qq, p0, 0, 0, 0);
;         p1 = __builtin_amdgcn_mfma_f32_32x32x16_bf16(b1, qq, p1, 0, 0, 0); }
; }
	s_cbranch_scc1 .LBB0_618
	v_mov_b32_e32 v194, v148
	ds_read_b128 v[64:67], v174 offset:49152
	ds_read_b128 v[68:71], v174 offset:57344
	ds_read_b128 v[198:201], v180 offset:49152
	ds_read_b128 v[206:209], v180 offset:57344
	s_add_i32 s8, 0, 0x12000
	v_add_f32_e32 v148, 0, v162
	s_waitcnt lgkmcnt(3)
	v_mfma_f32_32x32x16_bf16 v[80:95], v[64:67], v[120:123], 0
	v_add_f32_e32 v148, v205, v148
	v_add_f32_e32 v148, v149, v148
	v_add_f32_e32 v148, v163, v148
	v_add_f32_e32 v148, v150, v148
	v_add_f32_e32 v148, v161, v148
	v_add_f32_e32 v148, v151, v148
	v_add_f32_e32 v148, v160, v148
	s_waitcnt lgkmcnt(2)
	v_mfma_f32_32x32x16_bf16 v[64:79], v[68:71], v[120:123], 0
	v_add_f32_e32 v148, v152, v148
	v_add_f32_e32 v148, v155, v148
	v_add_f32_e32 v148, v153, v148
	v_add_f32_e32 v148, v154, v148
	v_exp_f32_e32 v140, v140
	v_add_f32_e32 v148, v145, v148
	v_exp_f32_e32 v141, v141
	s_waitcnt lgkmcnt(1)
	v_mfma_f32_32x32x16_bf16 v[80:95], v[198:201], v[124:127], v[80:95]
	v_add_f32_e32 v148, v147, v148
	v_exp_f32_e32 v138, v138
	v_add_f32_e32 v148, v144, v148
	v_exp_f32_e32 v139, v139
	v_add_f32_e32 v148, v146, v148
	v_exp_f32_e32 v132, v132
	v_add_f32_e32 v148, v140, v148
	s_waitcnt lgkmcnt(0)
	v_mfma_f32_32x32x16_bf16 v[64:79], v[206:209], v[124:127], v[64:79]
	ds_read_b128 v[198:201], v182 offset:49152
	ds_read_b128 v[206:209], v182 offset:57344
	v_exp_f32_e32 v133, v133
	v_add_f32_e32 v148, v141, v148
	v_exp_f32_e32 v130, v130
	v_add_f32_e32 v148, v138, v148
	v_exp_f32_e32 v131, v131
	v_add_f32_e32 v148, v139, v148
	s_waitcnt lgkmcnt(1)
	v_mfma_f32_32x32x16_bf16 v[80:95], v[198:201], v[116:119], v[80:95]
	v_exp_f32_e32 v128, v128
	v_add_f32_e32 v148, v132, v148
	v_exp_f32_e32 v129, v129
	v_add_f32_e32 v148, v133, v148
	v_exp_f32_e32 v142, v142
	v_add_f32_e32 v148, v130, v148
	v_exp_f32_e32 v143, v143
	s_waitcnt lgkmcnt(0)
	v_mfma_f32_32x32x16_bf16 v[64:79], v[206:209], v[116:119], v[64:79]
	ds_read_b128 v[198:201], v184 offset:49152
	ds_read_b128 v[206:209], v184 offset:57344
	v_add_f32_e32 v148, v131, v148
	v_exp_f32_e32 v136, v136
	v_add_f32_e32 v148, v128, v148
	v_exp_f32_e32 v137, v137
	v_add_f32_e32 v148, v129, v148
	v_exp_f32_e32 v134, v134
	s_waitcnt lgkmcnt(1)
	v_mfma_f32_32x32x16_bf16 v[80:95], v[198:201], v[112:115], v[80:95]
	v_add_f32_e32 v148, v142, v148
	v_exp_f32_e32 v135, v135
	v_add_f32_e32 v148, v143, v148
	v_add_f32_e32 v148, v136, v148
	v_add_f32_e32 v148, v137, v148
	v_add_f32_e32 v148, v134, v148
	s_waitcnt lgkmcnt(0)
	v_mfma_f32_32x32x16_bf16 v[64:79], v[206:209], v[112:115], v[64:79]
	ds_read_b128 v[198:201], v185 offset:49152
	ds_read_b128 v[206:209], v185 offset:57344
	s_waitcnt lgkmcnt(1)
	v_mfma_f32_32x32x16_bf16 v[80:95], v[198:201], v[108:111], v[80:95]
	s_waitcnt lgkmcnt(0)
	v_mfma_f32_32x32x16_bf16 v[64:79], v[206:209], v[108:111], v[64:79]
	ds_read_b128 v[198:201], v183 offset:49152
	ds_read_b128 v[206:209], v183 offset:57344
	s_waitcnt lgkmcnt(1)
	v_mfma_f32_32x32x16_bf16 v[80:95], v[198:201], v[104:107], v[80:95]
	s_waitcnt lgkmcnt(0)
	v_mfma_f32_32x32x16_bf16 v[64:79], v[206:209], v[104:107], v[64:79]
	ds_read_b128 v[198:201], v181 offset:49152
	ds_read_b128 v[206:209], v181 offset:57344
	s_waitcnt lgkmcnt(1)
	v_mfma_f32_32x32x16_bf16 v[80:95], v[198:201], v[100:103], v[80:95]
	s_waitcnt lgkmcnt(0)
	v_mfma_f32_32x32x16_bf16 v[64:79], v[206:209], v[100:103], v[64:79]
	ds_read_b128 v[198:201], v179 offset:49152
	ds_read_b128 v[206:209], v179 offset:57344
	s_waitcnt lgkmcnt(1)
	v_mfma_f32_32x32x16_bf16 v[80:95], v[198:201], v[96:99], v[80:95]
	v_add_u32_e32 v199, s8, v186
	v_add_u32_e32 v198, s8, v188
	s_waitcnt lgkmcnt(0)
	v_mfma_f32_32x32x16_bf16 v[64:79], v[206:209], v[96:99], v[64:79]
	ds_read_b128 v[200:203], v199
	ds_read_b128 v[206:209], v199 offset:4096
	ds_read_b128 v[214:217], v177
	s_waitcnt lgkmcnt(0)
	v_mfma_f32_32x32x16_bf16 v[80:95], v[200:203], v[214:217], v[80:95]
	v_mfma_f32_32x32x16_bf16 v[64:79], v[206:209], v[214:217], v[64:79]
	ds_read_b128 v[200:203], v198
	ds_read_b128 v[206:209], v198 offset:4096
	ds_read_b128 v[214:217], v175
	s_waitcnt lgkmcnt(0)
	v_mfma_f32_32x32x16_bf16 v[80:95], v[200:203], v[214:217], v[80:95]
	v_add_u32_e32 v200, s8, v190
	v_add_u32_e32 v201, s8, v192
	v_add_f32_e32 v202, v135, v148
	v_mov_b32_e32 v203, v202
	s_nop 1
	v_permlane32_swap_b32_e32 v202, v203
	v_mfma_f32_32x32x16_bf16 v[64:79], v[206:209], v[214:217], v[64:79]
	ds_read_b128 v[206:209], v200
	ds_read_b128 v[214:217], v200 offset:4096
	ds_read_b128 v[218:221], v178
	s_waitcnt lgkmcnt(0)
	v_mfma_f32_32x32x16_bf16 v[80:95], v[206:209], v[218:221], v[80:95]
	v_mfma_f32_32x32x16_bf16 v[64:79], v[214:217], v[218:221], v[64:79]
	ds_read_b128 v[206:209], v201
	ds_read_b128 v[214:217], v201 offset:4096
	ds_read_b128 v[218:221], v176
	v_cvt_pk_bf16_f32 v148, v162, v205
	v_cvt_pk_bf16_f32 v149, v149, v163
	v_cvt_pk_bf16_f32 v150, v150, v161
	v_cvt_pk_bf16_f32 v151, v151, v160
	v_cvt_pk_bf16_f32 v152, v152, v155
	v_cvt_pk_bf16_f32 v153, v153, v154
	s_waitcnt lgkmcnt(0)
; #define SBAR() __builtin_amdgcn_sched_barrier(0)
; __device__ __forceinline__ void partialSM(f32x16& p0, f32x16& p1, float& m_reg, float& mn, float& alpha) {
;     constexpr float C = SCALE * 1.4426950408889634f;
;     float pmax = p0[0];
; #pragma unroll
;     for (int r = 1; r < 16; ++r) pmax = fmaxf(pmax, p0[r]);
; #pragma unroll
;     for (int r = 0; r < 16; ++r) pmax = fmaxf(pmax, p1[r]);
;     { auto rr = __builtin_amdgcn_permlane32_swap(__float_as_uint(pmax), __float_as_uint(pmax), false, false);
;       pmax = fmaxf(__uint_as_float(rr[0]), __uint_as_float(rr[1])); }
;     if (__builtin_expect(__all(pmax - m_reg <= THR / SCALE), 1)) { mn = m_reg; alpha = 1.f; }
;     else { mn = fmaxf(m_reg, pmax); alpha = __builtin_amdgcn_exp2f((m_reg - mn) * C); m_reg = mn; }
; template <int OFF> __device__ __forceinline__ s16x4 tr_read(int vb) {
;     s16x4 r; asm volatile("ds_read_b64_tr_b16 %0, %1 offset:%2" : "=&v"(r) : "v"(vb), "i"(OFF) : "memory"); return r;
; }
; template <int D0> __device__ __forceinline__ void pv_one(f32x16& od, int vb, bf16x8 pa0, bf16x8 pa1, bf16x8 pa2, bf16x8 pa3) {
;     const s16x4 l0 = tr_read<v_rd_off(D0, 0, 0)>(vb), h0 = tr_read<v_rd_off(D0, 0, 1)>(vb), l1 = tr_read<v_rd_off(D0, 1, 0)>(vb), h1 = tr_read<v_rd_off(D0, 1, 1)>(vb);
;     const s16x4 l2 = tr_read<v_rd_off(D0, 2, 0)>(vb), h2 = tr_read<v_rd_off(D0, 2, 1)>(vb), l3 = tr_read<v_rd_off(D0, 3, 0)>(vb), h3 = tr_read<v_rd_off(D0, 3, 1)>(vb);
;     asm volatile("s_waitcnt lgkmcnt(0)" ::: "memory"); SBAR();
;     ...
;     od = __builtin_amdgcn_mfma_f32_32x32x16_bf16(pa0, PK(l0, h0), od, 0, 0, 0);
;     od = __builtin_amdgcn_mfma_f32_32x32x16_bf16(pa1, PK(l1, h1), od, 0, 0, 0);
;     od = __builtin_amdgcn_mfma_f32_32x32x16_bf16(pa2, PK(l2, h2), od, 0, 0, 0);
;     od = __builtin_amdgcn_mfma_f32_32x32x16_bf16(pa3, PK(l3, h3), od, 0, 0, 0);
;     ...
; }
; __device__ __forceinline__ void pv_d0(f32x16* o, int vb, bf16x8 pa0, bf16x8 pa1, bf16x8 pa2, bf16x8 pa3) {
;     pv_one<0>(o[0], vb, pa0, pa1, pa2, pa3); pv_one<1>(o[1], vb, pa0, pa1, pa2, pa3); pv_one<2>(o[2], vb, pa0, pa1, pa2, pa3); pv_one<3>(o[3], vb, pa0, pa1, pa2, pa3);
; }
	v_mfma_f32_32x32x16_bf16 v[80:95], v[206:209], v[218:221], v[80:95]
	v_cvt_pk_bf16_f32 v154, v145, v147
	v_cvt_pk_bf16_f32 v155, v144, v146
	v_cvt_pk_bf16_f32 v204, v140, v141
	v_cvt_pk_bf16_f32 v205, v138, v139
	v_cvt_pk_bf16_f32 v206, v132, v133
	v_permlane32_swap_b32_e32 v148, v150
	v_mfma_f32_32x32x16_bf16 v[64:79], v[214:217], v[218:221], v[64:79]
	v_cvt_pk_bf16_f32 v207, v130, v131
	v_permlane32_swap_b32_e32 v204, v206
	v_cvt_pk_bf16_f32 v208, v128, v129
	v_cvt_pk_bf16_f32 v209, v142, v143
	v_cvt_pk_bf16_f32 v210, v136, v137
	v_cvt_pk_bf16_f32 v211, v134, v135
	v_permlane32_swap_b32_e32 v149, v151
	v_permlane32_swap_b32_e32 v152, v154
	v_permlane32_swap_b32_e32 v153, v155
	v_permlane32_swap_b32_e32 v205, v207
	v_permlane32_swap_b32_e32 v208, v210
	v_permlane32_swap_b32_e32 v209, v211
	s_add_i32 m0, s37, 0x4000
	s_nop 0
	global_load_lds_dwordx4 v242, s[44:45]
	s_add_i32 m0, s37, 0x6000
	v_add_u32_e32 v242, 0x40000, v242
	global_load_lds_dwordx4 v243, s[44:45]
	s_add_i32 m0, s37, 0x8000
	v_add_u32_e32 v243, 0x40000, v243
	global_load_lds_dwordx4 v244, s[44:45]
	s_add_i32 m0, s37, 0xa000
	v_add_u32_e32 v244, 0x40000, v244
	global_load_lds_dwordx4 v245, s[44:45]
	s_add_i32 m0, s37, 0x10000
	v_add_u32_e32 v245, 0x40000, v245
	global_load_lds_dwordx4 v246, s[44:45]
	v_add_u32_e32 v246, 0x2000, v246
	ds_read_b64_tr_b16 v[214:215], v247 offset:0
	ds_read_b64_tr_b16 v[216:217], v247 offset:0x800
	ds_read_b64_tr_b16 v[218:219], v247 offset:0x1000
	ds_read_b64_tr_b16 v[220:221], v247 offset:0x1800
	ds_read_b64_tr_b16 v[224:225], v247 offset:0x2000
	ds_read_b64_tr_b16 v[226:227], v247 offset:0x2800
	ds_read_b64_tr_b16 v[238:239], v247 offset:0x3000
	ds_read_b64_tr_b16 v[240:241], v247 offset:0x3800
	s_waitcnt lgkmcnt(0)
	s_nop 0
	v_mfma_f32_32x32x16_bf16 v[0:15], v[148:151], v[214:217], v[0:15]
	ds_read_b64_tr_b16 v[214:215], v247 offset:0x200
	ds_read_b64_tr_b16 v[216:217], v247 offset:0xa00
	v_mfma_f32_32x32x16_bf16 v[0:15], v[152:155], v[218:221], v[0:15]
	ds_read_b64_tr_b16 v[218:219], v247 offset:0x1200
	ds_read_b64_tr_b16 v[220:221], v247 offset:0x1a00
	v_mfma_f32_32x32x16_bf16 v[0:15], v[204:207], v[224:227], v[0:15]
	ds_read_b64_tr_b16 v[224:225], v247 offset:0x2200
	ds_read_b64_tr_b16 v[226:227], v247 offset:0x2a00
	v_mfma_f32_32x32x16_bf16 v[0:15], v[208:211], v[238:241], v[0:15]
	ds_read_b64_tr_b16 v[238:239], v247 offset:0x3200
	ds_read_b64_tr_b16 v[240:241], v247 offset:0x3a00
	s_waitcnt lgkmcnt(0)
	v_mfma_f32_32x32x16_bf16 v[48:63], v[148:151], v[214:217], v[48:63]
	ds_read_b64_tr_b16 v[214:215], v247 offset:0x400
	ds_read_b64_tr_b16 v[216:217], v247 offset:0xc00
	v_mfma_f32_32x32x16_bf16 v[48:63], v[152:155], v[218:221], v[48:63]
	ds_read_b64_tr_b16 v[218:219], v247 offset:0x1400
	ds_read_b64_tr_b16 v[220:221], v247 offset:0x1c00
	v_mfma_f32_32x32x16_bf16 v[48:63], v[204:207], v[224:227], v[48:63]
	ds_read_b64_tr_b16 v[224:225], v247 offset:0x2400
	ds_read_b64_tr_b16 v[226:227], v247 offset:0x2c00
	v_mfma_f32_32x32x16_bf16 v[48:63], v[208:211], v[238:241], v[48:63]
	ds_read_b64_tr_b16 v[238:239], v247 offset:0x3400
	ds_read_b64_tr_b16 v[240:241], v247 offset:0x3c00
	s_waitcnt lgkmcnt(0)
	v_mfma_f32_32x32x16_bf16 v[32:47], v[148:151], v[214:217], v[32:47]
	ds_read_b64_tr_b16 v[214:215], v247 offset:0x600
	ds_read_b64_tr_b16 v[216:217], v247 offset:0xe00
	v_mfma_f32_32x32x16_bf16 v[32:47], v[152:155], v[218:221], v[32:47]
	ds_read_b64_tr_b16 v[218:219], v247 offset:0x1600
	ds_read_b64_tr_b16 v[220:221], v247 offset:0x1e00
	v_mfma_f32_32x32x16_bf16 v[32:47], v[204:207], v[224:227], v[32:47]
	ds_read_b64_tr_b16 v[224:225], v247 offset:0x2600
	ds_read_b64_tr_b16 v[226:227], v247 offset:0x2e00
	v_mfma_f32_32x32x16_bf16 v[32:47], v[208:211], v[238:241], v[32:47]
	ds_read_b64_tr_b16 v[238:239], v247 offset:0x3600
	ds_read_b64_tr_b16 v[240:241], v247 offset:0x3e00
	s_waitcnt lgkmcnt(0)
	v_mfma_f32_32x32x16_bf16 v[16:31], v[148:151], v[214:217], v[16:31]
	v_max_f32_e32 v148, v81, v81
	v_max_f32_e32 v149, v80, v80
	v_max_f32_e32 v148, v149, v148
	v_max3_f32 v148, v148, v82, v83
	v_max3_f32 v148, v148, v84, v85
	v_max3_f32 v148, v148, v86, v87
	v_max3_f32 v148, v148, v88, v89
	v_max3_f32 v148, v148, v90, v91
	v_max3_f32 v148, v148, v92, v93
	v_mfma_f32_32x32x16_bf16 v[16:31], v[152:155], v[218:221], v[16:31]
	v_max3_f32 v148, v148, v94, v95
	v_max3_f32 v148, v148, v64, v65
	v_max3_f32 v148, v148, v66, v67
	v_max3_f32 v148, v148, v68, v69
	v_max3_f32 v148, v148, v70, v71
	v_max3_f32 v148, v148, v72, v73
	v_max3_f32 v148, v148, v74, v75
	v_max3_f32 v148, v148, v76, v77
	v_mfma_f32_32x32x16_bf16 v[16:31], v[204:207], v[224:227], v[16:31]
	v_max3_f32 v148, v148, v78, v79
	v_mov_b32_e32 v149, v148
	s_nop 1
	v_permlane32_swap_b32_e32 v148, v149
	v_max_f32_e32 v149, v149, v149
	v_max_f32_e32 v148, v148, v148
	v_max_f32_e32 v148, v148, v149
	v_sub_f32_e32 v149, v148, v197
	v_cmp_ge_f32_e32 vcc, s88, v149
	v_max_f32_e32 v149, v197, v197
	v_max_f32_e32 v148, v149, v148
	v_mfma_f32_32x32x16_bf16 v[16:31], v[208:211], v[238:241], v[16:31]
	v_sub_f32_e32 v149, v197, v148
	v_mul_f32_e32 v149, 0x3dd53b94, v149
	v_exp_f32_e32 v149, v149
	s_cmp_eq_u64 vcc, exec
	s_cselect_b64 s[8:9], -1, 0
	v_cndmask_b32_e64 v204, v149, 1.0, s[8:9]
	v_cmp_gt_f32_e32 vcc, 1.0, v204
	s_cbranch_vccz .Latt_u1_612
; #define SBAR() __builtin_amdgcn_sched_barrier(0)
; #define RESC(a) do { if (__any((a) < 1.f)) { if (hi == 0) al_l[r32] = (a); asm volatile("s_waitcnt lgkmcnt(0)" ::: "memory"); \
;     _Pragma("unroll") for (int d = 0; d < 4; ++d) _Pragma("unroll") for (int r = 0; r < 16; ++r) o[d][r] *= al_l[crow(r, hi)]; } } while (0)
; __device__ __forceinline__ void partialSM(f32x16& p0, f32x16& p1, float& m_reg, float& mn, float& alpha) {
;     constexpr float C = SCALE * 1.4426950408889634f;
;     float pmax = p0[0];
; #pragma unroll
;     for (int r = 1; r < 16; ++r) pmax = fmaxf(pmax, p0[r]);
; #pragma unroll
;     for (int r = 0; r < 16; ++r) pmax = fmaxf(pmax, p1[r]);
;     { auto rr = __builtin_amdgcn_permlane32_swap(__float_as_uint(pmax), __float_as_uint(pmax), false, false);
;       pmax = fmaxf(__uint_as_float(rr[0]), __uint_as_float(rr[1])); }
;     if (__builtin_expect(__all(pmax - m_reg <= THR / SCALE), 1)) { mn = m_reg; alpha = 1.f; }
;     else { mn = fmaxf(m_reg, pmax); alpha = __builtin_amdgcn_exp2f((m_reg - mn) * C); m_reg = mn; }
;     const float mnC = -mn * C;
; #pragma unroll
;     for (int r = 0; r < 16; ++r) p0[r] = fmaf(p0[r], C, mnC);
; #pragma unroll
;     for (int r = 0; r < 16; ++r) p1[r] = fmaf(p1[r], C, mnC);
; #pragma unroll
;     for (int r = 0; r < 16; ++r) p0[r] = __builtin_amdgcn_exp2f(p0[r]);
; }
; __device__ __forceinline__ void attn_body(const bf16_t* __restrict__ Qb, const bf16_t* __restrict__ Kh, const bf16_t* __restrict__ Vh, const bf16_t* __restrict__ Rh,
;                                           bf16_t* __restrict__ Zb, int seq, char* lds, int wv, bool nowrite) {
;     ...
;         RESC(alB); __syncthreads();
;         SBAR(); qkt(pA0, pA1, K_lds, R_lds, qr, Qp, r32, hi);
	s_and_saveexec_b64 s[10:11], s[6:7]
	ds_write_b32 v166, v204 offset:128
	s_or_b64 exec, exec, s[10:11]
	s_waitcnt lgkmcnt(0)
	v_add_u32_e32 v140, s1, v212
	ds_read_b128 v[128:131], v140 offset:224
	ds_read_b128 v[132:135], v140 offset:192
	ds_read_b128 v[136:139], v140 offset:160
	ds_read_b128 v[140:143], v140 offset:128
	s_waitcnt lgkmcnt(3)
	v_pk_mul_f32 v[12:13], v[12:13], v[128:129]
	s_waitcnt lgkmcnt(2)
	v_pk_mul_f32 v[8:9], v[8:9], v[132:133]
	s_waitcnt lgkmcnt(1)
	v_pk_mul_f32 v[4:5], v[4:5], v[136:137]
	v_pk_mul_f32 v[14:15], v[14:15], v[130:131]
	v_pk_mul_f32 v[10:11], v[10:11], v[134:135]
	v_pk_mul_f32 v[6:7], v[6:7], v[138:139]
	s_waitcnt lgkmcnt(0)
	v_pk_mul_f32 v[2:3], v[2:3], v[142:143]
	v_pk_mul_f32 v[0:1], v[0:1], v[140:141]
	v_pk_mul_f32 v[60:61], v[60:61], v[128:129]
	v_pk_mul_f32 v[56:57], v[56:57], v[132:133]
	v_pk_mul_f32 v[52:53], v[52:53], v[136:137]
	v_pk_mul_f32 v[62:63], v[62:63], v[130:131]
	v_pk_mul_f32 v[58:59], v[58:59], v[134:135]
	v_pk_mul_f32 v[54:55], v[54:55], v[138:139]
	v_pk_mul_f32 v[50:51], v[50:51], v[142:143]
	v_pk_mul_f32 v[48:49], v[48:49], v[140:141]
	v_pk_mul_f32 v[44:45], v[44:45], v[128:129]
	v_pk_mul_f32 v[40:41], v[40:41], v[132:133]
	v_pk_mul_f32 v[36:37], v[36:37], v[136:137]
	v_pk_mul_f32 v[46:47], v[46:47], v[130:131]
	v_pk_mul_f32 v[42:43], v[42:43], v[134:135]
	v_pk_mul_f32 v[38:39], v[38:39], v[138:139]
	v_pk_mul_f32 v[34:35], v[34:35], v[142:143]
	v_pk_mul_f32 v[32:33], v[32:33], v[140:141]
	v_pk_mul_f32 v[28:29], v[28:29], v[128:129]
	v_pk_mul_f32 v[24:25], v[24:25], v[132:133]
	v_pk_mul_f32 v[20:21], v[20:21], v[136:137]
	v_pk_mul_f32 v[30:31], v[30:31], v[130:131]
	v_pk_mul_f32 v[26:27], v[26:27], v[134:135]
	v_pk_mul_f32 v[22:23], v[22:23], v[138:139]
	v_pk_mul_f32 v[18:19], v[18:19], v[142:143]
	v_pk_mul_f32 v[16:17], v[16:17], v[140:141]
.Latt_u1_612:
	v_cndmask_b32_e64 v197, v148, v197, s[8:9]
	v_mul_f32_e32 v144, 0xbdd53b94, v197
	v_fmamk_f32 v80, v80, 0x3dd53b94, v144
	v_fmamk_f32 v81, v81, 0x3dd53b94, v144
	v_fmamk_f32 v82, v82, 0x3dd53b94, v144
	v_fmamk_f32 v83, v83, 0x3dd53b94, v144
	v_fmamk_f32 v84, v84, 0x3dd53b94, v144
	v_fmamk_f32 v85, v85, 0x3dd53b94, v144
	v_fmamk_f32 v86, v86, 0x3dd53b94, v144
	v_fmamk_f32 v87, v87, 0x3dd53b94, v144
	v_fmamk_f32 v88, v88, 0x3dd53b94, v144
	v_fmamk_f32 v89, v89, 0x3dd53b94, v144
	v_fmamk_f32 v90, v90, 0x3dd53b94, v144
	v_fmamk_f32 v91, v91, 0x3dd53b94, v144
	v_fmamk_f32 v92, v92, 0x3dd53b94, v144
	v_fmamk_f32 v93, v93, 0x3dd53b94, v144
	v_fmamk_f32 v94, v94, 0x3dd53b94, v144
	v_fmamk_f32 v95, v95, 0x3dd53b94, v144
	v_fmamk_f32 v206, v68, 0x3dd53b94, v144
	v_fmamk_f32 v148, v71, 0x3dd53b94, v144
	v_fmamk_f32 v149, v72, 0x3dd53b94, v144
	v_fmamk_f32 v207, v77, 0x3dd53b94, v144
	v_fmamk_f32 v153, v64, 0x3dd53b94, v144
	v_fmamk_f32 v154, v65, 0x3dd53b94, v144
	v_fmamk_f32 v155, v66, 0x3dd53b94, v144
	v_fmamk_f32 v205, v67, 0x3dd53b94, v144
	v_fmamk_f32 v146, v69, 0x3dd53b94, v144
	v_fmamk_f32 v147, v70, 0x3dd53b94, v144
	v_fmamk_f32 v150, v73, 0x3dd53b94, v144
	v_fmamk_f32 v151, v74, 0x3dd53b94, v144
	v_fmamk_f32 v152, v75, 0x3dd53b94, v144
	v_fmamk_f32 v145, v76, 0x3dd53b94, v144
	v_exp_f32_e32 v141, v80
	v_exp_f32_e32 v143, v81
	v_exp_f32_e32 v139, v82
	v_exp_f32_e32 v142, v83
	v_exp_f32_e32 v138, v84
	v_exp_f32_e32 v140, v85
	v_exp_f32_e32 v136, v86
	v_exp_f32_e32 v137, v87
	v_exp_f32_e32 v133, v88
	v_exp_f32_e32 v135, v89
	v_exp_f32_e32 v132, v90
	v_exp_f32_e32 v134, v91
	v_exp_f32_e32 v129, v92
	v_exp_f32_e32 v131, v93
	v_exp_f32_e32 v128, v94
	v_exp_f32_e32 v130, v95
	v_fmamk_f32 v208, v78, 0x3dd53b94, v144
	v_fmac_f32_e32 v144, 0x3dd53b94, v79
	s_waitcnt vmcnt(0)
	s_waitcnt lgkmcnt(0)
	s_barrier
	ds_read_b128 v[64:67], v174 offset:32768
	ds_read_b128 v[68:71], v174 offset:40960
	ds_read_b128 v[214:217], v180 offset:32768
	ds_read_b128 v[218:221], v180 offset:40960
	v_exp_f32_e32 v209, v153
	v_exp_f32_e32 v210, v154
	s_waitcnt lgkmcnt(3)
	v_mfma_f32_32x32x16_bf16 v[80:95], v[64:67], v[120:123], 0
	v_exp_f32_e32 v211, v155
	v_exp_f32_e32 v205, v205
	v_exp_f32_e32 v146, v146
	v_exp_f32_e32 v147, v147
	v_exp_f32_e32 v145, v145
	v_exp_f32_e32 v144, v144
	s_waitcnt lgkmcnt(2)
	v_mfma_f32_32x32x16_bf16 v[64:79], v[68:71], v[120:123], 0
	s_waitcnt lgkmcnt(1)
	v_mfma_f32_32x32x16_bf16 v[80:95], v[214:217], v[124:127], v[80:95]
	s_waitcnt lgkmcnt(0)
	v_mfma_f32_32x32x16_bf16 v[64:79], v[218:221], v[124:127], v[64:79]
	ds_read_b128 v[214:217], v182 offset:32768
	ds_read_b128 v[218:221], v182 offset:40960
	s_waitcnt lgkmcnt(1)
	v_mfma_f32_32x32x16_bf16 v[80:95], v[214:217], v[116:119], v[80:95]
	s_waitcnt lgkmcnt(0)
	v_mfma_f32_32x32x16_bf16 v[64:79], v[218:221], v[116:119], v[64:79]
	ds_read_b128 v[214:217], v184 offset:32768
	ds_read_b128 v[218:221], v184 offset:40960
	s_waitcnt lgkmcnt(1)
	v_mfma_f32_32x32x16_bf16 v[80:95], v[214:217], v[112:115], v[80:95]
	s_waitcnt lgkmcnt(0)
	v_mfma_f32_32x32x16_bf16 v[64:79], v[218:221], v[112:115], v[64:79]
	ds_read_b128 v[214:217], v185 offset:32768
	ds_read_b128 v[218:221], v185 offset:40960
	s_waitcnt lgkmcnt(1)
	v_mfma_f32_32x32x16_bf16 v[80:95], v[214:217], v[108:111], v[80:95]
	s_waitcnt lgkmcnt(0)
	v_mfma_f32_32x32x16_bf16 v[64:79], v[218:221], v[108:111], v[64:79]
	ds_read_b128 v[214:217], v183 offset:32768
	ds_read_b128 v[218:221], v183 offset:40960
	s_waitcnt lgkmcnt(1)
	v_mfma_f32_32x32x16_bf16 v[80:95], v[214:217], v[104:107], v[80:95]
	s_waitcnt lgkmcnt(0)
	v_mfma_f32_32x32x16_bf16 v[64:79], v[218:221], v[104:107], v[64:79]
	ds_read_b128 v[214:217], v181 offset:32768
	ds_read_b128 v[218:221], v181 offset:40960
	s_waitcnt lgkmcnt(1)
	v_mfma_f32_32x32x16_bf16 v[80:95], v[214:217], v[100:103], v[80:95]
	s_waitcnt lgkmcnt(0)
; __device__ __forceinline__ void finishSM(f32x16& p0, f32x16& p1, float alpha, float& l_reg, bf16x8& pa0, bf16x8& pa1, bf16x8& pa2, bf16x8& pa3) {
; #pragma unroll
;     for (int r = 0; r < 16; ++r) p1[r] = __builtin_amdgcn_exp2f(p1[r]);
;     float ps = 0;
; #pragma unroll
;     for (int r = 0; r < 16; ++r) ps += p0[r];
; #pragma unroll
;     for (int r = 0; r < 16; ++r) ps += p1[r];
;     { auto rr = __builtin_amdgcn_permlane32_swap(__float_as_uint(ps), __float_as_uint(ps), false, false);
;       ps = __uint_as_float(rr[0]) + __uint_as_float(rr[1]); }
;     l_reg = l_reg * alpha + ps;
;     ...
;     PK4(p0, 0, pa0); PK4(p0, 8, pa1); PK4(p1, 0, pa2); PK4(p1, 8, pa3);
;     ...
; }
; __device__ __forceinline__ void qkt(f32x16& p0, f32x16& p1, const char* Ks, const char* Rs, const bf16x8* qr, const char* Qp, int r32, int hi) {
;     p0 = f32x16{}; p1 = f32x16{};
; #pragma unroll
;     for (int d0 = 0; d0 < 8; ++d0) { const int cb = (d0 * 16 + hi * 8) * 2;
;         const bf16x8 b0 = *reinterpret_cast<const bf16x8*>(Ks + KSWZ(r32, cb));
;         const bf16x8 b1 = *reinterpret_cast<const bf16x8*>(Ks + KSWZ(32 + r32, cb));
;         p0 = __builtin_amdgcn_mfma_f32_32x32x16_bf16(b0, qr[d0], p0, 0, 0, 0);
;         p1 = __builtin_amdgcn_mfma_f32_32x32x16_bf16(b1, qr[d0], p1, 0, 0, 0); }
; #pragma unroll
;     for (int d0 = 0; d0 < 4; ++d0) { const int cb = (d0 * 16 + hi * 8) * 2;
;         const bf16x8 b0 = *reinterpret_cast<const bf16x8*>(Rs + RSWZ(r32, cb));
;         const bf16x8 b1 = *reinterpret_cast<const bf16x8*>(Rs + RSWZ(32 + r32, cb));
;         const bf16x8 qq = *reinterpret_cast<const bf16x8*>(Qp + RSWZ(r32, cb));
;         p0 = __builtin_amdgcn_mfma_f32_32x32x16_bf16(b0, qq, p0, 0, 0, 0);
;         p1 = __builtin_amdgcn_mfma_f32_32x32x16_bf16(b1, qq, p1, 0, 0, 0); }
; }
; __device__ __forceinline__ int v_st(int k, int c) { const int kk = (k & ~0xC) | ((k & 4) << 1) | ((k & 8) >> 1); return ((kk >> 3) * 4 + (c >> 5)) * 512 + ((kk & 7) * 32 + (c & 31)) * 2; }
; __device__ __forceinline__ int v_rd_base(int lane) { return ((lane & 3) << 3) | (((lane >> 2) & 3) << 6) | (((lane >> 4) & 1) << 5) | (((lane >> 5) & 1) << 8); }
; template <int OFF> __device__ __forceinline__ s16x4 tr_read(int vb) {
;     s16x4 r; asm volatile("ds_read_b64_tr_b16 %0, %1 offset:%2" : "=&v"(r) : "v"(vb), "i"(OFF) : "memory"); return r;
; }
	v_mfma_f32_32x32x16_bf16 v[64:79], v[218:221], v[100:103], v[64:79]
	ds_read_b128 v[214:217], v179 offset:32768
	ds_read_b128 v[218:221], v179 offset:40960
	s_waitcnt lgkmcnt(1)
	v_mfma_f32_32x32x16_bf16 v[80:95], v[214:217], v[96:99], v[80:95]
	s_waitcnt lgkmcnt(0)
	v_mfma_f32_32x32x16_bf16 v[64:79], v[218:221], v[96:99], v[64:79]
	ds_read_b128 v[214:217], v187
	ds_read_b128 v[218:221], v187 offset:4096
	ds_read_b128 v[224:227], v177
	s_waitcnt lgkmcnt(0)
	v_mfma_f32_32x32x16_bf16 v[80:95], v[214:217], v[224:227], v[80:95]
	v_mfma_f32_32x32x16_bf16 v[64:79], v[218:221], v[224:227], v[64:79]
	ds_read_b128 v[214:217], v189
	ds_read_b128 v[218:221], v189 offset:4096
	ds_read_b128 v[224:227], v175
	s_waitcnt lgkmcnt(0)
	v_mfma_f32_32x32x16_bf16 v[80:95], v[214:217], v[224:227], v[80:95]
	v_mfma_f32_32x32x16_bf16 v[64:79], v[218:221], v[224:227], v[64:79]
	ds_read_b128 v[214:217], v191
	ds_read_b128 v[218:221], v191 offset:4096
	ds_read_b128 v[224:227], v178
	s_waitcnt lgkmcnt(0)
	v_mfma_f32_32x32x16_bf16 v[80:95], v[214:217], v[224:227], v[80:95]
	v_mfma_f32_32x32x16_bf16 v[64:79], v[218:221], v[224:227], v[64:79]
	ds_read_b128 v[214:217], v193
	ds_read_b128 v[218:221], v193 offset:4096
	ds_read_b128 v[224:227], v176
	s_waitcnt lgkmcnt(0)
	v_mfma_f32_32x32x16_bf16 v[80:95], v[214:217], v[224:227], v[80:95]
	v_exp_f32_e32 v215, v148
	v_add_f32_e32 v148, 0, v141
	v_add_f32_e32 v148, v143, v148
	v_add_f32_e32 v148, v139, v148
	v_add_f32_e32 v148, v142, v148
	v_add_f32_e32 v148, v138, v148
	v_add_f32_e32 v148, v140, v148
	v_add_f32_e32 v148, v136, v148
	v_add_f32_e32 v148, v137, v148
	v_add_f32_e32 v148, v133, v148
	v_add_f32_e32 v148, v135, v148
	v_add_f32_e32 v148, v132, v148
	v_add_f32_e32 v148, v134, v148
	v_add_f32_e32 v148, v129, v148
	v_add_f32_e32 v148, v131, v148
	v_add_f32_e32 v148, v128, v148
	v_add_f32_e32 v148, v130, v148
	v_exp_f32_e32 v214, v206
	v_add_f32_e32 v148, v209, v148
	v_add_f32_e32 v148, v210, v148
	v_add_f32_e32 v148, v211, v148
	v_add_f32_e32 v148, v205, v148
	v_exp_f32_e32 v216, v149
	v_add_f32_e32 v148, v214, v148
	v_exp_f32_e32 v217, v150
	v_add_f32_e32 v148, v146, v148
	v_mfma_f32_32x32x16_bf16 v[64:79], v[218:221], v[224:227], v[64:79]
	v_exp_f32_e32 v218, v151
	v_add_f32_e32 v148, v147, v148
	v_exp_f32_e32 v219, v152
	v_add_f32_e32 v148, v215, v148
	v_add_f32_e32 v148, v216, v148
	v_exp_f32_e32 v220, v207
	v_add_f32_e32 v148, v217, v148
	v_exp_f32_e32 v221, v208
	v_add_f32_e32 v148, v218, v148
	v_add_f32_e32 v148, v219, v148
	v_add_f32_e32 v148, v145, v148
	v_add_f32_e32 v148, v220, v148
	v_add_f32_e32 v148, v221, v148
	v_add_f32_e32 v206, v144, v148
	v_mov_b32_e32 v207, v206
	v_cvt_pk_bf16_f32 v148, v141, v143
	v_cvt_pk_bf16_f32 v149, v139, v142
	v_cvt_pk_bf16_f32 v150, v138, v140
	v_cvt_pk_bf16_f32 v151, v136, v137
	s_nop 1
	v_permlane32_swap_b32_e32 v206, v207
	v_permlane32_swap_b32_e32 v148, v150
	v_permlane32_swap_b32_e32 v149, v151
	v_cvt_pk_bf16_f32 v152, v133, v135
	v_cvt_pk_bf16_f32 v153, v132, v134
	v_cvt_pk_bf16_f32 v154, v129, v131
	v_cvt_pk_bf16_f32 v155, v128, v130
	v_cvt_pk_bf16_f32 v208, v209, v210
	v_cvt_pk_bf16_f32 v209, v211, v205
	v_cvt_pk_bf16_f32 v210, v214, v146
	v_cvt_pk_bf16_f32 v211, v147, v215
	v_cvt_pk_bf16_f32 v214, v216, v217
	v_cvt_pk_bf16_f32 v215, v218, v219
	v_cvt_pk_bf16_f32 v216, v145, v220
	v_cvt_pk_bf16_f32 v217, v221, v144
	s_nop 0
	v_permlane32_swap_b32_e32 v152, v154
	v_permlane32_swap_b32_e32 v153, v155
	v_permlane32_swap_b32_e32 v208, v210
	v_permlane32_swap_b32_e32 v209, v211
	v_permlane32_swap_b32_e32 v214, v216
	v_permlane32_swap_b32_e32 v215, v217
	s_add_i32 m0, s37, 0x1c800
	s_nop 0
	global_load_lds_dwordx4 v242, s[44:45]
	s_add_i32 m0, s37, 0x1e800
	v_add_u32_e32 v242, 0x40000, v242
	global_load_lds_dwordx4 v243, s[44:45]
	s_add_i32 m0, s37, 0xc000
	v_add_u32_e32 v243, 0x40000, v243
	global_load_lds_dwordx4 v244, s[44:45]
	s_add_i32 m0, s37, 0xe000
	v_add_u32_e32 v244, 0x40000, v244
	global_load_lds_dwordx4 v245, s[44:45]
	s_add_i32 m0, s37, 0x12000
	v_add_u32_e32 v245, 0x40000, v245
	global_load_lds_dwordx4 v246, s[44:45]
	v_add_u32_e32 v246, 0x2000, v246
	ds_read_b64_tr_b16 v[160:161], v169 offset:0
	ds_read_b64_tr_b16 v[162:163], v169 offset:0x800
	ds_read_b64_tr_b16 v[218:219], v169 offset:0x1000
	ds_read_b64_tr_b16 v[220:221], v169 offset:0x1800
	ds_read_b64_tr_b16 v[224:225], v169 offset:0x2000
	ds_read_b64_tr_b16 v[226:227], v169 offset:0x2800
	ds_read_b64_tr_b16 v[238:239], v169 offset:0x3000
	ds_read_b64_tr_b16 v[240:241], v169 offset:0x3800
	s_waitcnt lgkmcnt(0)
	s_nop 0
	v_mfma_f32_32x32x16_bf16 v[0:15], v[148:151], v[160:163], v[0:15]
	ds_read_b64_tr_b16 v[160:161], v169 offset:0x200
	ds_read_b64_tr_b16 v[162:163], v169 offset:0xa00
	v_mfma_f32_32x32x16_bf16 v[0:15], v[152:155], v[218:221], v[0:15]
	ds_read_b64_tr_b16 v[218:219], v169 offset:0x1200
	ds_read_b64_tr_b16 v[220:221], v169 offset:0x1a00
	v_mfma_f32_32x32x16_bf16 v[0:15], v[208:211], v[224:227], v[0:15]
	ds_read_b64_tr_b16 v[224:225], v169 offset:0x2200
	ds_read_b64_tr_b16 v[226:227], v169 offset:0x2a00
	v_mfma_f32_32x32x16_bf16 v[0:15], v[214:217], v[238:241], v[0:15]
	ds_read_b64_tr_b16 v[238:239], v169 offset:0x3200
	ds_read_b64_tr_b16 v[240:241], v169 offset:0x3a00
	s_waitcnt lgkmcnt(0)
	v_mfma_f32_32x32x16_bf16 v[48:63], v[148:151], v[160:163], v[48:63]
	ds_read_b64_tr_b16 v[160:161], v169 offset:0x400
	ds_read_b64_tr_b16 v[162:163], v169 offset:0xc00
	v_mfma_f32_32x32x16_bf16 v[48:63], v[152:155], v[218:221], v[48:63]
	ds_read_b64_tr_b16 v[218:219], v169 offset:0x1400
	ds_read_b64_tr_b16 v[220:221], v169 offset:0x1c00
	v_mfma_f32_32x32x16_bf16 v[48:63], v[208:211], v[224:227], v[48:63]
	ds_read_b64_tr_b16 v[224:225], v169 offset:0x2400
	ds_read_b64_tr_b16 v[226:227], v169 offset:0x2c00
	v_mfma_f32_32x32x16_bf16 v[48:63], v[214:217], v[238:241], v[48:63]
	ds_read_b64_tr_b16 v[238:239], v169 offset:0x3400
	ds_read_b64_tr_b16 v[240:241], v169 offset:0x3c00
	s_waitcnt lgkmcnt(0)
; #define SWRITE(b) do { *(bf16x8*)(V_lds + (b) * SHM_V + vst0) = vs0; *(bf16x8*)(V_lds + (b) * SHM_V + vst1) = vs1; const int kc = sc * 2; \
;     *(bf16x8*)(K_lds + (b) * SHM_K + KSWZ(sr, kc)) = ks0; *(bf16x8*)(K_lds + (b) * SHM_K + KSWZ(32 + sr, kc)) = ks1; \
;     *(bf16x8*)(R_lds + (b) * SHM_R + RSWZ(rr, rc * 2)) = rs0; } while (0)
; #define SWAIT() asm volatile("s_waitcnt vmcnt(0)" ::: "memory")
; #define RESC(a) do { if (__any((a) < 1.f)) { if (hi == 0) al_l[r32] = (a); asm volatile("s_waitcnt lgkmcnt(0)" ::: "memory"); \
;     _Pragma("unroll") for (int d = 0; d < 4; ++d) _Pragma("unroll") for (int r = 0; r < 16; ++r) o[d][r] *= al_l[crow(r, hi)]; } } while (0)
; __device__ __forceinline__ void partialSM(f32x16& p0, f32x16& p1, float& m_reg, float& mn, float& alpha) {
;     constexpr float C = SCALE * 1.4426950408889634f;
;     float pmax = p0[0];
; #pragma unroll
;     for (int r = 1; r < 16; ++r) pmax = fmaxf(pmax, p0[r]);
; #pragma unroll
;     for (int r = 0; r < 16; ++r) pmax = fmaxf(pmax, p1[r]);
;     { auto rr = __builtin_amdgcn_permlane32_swap(__float_as_uint(pmax), __float_as_uint(pmax), false, false);
;       pmax = fmaxf(__uint_as_float(rr[0]), __uint_as_float(rr[1])); }
;     if (__builtin_expect(__all(pmax - m_reg <= THR / SCALE), 1)) { mn = m_reg; alpha = 1.f; }
;     else { mn = fmaxf(m_reg, pmax); alpha = __builtin_amdgcn_exp2f((m_reg - mn) * C); m_reg = mn; }
;     const float mnC = -mn * C;
; #pragma unroll
;     for (int r = 0; r < 16; ++r) p0[r] = fmaf(p0[r], C, mnC);
; #pragma unroll
;     for (int r = 0; r < 16; ++r) p1[r] = fmaf(p1[r], C, mnC);
; #pragma unroll
;     for (int r = 0; r < 16; ++r) p0[r] = __builtin_amdgcn_exp2f(p0[r]);
; }
; __device__ __forceinline__ void attn_body(const bf16_t* __restrict__ Qb, const bf16_t* __restrict__ Kh, const bf16_t* __restrict__ Vh, const bf16_t* __restrict__ Rh,
;                                           bf16_t* __restrict__ Zb, int seq, char* lds, int wv, bool nowrite) {
;     ...
;         pv_d0(o, vb0 + SHM_V, pa0, pa1, pa2, pa3); partialSM(pA0, pA1, m_reg, mnA, alA);
;         __syncthreads(); SWAIT(); SWRITE(1);
;         RESC(alA); __syncthreads();
	v_mfma_f32_32x32x16_bf16 v[32:47], v[148:151], v[160:163], v[32:47]
	ds_read_b64_tr_b16 v[160:161], v169 offset:0x600
	ds_read_b64_tr_b16 v[162:163], v169 offset:0xe00
	v_mfma_f32_32x32x16_bf16 v[32:47], v[152:155], v[218:221], v[32:47]
	ds_read_b64_tr_b16 v[218:219], v169 offset:0x1600
	ds_read_b64_tr_b16 v[220:221], v169 offset:0x1e00
	v_mfma_f32_32x32x16_bf16 v[32:47], v[208:211], v[224:227], v[32:47]
	ds_read_b64_tr_b16 v[224:225], v169 offset:0x2600
	ds_read_b64_tr_b16 v[226:227], v169 offset:0x2e00
	v_mfma_f32_32x32x16_bf16 v[32:47], v[214:217], v[238:241], v[32:47]
	ds_read_b64_tr_b16 v[238:239], v169 offset:0x3600
	ds_read_b64_tr_b16 v[240:241], v169 offset:0x3e00
	s_waitcnt lgkmcnt(0)
	v_mfma_f32_32x32x16_bf16 v[16:31], v[148:151], v[160:163], v[16:31]
	v_max_f32_e32 v148, v81, v81
	v_max_f32_e32 v149, v80, v80
	v_max_f32_e32 v148, v149, v148
	v_max3_f32 v148, v148, v82, v83
	v_max3_f32 v148, v148, v84, v85
	v_max3_f32 v148, v148, v86, v87
	v_max3_f32 v148, v148, v88, v89
	v_max3_f32 v148, v148, v90, v91
	v_max3_f32 v148, v148, v92, v93
	v_mfma_f32_32x32x16_bf16 v[16:31], v[152:155], v[218:221], v[16:31]
	v_max3_f32 v148, v148, v94, v95
	v_max3_f32 v148, v148, v64, v65
	v_max3_f32 v148, v148, v66, v67
	v_max3_f32 v148, v148, v68, v69
	v_max3_f32 v148, v148, v70, v71
	v_max3_f32 v148, v148, v72, v73
	v_max3_f32 v148, v148, v74, v75
	v_max3_f32 v148, v148, v76, v77
	v_mfma_f32_32x32x16_bf16 v[16:31], v[208:211], v[224:227], v[16:31]
	v_max3_f32 v148, v148, v78, v79
	v_mov_b32_e32 v149, v148
	s_nop 1
	v_permlane32_swap_b32_e32 v148, v149
	v_max_f32_e32 v149, v149, v149
	v_max_f32_e32 v148, v148, v148
	v_max_f32_e32 v148, v148, v149
	v_sub_f32_e32 v149, v148, v197
	v_cmp_ge_f32_e32 vcc, s88, v149
	v_max_f32_e32 v149, v197, v197
	v_max_f32_e32 v149, v149, v148
	v_mfma_f32_32x32x16_bf16 v[16:31], v[214:217], v[238:241], v[16:31]
	v_sub_f32_e32 v148, v197, v149
	v_mul_f32_e32 v148, 0x3dd53b94, v148
	v_exp_f32_e32 v148, v148
	s_cmp_eq_u64 vcc, exec
	s_cselect_b64 s[8:9], -1, 0
	v_cndmask_b32_e64 v148, v148, 1.0, s[8:9]
	v_cmp_gt_f32_e32 vcc, 1.0, v148
	s_cbranch_vccz .Latt_u1_616
	s_and_saveexec_b64 s[10:11], s[6:7]
	ds_write_b32 v166, v148 offset:128
	s_or_b64 exec, exec, s[10:11]
	s_waitcnt lgkmcnt(0)
	v_add_u32_e32 v140, s1, v212
	ds_read_b128 v[128:131], v140 offset:224
	ds_read_b128 v[132:135], v140 offset:192
	ds_read_b128 v[136:139], v140 offset:160
	ds_read_b128 v[140:143], v140 offset:128
	s_waitcnt lgkmcnt(3)
	v_pk_mul_f32 v[12:13], v[12:13], v[128:129]
	s_waitcnt lgkmcnt(2)
	v_pk_mul_f32 v[8:9], v[8:9], v[132:133]
	s_waitcnt lgkmcnt(1)
	v_pk_mul_f32 v[4:5], v[4:5], v[136:137]
	v_pk_mul_f32 v[14:15], v[14:15], v[130:131]
	v_pk_mul_f32 v[10:11], v[10:11], v[134:135]
	v_pk_mul_f32 v[6:7], v[6:7], v[138:139]
	s_waitcnt lgkmcnt(0)
	v_pk_mul_f32 v[2:3], v[2:3], v[142:143]
	v_pk_mul_f32 v[0:1], v[0:1], v[140:141]
	v_pk_mul_f32 v[60:61], v[60:61], v[128:129]
	v_pk_mul_f32 v[56:57], v[56:57], v[132:133]
	v_pk_mul_f32 v[52:53], v[52:53], v[136:137]
	v_pk_mul_f32 v[62:63], v[62:63], v[130:131]
	v_pk_mul_f32 v[58:59], v[58:59], v[134:135]
	v_pk_mul_f32 v[54:55], v[54:55], v[138:139]
	v_pk_mul_f32 v[50:51], v[50:51], v[142:143]
	v_pk_mul_f32 v[48:49], v[48:49], v[140:141]
	v_pk_mul_f32 v[44:45], v[44:45], v[128:129]
	v_pk_mul_f32 v[40:41], v[40:41], v[132:133]
	v_pk_mul_f32 v[36:37], v[36:37], v[136:137]
	v_pk_mul_f32 v[46:47], v[46:47], v[130:131]
	v_pk_mul_f32 v[42:43], v[42:43], v[134:135]
	v_pk_mul_f32 v[38:39], v[38:39], v[138:139]
	v_pk_mul_f32 v[34:35], v[34:35], v[142:143]
	v_pk_mul_f32 v[32:33], v[32:33], v[140:141]
	v_pk_mul_f32 v[28:29], v[28:29], v[128:129]
	v_pk_mul_f32 v[24:25], v[24:25], v[132:133]
	v_pk_mul_f32 v[20:21], v[20:21], v[136:137]
	v_pk_mul_f32 v[30:31], v[30:31], v[130:131]
	v_pk_mul_f32 v[26:27], v[26:27], v[134:135]
	v_pk_mul_f32 v[22:23], v[22:23], v[138:139]
	v_pk_mul_f32 v[18:19], v[18:19], v[142:143]
	v_pk_mul_f32 v[16:17], v[16:17], v[140:141]
.Latt_u1_616:
	v_cndmask_b32_e64 v197, v149, v197, s[8:9]
	v_mul_f32_e32 v134, 0xbdd53b94, v197
	v_mov_b32_e32 v135, v134
	v_fmamk_f32 v80, v80, 0x3dd53b94, v134
	v_fmamk_f32 v81, v81, 0x3dd53b94, v134
	v_fmamk_f32 v82, v82, 0x3dd53b94, v134
	v_fmamk_f32 v83, v83, 0x3dd53b94, v134
	v_fmamk_f32 v84, v84, 0x3dd53b94, v134
	v_fmamk_f32 v85, v85, 0x3dd53b94, v134
	v_fmamk_f32 v86, v86, 0x3dd53b94, v134
	v_fmamk_f32 v87, v87, 0x3dd53b94, v134
	v_fmamk_f32 v88, v88, 0x3dd53b94, v134
	v_fmamk_f32 v89, v89, 0x3dd53b94, v134
	v_fmamk_f32 v90, v90, 0x3dd53b94, v134
	v_fmamk_f32 v91, v91, 0x3dd53b94, v134
	v_fmamk_f32 v92, v92, 0x3dd53b94, v134
	v_fmamk_f32 v93, v93, 0x3dd53b94, v134
	v_fmamk_f32 v94, v94, 0x3dd53b94, v134
	v_fmac_f32_e32 v135, 0x3dd53b94, v95
	v_exp_f32_e32 v162, v80
	v_exp_f32_e32 v205, v81
	v_exp_f32_e32 v149, v82
	v_exp_f32_e32 v163, v83
	v_exp_f32_e32 v150, v84
	v_exp_f32_e32 v161, v85
	v_exp_f32_e32 v151, v86
	v_exp_f32_e32 v160, v87
	v_exp_f32_e32 v152, v88
	v_exp_f32_e32 v155, v89
	v_exp_f32_e32 v153, v90
	v_exp_f32_e32 v154, v91
	v_exp_f32_e32 v145, v92
	v_exp_f32_e32 v147, v93
	v_exp_f32_e32 v144, v94
	v_exp_f32_e32 v146, v135
	v_pk_fma_f32 v[140:141], v[64:65], s[36:37], v[134:135] op_sel_hi:[1,0,0]
	v_add_f32_e32 v64, v202, v203
	v_fmac_f32_e32 v64, v194, v167
	v_add_f32_e32 v167, v206, v207
	s_add_i32 s3, s3, 2
	v_pk_fma_f32 v[138:139], v[66:67], s[36:37], v[134:135] op_sel_hi:[1,0,0]
	v_pk_fma_f32 v[132:133], v[68:69], s[36:37], v[134:135] op_sel_hi:[1,0,0]
	v_pk_fma_f32 v[130:131], v[70:71], s[36:37], v[134:135] op_sel_hi:[1,0,0]
	v_pk_fma_f32 v[128:129], v[72:73], s[36:37], v[134:135] op_sel_hi:[1,0,0]
	v_pk_fma_f32 v[142:143], v[74:75], s[36:37], v[134:135] op_sel_hi:[1,0,0]
	v_pk_fma_f32 v[136:137], v[76:77], s[36:37], v[134:135] op_sel_hi:[1,0,0]
	v_pk_fma_f32 v[134:135], v[78:79], s[36:37], v[134:135] op_sel_hi:[1,0,0]
	v_fmac_f32_e32 v167, v64, v204
	s_cmp_gt_u32 s3, 28
	s_waitcnt vmcnt(0)
	s_waitcnt lgkmcnt(0)
	s_barrier
; __device__ __forceinline__ void finishSM(f32x16& p0, f32x16& p1, float alpha, float& l_reg, bf16x8& pa0, bf16x8& pa1, bf16x8& pa2, bf16x8& pa3) {
; #pragma unroll
;     for (int r = 0; r < 16; ++r) p1[r] = __builtin_amdgcn_exp2f(p1[r]);
;     float ps = 0;
; #pragma unroll
;     for (int r = 0; r < 16; ++r) ps += p0[r];
; #pragma unroll
;     for (int r = 0; r < 16; ++r) ps += p1[r];
;     { auto rr = __builtin_amdgcn_permlane32_swap(__float_as_uint(ps), __float_as_uint(ps), false, false);
;       ps = __uint_as_float(rr[0]) + __uint_as_float(rr[1]); }
;     l_reg = l_reg * alpha + ps;
;     ...
;     PK4(p0, 0, pa0); PK4(p0, 8, pa1); PK4(p1, 0, pa2); PK4(p1, 8, pa3);
;     ...
; }
; __device__ __forceinline__ void qkt(f32x16& p0, f32x16& p1, const char* Ks, const char* Rs, const bf16x8* qr, const char* Qp, int r32, int hi) {
;     p0 = f32x16{}; p1 = f32x16{};
; #pragma unroll
;     for (int d0 = 0; d0 < 8; ++d0) { const int cb = (d0 * 16 + hi * 8) * 2;
;         const bf16x8 b0 = *reinterpret_cast<const bf16x8*>(Ks + KSWZ(r32, cb));
;         const bf16x8 b1 = *reinterpret_cast<const bf16x8*>(Ks + KSWZ(32 + r32, cb));
;         p0 = __builtin_amdgcn_mfma_f32_32x32x16_bf16(b0, qr[d0], p0, 0, 0, 0);
;         p1 = __builtin_amdgcn_mfma_f32_32x32x16_bf16(b1, qr[d0], p1, 0, 0, 0); }
; #pragma unroll
;     for (int d0 = 0; d0 < 4; ++d0) { const int cb = (d0 * 16 + hi * 8) * 2;
;         const bf16x8 b0 = *reinterpret_cast<const bf16x8*>(Rs + RSWZ(r32, cb));
;         const bf16x8 b1 = *reinterpret_cast<const bf16x8*>(Rs + RSWZ(32 + r32, cb));
;         const bf16x8 qq = *reinterpret_cast<const bf16x8*>(Qp + RSWZ(r32, cb));
;         p0 = __builtin_amdgcn_mfma_f32_32x32x16_bf16(b0, qq, p0, 0, 0, 0);
;         p1 = __builtin_amdgcn_mfma_f32_32x32x16_bf16(b1, qq, p1, 0, 0, 0); }
; }
	s_cbranch_scc1 .LBB0_618
	v_mov_b32_e32 v194, v148
	ds_read_b128 v[64:67], v174 offset:49152
	ds_read_b128 v[68:71], v174 offset:57344
	ds_read_b128 v[198:201], v180 offset:49152
	ds_read_b128 v[206:209], v180 offset:57344
	s_add_i32 s8, 0, 0x12000
	v_add_f32_e32 v148, 0, v162
	s_waitcnt lgkmcnt(3)
	v_mfma_f32_32x32x16_bf16 v[80:95], v[64:67], v[120:123], 0
	v_add_f32_e32 v148, v205, v148
	v_add_f32_e32 v148, v149, v148
	v_add_f32_e32 v148, v163, v148
	v_add_f32_e32 v148, v150, v148
	v_add_f32_e32 v148, v161, v148
	v_add_f32_e32 v148, v151, v148
	v_add_f32_e32 v148, v160, v148
	s_waitcnt lgkmcnt(2)
	v_mfma_f32_32x32x16_bf16 v[64:79], v[68:71], v[120:123], 0
	v_add_f32_e32 v148, v152, v148
	v_add_f32_e32 v148, v155, v148
	v_add_f32_e32 v148, v153, v148
	v_add_f32_e32 v148, v154, v148
	v_exp_f32_e32 v140, v140
	v_add_f32_e32 v148, v145, v148
	v_exp_f32_e32 v141, v141
	s_waitcnt lgkmcnt(1)
	v_mfma_f32_32x32x16_bf16 v[80:95], v[198:201], v[124:127], v[80:95]
	v_add_f32_e32 v148, v147, v148
	v_exp_f32_e32 v138, v138
	v_add_f32_e32 v148, v144, v148
	v_exp_f32_e32 v139, v139
	v_add_f32_e32 v148, v146, v148
	v_exp_f32_e32 v132, v132
	v_add_f32_e32 v148, v140, v148
	s_waitcnt lgkmcnt(0)
	v_mfma_f32_32x32x16_bf16 v[64:79], v[206:209], v[124:127], v[64:79]
	ds_read_b128 v[198:201], v182 offset:49152
	ds_read_b128 v[206:209], v182 offset:57344
	v_exp_f32_e32 v133, v133
	v_add_f32_e32 v148, v141, v148
	v_exp_f32_e32 v130, v130
	v_add_f32_e32 v148, v138, v148
	v_exp_f32_e32 v131, v131
	v_add_f32_e32 v148, v139, v148
	s_waitcnt lgkmcnt(1)
	v_mfma_f32_32x32x16_bf16 v[80:95], v[198:201], v[116:119], v[80:95]
	v_exp_f32_e32 v128, v128
	v_add_f32_e32 v148, v132, v148
	v_exp_f32_e32 v129, v129
	v_add_f32_e32 v148, v133, v148
	v_exp_f32_e32 v142, v142
	v_add_f32_e32 v148, v130, v148
	v_exp_f32_e32 v143, v143
	s_waitcnt lgkmcnt(0)
	v_mfma_f32_32x32x16_bf16 v[64:79], v[206:209], v[116:119], v[64:79]
	ds_read_b128 v[198:201], v184 offset:49152
	ds_read_b128 v[206:209], v184 offset:57344
	v_add_f32_e32 v148, v131, v148
	v_exp_f32_e32 v136, v136
	v_add_f32_e32 v148, v128, v148
	v_exp_f32_e32 v137, v137
	v_add_f32_e32 v148, v129, v148
	v_exp_f32_e32 v134, v134
	s_waitcnt lgkmcnt(1)
	v_mfma_f32_32x32x16_bf16 v[80:95], v[198:201], v[112:115], v[80:95]
	v_add_f32_e32 v148, v142, v148
	v_exp_f32_e32 v135, v135
	v_add_f32_e32 v148, v143, v148
	v_add_f32_e32 v148, v136, v148
	v_add_f32_e32 v148, v137, v148
	v_add_f32_e32 v148, v134, v148
	s_waitcnt lgkmcnt(0)
	v_mfma_f32_32x32x16_bf16 v[64:79], v[206:209], v[112:115], v[64:79]
	ds_read_b128 v[198:201], v185 offset:49152
	ds_read_b128 v[206:209], v185 offset:57344
	s_waitcnt lgkmcnt(1)
	v_mfma_f32_32x32x16_bf16 v[80:95], v[198:201], v[108:111], v[80:95]
	s_waitcnt lgkmcnt(0)
	v_mfma_f32_32x32x16_bf16 v[64:79], v[206:209], v[108:111], v[64:79]
	ds_read_b128 v[198:201], v183 offset:49152
	ds_read_b128 v[206:209], v183 offset:57344
	s_waitcnt lgkmcnt(1)
	v_mfma_f32_32x32x16_bf16 v[80:95], v[198:201], v[104:107], v[80:95]
	s_waitcnt lgkmcnt(0)
	v_mfma_f32_32x32x16_bf16 v[64:79], v[206:209], v[104:107], v[64:79]
	ds_read_b128 v[198:201], v181 offset:49152
	ds_read_b128 v[206:209], v181 offset:57344
	s_waitcnt lgkmcnt(1)
	v_mfma_f32_32x32x16_bf16 v[80:95], v[198:201], v[100:103], v[80:95]
	s_waitcnt lgkmcnt(0)
	v_mfma_f32_32x32x16_bf16 v[64:79], v[206:209], v[100:103], v[64:79]
	ds_read_b128 v[198:201], v179 offset:49152
	ds_read_b128 v[206:209], v179 offset:57344
	s_waitcnt lgkmcnt(1)
	v_mfma_f32_32x32x16_bf16 v[80:95], v[198:201], v[96:99], v[80:95]
	v_add_u32_e32 v199, s8, v186
	v_add_u32_e32 v198, s8, v188
	s_waitcnt lgkmcnt(0)
	v_mfma_f32_32x32x16_bf16 v[64:79], v[206:209], v[96:99], v[64:79]
	ds_read_b128 v[200:203], v199
	ds_read_b128 v[206:209], v199 offset:4096
	ds_read_b128 v[214:217], v177
	s_waitcnt lgkmcnt(0)
	v_mfma_f32_32x32x16_bf16 v[80:95], v[200:203], v[214:217], v[80:95]
	v_mfma_f32_32x32x16_bf16 v[64:79], v[206:209], v[214:217], v[64:79]
	ds_read_b128 v[200:203], v198
	ds_read_b128 v[206:209], v198 offset:4096
	ds_read_b128 v[214:217], v175
	s_waitcnt lgkmcnt(0)
	v_mfma_f32_32x32x16_bf16 v[80:95], v[200:203], v[214:217], v[80:95]
	v_add_u32_e32 v200, s8, v190
	v_add_u32_e32 v201, s8, v192
	v_add_f32_e32 v202, v135, v148
	v_mov_b32_e32 v203, v202
	s_nop 1
	v_permlane32_swap_b32_e32 v202, v203
	v_mfma_f32_32x32x16_bf16 v[64:79], v[206:209], v[214:217], v[64:79]
	ds_read_b128 v[206:209], v200
	ds_read_b128 v[214:217], v200 offset:4096
	ds_read_b128 v[218:221], v178
	s_waitcnt lgkmcnt(0)
	v_mfma_f32_32x32x16_bf16 v[80:95], v[206:209], v[218:221], v[80:95]
	v_mfma_f32_32x32x16_bf16 v[64:79], v[214:217], v[218:221], v[64:79]
	ds_read_b128 v[206:209], v201
	ds_read_b128 v[214:217], v201 offset:4096
	ds_read_b128 v[218:221], v176
	v_cvt_pk_bf16_f32 v148, v162, v205
	v_cvt_pk_bf16_f32 v149, v149, v163
	v_cvt_pk_bf16_f32 v150, v150, v161
	v_cvt_pk_bf16_f32 v151, v151, v160
	v_cvt_pk_bf16_f32 v152, v152, v155
	v_cvt_pk_bf16_f32 v153, v153, v154
	s_waitcnt lgkmcnt(0)
; #define SBAR() __builtin_amdgcn_sched_barrier(0)
; __device__ __forceinline__ void partialSM(f32x16& p0, f32x16& p1, float& m_reg, float& mn, float& alpha) {
;     constexpr float C = SCALE * 1.4426950408889634f;
;     float pmax = p0[0];
; #pragma unroll
;     for (int r = 1; r < 16; ++r) pmax = fmaxf(pmax, p0[r]);
; #pragma unroll
;     for (int r = 0; r < 16; ++r) pmax = fmaxf(pmax, p1[r]);
;     { auto rr = __builtin_amdgcn_permlane32_swap(__float_as_uint(pmax), __float_as_uint(pmax), false, false);
;       pmax = fmaxf(__uint_as_float(rr[0]), __uint_as_float(rr[1])); }
;     if (__builtin_expect(__all(pmax - m_reg <= THR / SCALE), 1)) { mn = m_reg; alpha = 1.f; }
;     else { mn = fmaxf(m_reg, pmax); alpha = __builtin_amdgcn_exp2f((m_reg - mn) * C); m_reg = mn; }
; template <int OFF> __device__ __forceinline__ s16x4 tr_read(int vb) {
;     s16x4 r; asm volatile("ds_read_b64_tr_b16 %0, %1 offset:%2" : "=&v"(r) : "v"(vb), "i"(OFF) : "memory"); return r;
; }
; template <int D0> __device__ __forceinline__ void pv_one(f32x16& od, int vb, bf16x8 pa0, bf16x8 pa1, bf16x8 pa2, bf16x8 pa3) {
;     const s16x4 l0 = tr_read<v_rd_off(D0, 0, 0)>(vb), h0 = tr_read<v_rd_off(D0, 0, 1)>(vb), l1 = tr_read<v_rd_off(D0, 1, 0)>(vb), h1 = tr_read<v_rd_off(D0, 1, 1)>(vb);
;     const s16x4 l2 = tr_read<v_rd_off(D0, 2, 0)>(vb), h2 = tr_read<v_rd_off(D0, 2, 1)>(vb), l3 = tr_read<v_rd_off(D0, 3, 0)>(vb), h3 = tr_read<v_rd_off(D0, 3, 1)>(vb);
;     asm volatile("s_waitcnt lgkmcnt(0)" ::: "memory"); SBAR();
;     ...
;     od = __builtin_amdgcn_mfma_f32_32x32x16_bf16(pa0, PK(l0, h0), od, 0, 0, 0);
;     od = __builtin_amdgcn_mfma_f32_32x32x16_bf16(pa1, PK(l1, h1), od, 0, 0, 0);
;     od = __builtin_amdgcn_mfma_f32_32x32x16_bf16(pa2, PK(l2, h2), od, 0, 0, 0);
;     od = __builtin_amdgcn_mfma_f32_32x32x16_bf16(pa3, PK(l3, h3), od, 0, 0, 0);
;     ...
; }
; __device__ __forceinline__ void pv_d0(f32x16* o, int vb, bf16x8 pa0, bf16x8 pa1, bf16x8 pa2, bf16x8 pa3) {
;     pv_one<0>(o[0], vb, pa0, pa1, pa2, pa3); pv_one<1>(o[1], vb, pa0, pa1, pa2, pa3); pv_one<2>(o[2], vb, pa0, pa1, pa2, pa3); pv_one<3>(o[3], vb, pa0, pa1, pa2, pa3);
; }
	v_mfma_f32_32x32x16_bf16 v[80:95], v[206:209], v[218:221], v[80:95]
	v_cvt_pk_bf16_f32 v154, v145, v147
	v_cvt_pk_bf16_f32 v155, v144, v146
	v_cvt_pk_bf16_f32 v204, v140, v141
	v_cvt_pk_bf16_f32 v205, v138, v139
	v_cvt_pk_bf16_f32 v206, v132, v133
	v_permlane32_swap_b32_e32 v148, v150
	v_mfma_f32_32x32x16_bf16 v[64:79], v[214:217], v[218:221], v[64:79]
	v_cvt_pk_bf16_f32 v207, v130, v131
	v_permlane32_swap_b32_e32 v204, v206
	v_cvt_pk_bf16_f32 v208, v128, v129
	v_cvt_pk_bf16_f32 v209, v142, v143
	v_cvt_pk_bf16_f32 v210, v136, v137
	v_cvt_pk_bf16_f32 v211, v134, v135
	v_permlane32_swap_b32_e32 v149, v151
	v_permlane32_swap_b32_e32 v152, v154
	v_permlane32_swap_b32_e32 v153, v155
	v_permlane32_swap_b32_e32 v205, v207
	v_permlane32_swap_b32_e32 v208, v210
	v_permlane32_swap_b32_e32 v209, v211
	s_add_i32 m0, s37, 0x0
	s_nop 0
	global_load_lds_dwordx4 v242, s[44:45]
	s_add_i32 m0, s37, 0x2000
	v_add_u32_e32 v242, 0x40000, v242
	global_load_lds_dwordx4 v243, s[44:45]
	s_add_i32 m0, s37, 0x8000
	v_add_u32_e32 v243, 0x40000, v243
	global_load_lds_dwordx4 v244, s[44:45]
	s_add_i32 m0, s37, 0xa000
	v_add_u32_e32 v244, 0x40000, v244
	global_load_lds_dwordx4 v245, s[44:45]
	s_add_i32 m0, s37, 0x10000
	v_add_u32_e32 v245, 0x40000, v245
	global_load_lds_dwordx4 v246, s[44:45]
	v_add_u32_e32 v246, 0x2000, v246
	ds_read_b64_tr_b16 v[214:215], v168 offset:0
	ds_read_b64_tr_b16 v[216:217], v168 offset:0x800
	ds_read_b64_tr_b16 v[218:219], v168 offset:0x1000
	ds_read_b64_tr_b16 v[220:221], v168 offset:0x1800
	ds_read_b64_tr_b16 v[224:225], v168 offset:0x2000
	ds_read_b64_tr_b16 v[226:227], v168 offset:0x2800
	ds_read_b64_tr_b16 v[238:239], v168 offset:0x3000
	ds_read_b64_tr_b16 v[240:241], v168 offset:0x3800
	s_waitcnt lgkmcnt(0)
	s_nop 0
	v_mfma_f32_32x32x16_bf16 v[0:15], v[148:151], v[214:217], v[0:15]
	ds_read_b64_tr_b16 v[214:215], v168 offset:0x200
	ds_read_b64_tr_b16 v[216:217], v168 offset:0xa00
	v_mfma_f32_32x32x16_bf16 v[0:15], v[152:155], v[218:221], v[0:15]
	ds_read_b64_tr_b16 v[218:219], v168 offset:0x1200
	ds_read_b64_tr_b16 v[220:221], v168 offset:0x1a00
	v_mfma_f32_32x32x16_bf16 v[0:15], v[204:207], v[224:227], v[0:15]
	ds_read_b64_tr_b16 v[224:225], v168 offset:0x2200
	ds_read_b64_tr_b16 v[226:227], v168 offset:0x2a00
	v_mfma_f32_32x32x16_bf16 v[0:15], v[208:211], v[238:241], v[0:15]
	ds_read_b64_tr_b16 v[238:239], v168 offset:0x3200
	ds_read_b64_tr_b16 v[240:241], v168 offset:0x3a00
	s_waitcnt lgkmcnt(0)
	v_mfma_f32_32x32x16_bf16 v[48:63], v[148:151], v[214:217], v[48:63]
	ds_read_b64_tr_b16 v[214:215], v168 offset:0x400
	ds_read_b64_tr_b16 v[216:217], v168 offset:0xc00
	v_mfma_f32_32x32x16_bf16 v[48:63], v[152:155], v[218:221], v[48:63]
	ds_read_b64_tr_b16 v[218:219], v168 offset:0x1400
	ds_read_b64_tr_b16 v[220:221], v168 offset:0x1c00
	v_mfma_f32_32x32x16_bf16 v[48:63], v[204:207], v[224:227], v[48:63]
	ds_read_b64_tr_b16 v[224:225], v168 offset:0x2400
	ds_read_b64_tr_b16 v[226:227], v168 offset:0x2c00
	v_mfma_f32_32x32x16_bf16 v[48:63], v[208:211], v[238:241], v[48:63]
	ds_read_b64_tr_b16 v[238:239], v168 offset:0x3400
	ds_read_b64_tr_b16 v[240:241], v168 offset:0x3c00
	s_waitcnt lgkmcnt(0)
	v_mfma_f32_32x32x16_bf16 v[32:47], v[148:151], v[214:217], v[32:47]
	ds_read_b64_tr_b16 v[214:215], v168 offset:0x600
	ds_read_b64_tr_b16 v[216:217], v168 offset:0xe00
	v_mfma_f32_32x32x16_bf16 v[32:47], v[152:155], v[218:221], v[32:47]
	ds_read_b64_tr_b16 v[218:219], v168 offset:0x1600
	ds_read_b64_tr_b16 v[220:221], v168 offset:0x1e00
	v_mfma_f32_32x32x16_bf16 v[32:47], v[204:207], v[224:227], v[32:47]
	ds_read_b64_tr_b16 v[224:225], v168 offset:0x2600
	ds_read_b64_tr_b16 v[226:227], v168 offset:0x2e00
	v_mfma_f32_32x32x16_bf16 v[32:47], v[208:211], v[238:241], v[32:47]
	ds_read_b64_tr_b16 v[238:239], v168 offset:0x3600
	ds_read_b64_tr_b16 v[240:241], v168 offset:0x3e00
	s_waitcnt lgkmcnt(0)
	v_mfma_f32_32x32x16_bf16 v[16:31], v[148:151], v[214:217], v[16:31]
	v_max_f32_e32 v148, v81, v81
	v_max_f32_e32 v149, v80, v80
	v_max_f32_e32 v148, v149, v148
	v_max3_f32 v148, v148, v82, v83
	v_max3_f32 v148, v148, v84, v85
	v_max3_f32 v148, v148, v86, v87
	v_max3_f32 v148, v148, v88, v89
	v_max3_f32 v148, v148, v90, v91
	v_max3_f32 v148, v148, v92, v93
	v_mfma_f32_32x32x16_bf16 v[16:31], v[152:155], v[218:221], v[16:31]
	v_max3_f32 v148, v148, v94, v95
	v_max3_f32 v148, v148, v64, v65
	v_max3_f32 v148, v148, v66, v67
	v_max3_f32 v148, v148, v68, v69
	v_max3_f32 v148, v148, v70, v71
	v_max3_f32 v148, v148, v72, v73
	v_max3_f32 v148, v148, v74, v75
	v_max3_f32 v148, v148, v76, v77
	v_mfma_f32_32x32x16_bf16 v[16:31], v[204:207], v[224:227], v[16:31]
	v_max3_f32 v148, v148, v78, v79
	v_mov_b32_e32 v149, v148
	s_nop 1
	v_permlane32_swap_b32_e32 v148, v149
	v_max_f32_e32 v149, v149, v149
	v_max_f32_e32 v148, v148, v148
	v_max_f32_e32 v148, v148, v149
	v_sub_f32_e32 v149, v148, v197
	v_cmp_ge_f32_e32 vcc, s88, v149
	v_max_f32_e32 v149, v197, v197
	v_max_f32_e32 v148, v149, v148
	v_mfma_f32_32x32x16_bf16 v[16:31], v[208:211], v[238:241], v[16:31]
	v_sub_f32_e32 v149, v197, v148
	v_mul_f32_e32 v149, 0x3dd53b94, v149
	v_exp_f32_e32 v149, v149
	s_cmp_eq_u64 vcc, exec
	s_cselect_b64 s[8:9], -1, 0
	v_cndmask_b32_e64 v204, v149, 1.0, s[8:9]
	v_cmp_gt_f32_e32 vcc, 1.0, v204
	s_cbranch_vccz .Latt_u2_612
; #define SBAR() __builtin_amdgcn_sched_barrier(0)
; #define RESC(a) do { if (__any((a) < 1.f)) { if (hi == 0) al_l[r32] = (a); asm volatile("s_waitcnt lgkmcnt(0)" ::: "memory"); \
;     _Pragma("unroll") for (int d = 0; d < 4; ++d) _Pragma("unroll") for (int r = 0; r < 16; ++r) o[d][r] *= al_l[crow(r, hi)]; } } while (0)
; __device__ __forceinline__ void partialSM(f32x16& p0, f32x16& p1, float& m_reg, float& mn, float& alpha) {
;     constexpr float C = SCALE * 1.4426950408889634f;
;     float pmax = p0[0];
; #pragma unroll
;     for (int r = 1; r < 16; ++r) pmax = fmaxf(pmax, p0[r]);
; #pragma unroll
;     for (int r = 0; r < 16; ++r) pmax = fmaxf(pmax, p1[r]);
;     { auto rr = __builtin_amdgcn_permlane32_swap(__float_as_uint(pmax), __float_as_uint(pmax), false, false);
;       pmax = fmaxf(__uint_as_float(rr[0]), __uint_as_float(rr[1])); }
;     if (__builtin_expect(__all(pmax - m_reg <= THR / SCALE), 1)) { mn = m_reg; alpha = 1.f; }
;     else { mn = fmaxf(m_reg, pmax); alpha = __builtin_amdgcn_exp2f((m_reg - mn) * C); m_reg = mn; }
;     const float mnC = -mn * C;
; #pragma unroll
;     for (int r = 0; r < 16; ++r) p0[r] = fmaf(p0[r], C, mnC);
; #pragma unroll
;     for (int r = 0; r < 16; ++r) p1[r] = fmaf(p1[r], C, mnC);
; #pragma unroll
;     for (int r = 0; r < 16; ++r) p0[r] = __builtin_amdgcn_exp2f(p0[r]);
; }
; __device__ __forceinline__ void attn_body(const bf16_t* __restrict__ Qb, const bf16_t* __restrict__ Kh, const bf16_t* __restrict__ Vh, const bf16_t* __restrict__ Rh,
;                                           bf16_t* __restrict__ Zb, int seq, char* lds, int wv, bool nowrite) {
;     ...
;         RESC(alB); __syncthreads();
;         SBAR(); qkt(pA0, pA1, K_lds, R_lds, qr, Qp, r32, hi);
	s_and_saveexec_b64 s[10:11], s[6:7]
	ds_write_b32 v166, v204 offset:128
	s_or_b64 exec, exec, s[10:11]
	s_waitcnt lgkmcnt(0)
	v_add_u32_e32 v140, s1, v212
	ds_read_b128 v[128:131], v140 offset:224
	ds_read_b128 v[132:135], v140 offset:192
	ds_read_b128 v[136:139], v140 offset:160
	ds_read_b128 v[140:143], v140 offset:128
	s_waitcnt lgkmcnt(3)
	v_pk_mul_f32 v[12:13], v[12:13], v[128:129]
	s_waitcnt lgkmcnt(2)
	v_pk_mul_f32 v[8:9], v[8:9], v[132:133]
	s_waitcnt lgkmcnt(1)
	v_pk_mul_f32 v[4:5], v[4:5], v[136:137]
	v_pk_mul_f32 v[14:15], v[14:15], v[130:131]
	v_pk_mul_f32 v[10:11], v[10:11], v[134:135]
	v_pk_mul_f32 v[6:7], v[6:7], v[138:139]
	s_waitcnt lgkmcnt(0)
	v_pk_mul_f32 v[2:3], v[2:3], v[142:143]
	v_pk_mul_f32 v[0:1], v[0:1], v[140:141]
	v_pk_mul_f32 v[60:61], v[60:61], v[128:129]
	v_pk_mul_f32 v[56:57], v[56:57], v[132:133]
	v_pk_mul_f32 v[52:53], v[52:53], v[136:137]
	v_pk_mul_f32 v[62:63], v[62:63], v[130:131]
	v_pk_mul_f32 v[58:59], v[58:59], v[134:135]
	v_pk_mul_f32 v[54:55], v[54:55], v[138:139]
	v_pk_mul_f32 v[50:51], v[50:51], v[142:143]
	v_pk_mul_f32 v[48:49], v[48:49], v[140:141]
	v_pk_mul_f32 v[44:45], v[44:45], v[128:129]
	v_pk_mul_f32 v[40:41], v[40:41], v[132:133]
	v_pk_mul_f32 v[36:37], v[36:37], v[136:137]
	v_pk_mul_f32 v[46:47], v[46:47], v[130:131]
	v_pk_mul_f32 v[42:43], v[42:43], v[134:135]
	v_pk_mul_f32 v[38:39], v[38:39], v[138:139]
	v_pk_mul_f32 v[34:35], v[34:35], v[142:143]
	v_pk_mul_f32 v[32:33], v[32:33], v[140:141]
	v_pk_mul_f32 v[28:29], v[28:29], v[128:129]
	v_pk_mul_f32 v[24:25], v[24:25], v[132:133]
	v_pk_mul_f32 v[20:21], v[20:21], v[136:137]
	v_pk_mul_f32 v[30:31], v[30:31], v[130:131]
	v_pk_mul_f32 v[26:27], v[26:27], v[134:135]
	v_pk_mul_f32 v[22:23], v[22:23], v[138:139]
	v_pk_mul_f32 v[18:19], v[18:19], v[142:143]
	v_pk_mul_f32 v[16:17], v[16:17], v[140:141]
.Latt_u2_612:
	v_cndmask_b32_e64 v197, v148, v197, s[8:9]
	v_mul_f32_e32 v144, 0xbdd53b94, v197
	v_fmamk_f32 v80, v80, 0x3dd53b94, v144
	v_fmamk_f32 v81, v81, 0x3dd53b94, v144
	v_fmamk_f32 v82, v82, 0x3dd53b94, v144
	v_fmamk_f32 v83, v83, 0x3dd53b94, v144
	v_fmamk_f32 v84, v84, 0x3dd53b94, v144
	v_fmamk_f32 v85, v85, 0x3dd53b94, v144
	v_fmamk_f32 v86, v86, 0x3dd53b94, v144
	v_fmamk_f32 v87, v87, 0x3dd53b94, v144
	v_fmamk_f32 v88, v88, 0x3dd53b94, v144
	v_fmamk_f32 v89, v89, 0x3dd53b94, v144
	v_fmamk_f32 v90, v90, 0x3dd53b94, v144
	v_fmamk_f32 v91, v91, 0x3dd53b94, v144
	v_fmamk_f32 v92, v92, 0x3dd53b94, v144
	v_fmamk_f32 v93, v93, 0x3dd53b94, v144
	v_fmamk_f32 v94, v94, 0x3dd53b94, v144
	v_fmamk_f32 v95, v95, 0x3dd53b94, v144
	v_fmamk_f32 v206, v68, 0x3dd53b94, v144
	v_fmamk_f32 v148, v71, 0x3dd53b94, v144
	v_fmamk_f32 v149, v72, 0x3dd53b94, v144
	v_fmamk_f32 v207, v77, 0x3dd53b94, v144
	v_fmamk_f32 v153, v64, 0x3dd53b94, v144
	v_fmamk_f32 v154, v65, 0x3dd53b94, v144
	v_fmamk_f32 v155, v66, 0x3dd53b94, v144
	v_fmamk_f32 v205, v67, 0x3dd53b94, v144
	v_fmamk_f32 v146, v69, 0x3dd53b94, v144
	v_fmamk_f32 v147, v70, 0x3dd53b94, v144
	v_fmamk_f32 v150, v73, 0x3dd53b94, v144
	v_fmamk_f32 v151, v74, 0x3dd53b94, v144
	v_fmamk_f32 v152, v75, 0x3dd53b94, v144
	v_fmamk_f32 v145, v76, 0x3dd53b94, v144
	v_exp_f32_e32 v141, v80
	v_exp_f32_e32 v143, v81
	v_exp_f32_e32 v139, v82
	v_exp_f32_e32 v142, v83
	v_exp_f32_e32 v138, v84
	v_exp_f32_e32 v140, v85
	v_exp_f32_e32 v136, v86
	v_exp_f32_e32 v137, v87
	v_exp_f32_e32 v133, v88
	v_exp_f32_e32 v135, v89
	v_exp_f32_e32 v132, v90
	v_exp_f32_e32 v134, v91
	v_exp_f32_e32 v129, v92
	v_exp_f32_e32 v131, v93
	v_exp_f32_e32 v128, v94
	v_exp_f32_e32 v130, v95
	v_fmamk_f32 v208, v78, 0x3dd53b94, v144
	v_fmac_f32_e32 v144, 0x3dd53b94, v79
	s_waitcnt vmcnt(0)
	s_waitcnt lgkmcnt(0)
	s_barrier
	ds_read_b128 v[64:67], v174 offset:32768
	ds_read_b128 v[68:71], v174 offset:40960
	ds_read_b128 v[214:217], v180 offset:32768
	ds_read_b128 v[218:221], v180 offset:40960
	v_exp_f32_e32 v209, v153
	v_exp_f32_e32 v210, v154
	s_waitcnt lgkmcnt(3)
	v_mfma_f32_32x32x16_bf16 v[80:95], v[64:67], v[120:123], 0
	v_exp_f32_e32 v211, v155
	v_exp_f32_e32 v205, v205
	v_exp_f32_e32 v146, v146
	v_exp_f32_e32 v147, v147
	v_exp_f32_e32 v145, v145
	v_exp_f32_e32 v144, v144
	s_waitcnt lgkmcnt(2)
	v_mfma_f32_32x32x16_bf16 v[64:79], v[68:71], v[120:123], 0
	s_waitcnt lgkmcnt(1)
	v_mfma_f32_32x32x16_bf16 v[80:95], v[214:217], v[124:127], v[80:95]
	s_waitcnt lgkmcnt(0)
	v_mfma_f32_32x32x16_bf16 v[64:79], v[218:221], v[124:127], v[64:79]
	ds_read_b128 v[214:217], v182 offset:32768
	ds_read_b128 v[218:221], v182 offset:40960
	s_waitcnt lgkmcnt(1)
	v_mfma_f32_32x32x16_bf16 v[80:95], v[214:217], v[116:119], v[80:95]
	s_waitcnt lgkmcnt(0)
	v_mfma_f32_32x32x16_bf16 v[64:79], v[218:221], v[116:119], v[64:79]
	ds_read_b128 v[214:217], v184 offset:32768
	ds_read_b128 v[218:221], v184 offset:40960
	s_waitcnt lgkmcnt(1)
	v_mfma_f32_32x32x16_bf16 v[80:95], v[214:217], v[112:115], v[80:95]
	s_waitcnt lgkmcnt(0)
	v_mfma_f32_32x32x16_bf16 v[64:79], v[218:221], v[112:115], v[64:79]
	ds_read_b128 v[214:217], v185 offset:32768
	ds_read_b128 v[218:221], v185 offset:40960
	s_waitcnt lgkmcnt(1)
	v_mfma_f32_32x32x16_bf16 v[80:95], v[214:217], v[108:111], v[80:95]
	s_waitcnt lgkmcnt(0)
	v_mfma_f32_32x32x16_bf16 v[64:79], v[218:221], v[108:111], v[64:79]
	ds_read_b128 v[214:217], v183 offset:32768
	ds_read_b128 v[218:221], v183 offset:40960
	s_waitcnt lgkmcnt(1)
	v_mfma_f32_32x32x16_bf16 v[80:95], v[214:217], v[104:107], v[80:95]
	s_waitcnt lgkmcnt(0)
	v_mfma_f32_32x32x16_bf16 v[64:79], v[218:221], v[104:107], v[64:79]
	ds_read_b128 v[214:217], v181 offset:32768
	ds_read_b128 v[218:221], v181 offset:40960
	s_waitcnt lgkmcnt(1)
	v_mfma_f32_32x32x16_bf16 v[80:95], v[214:217], v[100:103], v[80:95]
	s_waitcnt lgkmcnt(0)
; __device__ __forceinline__ void finishSM(f32x16& p0, f32x16& p1, float alpha, float& l_reg, bf16x8& pa0, bf16x8& pa1, bf16x8& pa2, bf16x8& pa3) {
; #pragma unroll
;     for (int r = 0; r < 16; ++r) p1[r] = __builtin_amdgcn_exp2f(p1[r]);
;     float ps = 0;
; #pragma unroll
;     for (int r = 0; r < 16; ++r) ps += p0[r];
; #pragma unroll
;     for (int r = 0; r < 16; ++r) ps += p1[r];
;     { auto rr = __builtin_amdgcn_permlane32_swap(__float_as_uint(ps), __float_as_uint(ps), false, false);
;       ps = __uint_as_float(rr[0]) + __uint_as_float(rr[1]); }
;     l_reg = l_reg * alpha + ps;
;     ...
;     PK4(p0, 0, pa0); PK4(p0, 8, pa1); PK4(p1, 0, pa2); PK4(p1, 8, pa3);
;     ...
; }
; __device__ __forceinline__ void qkt(f32x16& p0, f32x16& p1, const char* Ks, const char* Rs, const bf16x8* qr, const char* Qp, int r32, int hi) {
;     p0 = f32x16{}; p1 = f32x16{};
; #pragma unroll
;     for (int d0 = 0; d0 < 8; ++d0) { const int cb = (d0 * 16 + hi * 8) * 2;
;         const bf16x8 b0 = *reinterpret_cast<const bf16x8*>(Ks + KSWZ(r32, cb));
;         const bf16x8 b1 = *reinterpret_cast<const bf16x8*>(Ks + KSWZ(32 + r32, cb));
;         p0 = __builtin_amdgcn_mfma_f32_32x32x16_bf16(b0, qr[d0], p0, 0, 0, 0);
;         p1 = __builtin_amdgcn_mfma_f32_32x32x16_bf16(b1, qr[d0], p1, 0, 0, 0); }
; #pragma unroll
;     for (int d0 = 0; d0 < 4; ++d0) { const int cb = (d0 * 16 + hi * 8) * 2;
;         const bf16x8 b0 = *reinterpret_cast<const bf16x8*>(Rs + RSWZ(r32, cb));
;         const bf16x8 b1 = *reinterpret_cast<const bf16x8*>(Rs + RSWZ(32 + r32, cb));
;         const bf16x8 qq = *reinterpret_cast<const bf16x8*>(Qp + RSWZ(r32, cb));
;         p0 = __builtin_amdgcn_mfma_f32_32x32x16_bf16(b0, qq, p0, 0, 0, 0);
;         p1 = __builtin_amdgcn_mfma_f32_32x32x16_bf16(b1, qq, p1, 0, 0, 0); }
; }
; __device__ __forceinline__ int v_st(int k, int c) { const int kk = (k & ~0xC) | ((k & 4) << 1) | ((k & 8) >> 1); return ((kk >> 3) * 4 + (c >> 5)) * 512 + ((kk & 7) * 32 + (c & 31)) * 2; }
; __device__ __forceinline__ int v_rd_base(int lane) { return ((lane & 3) << 3) | (((lane >> 2) & 3) << 6) | (((lane >> 4) & 1) << 5) | (((lane >> 5) & 1) << 8); }
; template <int OFF> __device__ __forceinline__ s16x4 tr_read(int vb) {
;     s16x4 r; asm volatile("ds_read_b64_tr_b16 %0, %1 offset:%2" : "=&v"(r) : "v"(vb), "i"(OFF) : "memory"); return r;
; }
	v_mfma_f32_32x32x16_bf16 v[64:79], v[218:221], v[100:103], v[64:79]
	ds_read_b128 v[214:217], v179 offset:32768
	ds_read_b128 v[218:221], v179 offset:40960
	s_waitcnt lgkmcnt(1)
	v_mfma_f32_32x32x16_bf16 v[80:95], v[214:217], v[96:99], v[80:95]
	s_waitcnt lgkmcnt(0)
	v_mfma_f32_32x32x16_bf16 v[64:79], v[218:221], v[96:99], v[64:79]
	ds_read_b128 v[214:217], v187
	ds_read_b128 v[218:221], v187 offset:4096
	ds_read_b128 v[224:227], v177
	s_waitcnt lgkmcnt(0)
	v_mfma_f32_32x32x16_bf16 v[80:95], v[214:217], v[224:227], v[80:95]
	v_mfma_f32_32x32x16_bf16 v[64:79], v[218:221], v[224:227], v[64:79]
	ds_read_b128 v[214:217], v189
	ds_read_b128 v[218:221], v189 offset:4096
	ds_read_b128 v[224:227], v175
	s_waitcnt lgkmcnt(0)
	v_mfma_f32_32x32x16_bf16 v[80:95], v[214:217], v[224:227], v[80:95]
	v_mfma_f32_32x32x16_bf16 v[64:79], v[218:221], v[224:227], v[64:79]
	ds_read_b128 v[214:217], v191
	ds_read_b128 v[218:221], v191 offset:4096
	ds_read_b128 v[224:227], v178
	s_waitcnt lgkmcnt(0)
	v_mfma_f32_32x32x16_bf16 v[80:95], v[214:217], v[224:227], v[80:95]
	v_mfma_f32_32x32x16_bf16 v[64:79], v[218:221], v[224:227], v[64:79]
	ds_read_b128 v[214:217], v193
	ds_read_b128 v[218:221], v193 offset:4096
	ds_read_b128 v[224:227], v176
	s_waitcnt lgkmcnt(0)
	v_mfma_f32_32x32x16_bf16 v[80:95], v[214:217], v[224:227], v[80:95]
	v_exp_f32_e32 v215, v148
	v_add_f32_e32 v148, 0, v141
	v_add_f32_e32 v148, v143, v148
	v_add_f32_e32 v148, v139, v148
	v_add_f32_e32 v148, v142, v148
	v_add_f32_e32 v148, v138, v148
	v_add_f32_e32 v148, v140, v148
	v_add_f32_e32 v148, v136, v148
	v_add_f32_e32 v148, v137, v148
	v_add_f32_e32 v148, v133, v148
	v_add_f32_e32 v148, v135, v148
	v_add_f32_e32 v148, v132, v148
	v_add_f32_e32 v148, v134, v148
	v_add_f32_e32 v148, v129, v148
	v_add_f32_e32 v148, v131, v148
	v_add_f32_e32 v148, v128, v148
	v_add_f32_e32 v148, v130, v148
	v_exp_f32_e32 v214, v206
	v_add_f32_e32 v148, v209, v148
	v_add_f32_e32 v148, v210, v148
	v_add_f32_e32 v148, v211, v148
	v_add_f32_e32 v148, v205, v148
	v_exp_f32_e32 v216, v149
	v_add_f32_e32 v148, v214, v148
	v_exp_f32_e32 v217, v150
	v_add_f32_e32 v148, v146, v148
	v_mfma_f32_32x32x16_bf16 v[64:79], v[218:221], v[224:227], v[64:79]
	v_exp_f32_e32 v218, v151
	v_add_f32_e32 v148, v147, v148
	v_exp_f32_e32 v219, v152
	v_add_f32_e32 v148, v215, v148
	v_add_f32_e32 v148, v216, v148
	v_exp_f32_e32 v220, v207
	v_add_f32_e32 v148, v217, v148
	v_exp_f32_e32 v221, v208
	v_add_f32_e32 v148, v218, v148
	v_add_f32_e32 v148, v219, v148
	v_add_f32_e32 v148, v145, v148
	v_add_f32_e32 v148, v220, v148
	v_add_f32_e32 v148, v221, v148
	v_add_f32_e32 v206, v144, v148
	v_mov_b32_e32 v207, v206
	v_cvt_pk_bf16_f32 v148, v141, v143
	v_cvt_pk_bf16_f32 v149, v139, v142
	v_cvt_pk_bf16_f32 v150, v138, v140
	v_cvt_pk_bf16_f32 v151, v136, v137
	s_nop 1
	v_permlane32_swap_b32_e32 v206, v207
	v_permlane32_swap_b32_e32 v148, v150
	v_permlane32_swap_b32_e32 v149, v151
	v_cvt_pk_bf16_f32 v152, v133, v135
	v_cvt_pk_bf16_f32 v153, v132, v134
	v_cvt_pk_bf16_f32 v154, v129, v131
	v_cvt_pk_bf16_f32 v155, v128, v130
	v_cvt_pk_bf16_f32 v208, v209, v210
	v_cvt_pk_bf16_f32 v209, v211, v205
	v_cvt_pk_bf16_f32 v210, v214, v146
	v_cvt_pk_bf16_f32 v211, v147, v215
	v_cvt_pk_bf16_f32 v214, v216, v217
	v_cvt_pk_bf16_f32 v215, v218, v219
	v_cvt_pk_bf16_f32 v216, v145, v220
	v_cvt_pk_bf16_f32 v217, v221, v144
	s_nop 0
	v_permlane32_swap_b32_e32 v152, v154
	v_permlane32_swap_b32_e32 v153, v155
	v_permlane32_swap_b32_e32 v208, v210
	v_permlane32_swap_b32_e32 v209, v211
	v_permlane32_swap_b32_e32 v214, v216
	v_permlane32_swap_b32_e32 v215, v217
	s_add_i32 m0, s37, 0x4000
	s_nop 0
	global_load_lds_dwordx4 v242, s[44:45]
	s_add_i32 m0, s37, 0x6000
	v_add_u32_e32 v242, 0x40000, v242
	global_load_lds_dwordx4 v243, s[44:45]
	s_add_i32 m0, s37, 0xc000
	v_add_u32_e32 v243, 0x40000, v243
	global_load_lds_dwordx4 v244, s[44:45]
	s_add_i32 m0, s37, 0xe000
	v_add_u32_e32 v244, 0x40000, v244
	global_load_lds_dwordx4 v245, s[44:45]
	s_add_i32 m0, s37, 0x12000
	v_add_u32_e32 v245, 0x40000, v245
	global_load_lds_dwordx4 v246, s[44:45]
	v_add_u32_e32 v246, 0x2000, v246
	ds_read_b64_tr_b16 v[160:161], v247 offset:0
	ds_read_b64_tr_b16 v[162:163], v247 offset:0x800
	ds_read_b64_tr_b16 v[218:219], v247 offset:0x1000
	ds_read_b64_tr_b16 v[220:221], v247 offset:0x1800
	ds_read_b64_tr_b16 v[224:225], v247 offset:0x2000
	ds_read_b64_tr_b16 v[226:227], v247 offset:0x2800
	ds_read_b64_tr_b16 v[238:239], v247 offset:0x3000
	ds_read_b64_tr_b16 v[240:241], v247 offset:0x3800
	s_waitcnt lgkmcnt(0)
	s_nop 0
	v_mfma_f32_32x32x16_bf16 v[0:15], v[148:151], v[160:163], v[0:15]
	ds_read_b64_tr_b16 v[160:161], v247 offset:0x200
	ds_read_b64_tr_b16 v[162:163], v247 offset:0xa00
	v_mfma_f32_32x32x16_bf16 v[0:15], v[152:155], v[218:221], v[0:15]
	ds_read_b64_tr_b16 v[218:219], v247 offset:0x1200
	ds_read_b64_tr_b16 v[220:221], v247 offset:0x1a00
	v_mfma_f32_32x32x16_bf16 v[0:15], v[208:211], v[224:227], v[0:15]
	ds_read_b64_tr_b16 v[224:225], v247 offset:0x2200
	ds_read_b64_tr_b16 v[226:227], v247 offset:0x2a00
	v_mfma_f32_32x32x16_bf16 v[0:15], v[214:217], v[238:241], v[0:15]
	ds_read_b64_tr_b16 v[238:239], v247 offset:0x3200
	ds_read_b64_tr_b16 v[240:241], v247 offset:0x3a00
	s_waitcnt lgkmcnt(0)
	v_mfma_f32_32x32x16_bf16 v[48:63], v[148:151], v[160:163], v[48:63]
	ds_read_b64_tr_b16 v[160:161], v247 offset:0x400
	ds_read_b64_tr_b16 v[162:163], v247 offset:0xc00
	v_mfma_f32_32x32x16_bf16 v[48:63], v[152:155], v[218:221], v[48:63]
	ds_read_b64_tr_b16 v[218:219], v247 offset:0x1400
	ds_read_b64_tr_b16 v[220:221], v247 offset:0x1c00
	v_mfma_f32_32x32x16_bf16 v[48:63], v[208:211], v[224:227], v[48:63]
	ds_read_b64_tr_b16 v[224:225], v247 offset:0x2400
	ds_read_b64_tr_b16 v[226:227], v247 offset:0x2c00
	v_mfma_f32_32x32x16_bf16 v[48:63], v[214:217], v[238:241], v[48:63]
	ds_read_b64_tr_b16 v[238:239], v247 offset:0x3400
	ds_read_b64_tr_b16 v[240:241], v247 offset:0x3c00
	s_waitcnt lgkmcnt(0)
; #define SWRITE(b) do { *(bf16x8*)(V_lds + (b) * SHM_V + vst0) = vs0; *(bf16x8*)(V_lds + (b) * SHM_V + vst1) = vs1; const int kc = sc * 2; \
;     *(bf16x8*)(K_lds + (b) * SHM_K + KSWZ(sr, kc)) = ks0; *(bf16x8*)(K_lds + (b) * SHM_K + KSWZ(32 + sr, kc)) = ks1; \
;     *(bf16x8*)(R_lds + (b) * SHM_R + RSWZ(rr, rc * 2)) = rs0; } while (0)
; #define SWAIT() asm volatile("s_waitcnt vmcnt(0)" ::: "memory")
; #define RESC(a) do { if (__any((a) < 1.f)) { if (hi == 0) al_l[r32] = (a); asm volatile("s_waitcnt lgkmcnt(0)" ::: "memory"); \
;     _Pragma("unroll") for (int d = 0; d < 4; ++d) _Pragma("unroll") for (int r = 0; r < 16; ++r) o[d][r] *= al_l[crow(r, hi)]; } } while (0)
; __device__ __forceinline__ void partialSM(f32x16& p0, f32x16& p1, float& m_reg, float& mn, float& alpha) {
;     constexpr float C = SCALE * 1.4426950408889634f;
;     float pmax = p0[0];
; #pragma unroll
;     for (int r = 1; r < 16; ++r) pmax = fmaxf(pmax, p0[r]);
; #pragma unroll
;     for (int r = 0; r < 16; ++r) pmax = fmaxf(pmax, p1[r]);
;     { auto rr = __builtin_amdgcn_permlane32_swap(__float_as_uint(pmax), __float_as_uint(pmax), false, false);
;       pmax = fmaxf(__uint_as_float(rr[0]), __uint_as_float(rr[1])); }
;     if (__builtin_expect(__all(pmax - m_reg <= THR / SCALE), 1)) { mn = m_reg; alpha = 1.f; }
;     else { mn = fmaxf(m_reg, pmax); alpha = __builtin_amdgcn_exp2f((m_reg - mn) * C); m_reg = mn; }
;     const float mnC = -mn * C;
; #pragma unroll
;     for (int r = 0; r < 16; ++r) p0[r] = fmaf(p0[r], C, mnC);
; #pragma unroll
;     for (int r = 0; r < 16; ++r) p1[r] = fmaf(p1[r], C, mnC);
; #pragma unroll
;     for (int r = 0; r < 16; ++r) p0[r] = __builtin_amdgcn_exp2f(p0[r]);
; }
; __device__ __forceinline__ void attn_body(const bf16_t* __restrict__ Qb, const bf16_t* __restrict__ Kh, const bf16_t* __restrict__ Vh, const bf16_t* __restrict__ Rh,
;                                           bf16_t* __restrict__ Zb, int seq, char* lds, int wv, bool nowrite) {
;     ...
;         pv_d0(o, vb0 + SHM_V, pa0, pa1, pa2, pa3); partialSM(pA0, pA1, m_reg, mnA, alA);
;         __syncthreads(); SWAIT(); SWRITE(1);
;         RESC(alA); __syncthreads();
;     }
	v_mfma_f32_32x32x16_bf16 v[32:47], v[148:151], v[160:163], v[32:47]
	ds_read_b64_tr_b16 v[160:161], v247 offset:0x600
	ds_read_b64_tr_b16 v[162:163], v247 offset:0xe00
	v_mfma_f32_32x32x16_bf16 v[32:47], v[152:155], v[218:221], v[32:47]
	ds_read_b64_tr_b16 v[218:219], v247 offset:0x1600
	ds_read_b64_tr_b16 v[220:221], v247 offset:0x1e00
	v_mfma_f32_32x32x16_bf16 v[32:47], v[208:211], v[224:227], v[32:47]
	ds_read_b64_tr_b16 v[224:225], v247 offset:0x2600
	ds_read_b64_tr_b16 v[226:227], v247 offset:0x2e00
	v_mfma_f32_32x32x16_bf16 v[32:47], v[214:217], v[238:241], v[32:47]
	ds_read_b64_tr_b16 v[238:239], v247 offset:0x3600
	ds_read_b64_tr_b16 v[240:241], v247 offset:0x3e00
	s_waitcnt lgkmcnt(0)
	v_mfma_f32_32x32x16_bf16 v[16:31], v[148:151], v[160:163], v[16:31]
	v_max_f32_e32 v148, v81, v81
	v_max_f32_e32 v149, v80, v80
	v_max_f32_e32 v148, v149, v148
	v_max3_f32 v148, v148, v82, v83
	v_max3_f32 v148, v148, v84, v85
	v_max3_f32 v148, v148, v86, v87
	v_max3_f32 v148, v148, v88, v89
	v_max3_f32 v148, v148, v90, v91
	v_max3_f32 v148, v148, v92, v93
	v_mfma_f32_32x32x16_bf16 v[16:31], v[152:155], v[218:221], v[16:31]
	v_max3_f32 v148, v148, v94, v95
	v_max3_f32 v148, v148, v64, v65
	v_max3_f32 v148, v148, v66, v67
	v_max3_f32 v148, v148, v68, v69
	v_max3_f32 v148, v148, v70, v71
	v_max3_f32 v148, v148, v72, v73
	v_max3_f32 v148, v148, v74, v75
	v_max3_f32 v148, v148, v76, v77
	v_mfma_f32_32x32x16_bf16 v[16:31], v[208:211], v[224:227], v[16:31]
	v_max3_f32 v148, v148, v78, v79
	v_mov_b32_e32 v149, v148
	s_nop 1
	v_permlane32_swap_b32_e32 v148, v149
	v_max_f32_e32 v149, v149, v149
	v_max_f32_e32 v148, v148, v148
	v_max_f32_e32 v148, v148, v149
	v_sub_f32_e32 v149, v148, v197
	v_cmp_ge_f32_e32 vcc, s88, v149
	v_max_f32_e32 v149, v197, v197
	v_max_f32_e32 v149, v149, v148
	v_mfma_f32_32x32x16_bf16 v[16:31], v[214:217], v[238:241], v[16:31]
	v_sub_f32_e32 v148, v197, v149
	v_mul_f32_e32 v148, 0x3dd53b94, v148
	v_exp_f32_e32 v148, v148
	s_cmp_eq_u64 vcc, exec
	s_cselect_b64 s[8:9], -1, 0
	v_cndmask_b32_e64 v148, v148, 1.0, s[8:9]
	v_cmp_gt_f32_e32 vcc, 1.0, v148
	s_cbranch_vccz .Latt_u2_616
	s_and_saveexec_b64 s[10:11], s[6:7]
	ds_write_b32 v166, v148 offset:128
	s_or_b64 exec, exec, s[10:11]
	s_waitcnt lgkmcnt(0)
	v_add_u32_e32 v140, s1, v212
	ds_read_b128 v[128:131], v140 offset:224
	ds_read_b128 v[132:135], v140 offset:192
	ds_read_b128 v[136:139], v140 offset:160
	ds_read_b128 v[140:143], v140 offset:128
	s_waitcnt lgkmcnt(3)
	v_pk_mul_f32 v[12:13], v[12:13], v[128:129]
	s_waitcnt lgkmcnt(2)
	v_pk_mul_f32 v[8:9], v[8:9], v[132:133]
	s_waitcnt lgkmcnt(1)
	v_pk_mul_f32 v[4:5], v[4:5], v[136:137]
	v_pk_mul_f32 v[14:15], v[14:15], v[130:131]
	v_pk_mul_f32 v[10:11], v[10:11], v[134:135]
	v_pk_mul_f32 v[6:7], v[6:7], v[138:139]
	s_waitcnt lgkmcnt(0)
	v_pk_mul_f32 v[2:3], v[2:3], v[142:143]
	v_pk_mul_f32 v[0:1], v[0:1], v[140:141]
	v_pk_mul_f32 v[60:61], v[60:61], v[128:129]
	v_pk_mul_f32 v[56:57], v[56:57], v[132:133]
	v_pk_mul_f32 v[52:53], v[52:53], v[136:137]
	v_pk_mul_f32 v[62:63], v[62:63], v[130:131]
	v_pk_mul_f32 v[58:59], v[58:59], v[134:135]
	v_pk_mul_f32 v[54:55], v[54:55], v[138:139]
	v_pk_mul_f32 v[50:51], v[50:51], v[142:143]
	v_pk_mul_f32 v[48:49], v[48:49], v[140:141]
	v_pk_mul_f32 v[44:45], v[44:45], v[128:129]
	v_pk_mul_f32 v[40:41], v[40:41], v[132:133]
	v_pk_mul_f32 v[36:37], v[36:37], v[136:137]
	v_pk_mul_f32 v[46:47], v[46:47], v[130:131]
	v_pk_mul_f32 v[42:43], v[42:43], v[134:135]
	v_pk_mul_f32 v[38:39], v[38:39], v[138:139]
	v_pk_mul_f32 v[34:35], v[34:35], v[142:143]
	v_pk_mul_f32 v[32:33], v[32:33], v[140:141]
	v_pk_mul_f32 v[28:29], v[28:29], v[128:129]
	v_pk_mul_f32 v[24:25], v[24:25], v[132:133]
	v_pk_mul_f32 v[20:21], v[20:21], v[136:137]
	v_pk_mul_f32 v[30:31], v[30:31], v[130:131]
	v_pk_mul_f32 v[26:27], v[26:27], v[134:135]
	v_pk_mul_f32 v[22:23], v[22:23], v[138:139]
	v_pk_mul_f32 v[18:19], v[18:19], v[142:143]
	v_pk_mul_f32 v[16:17], v[16:17], v[140:141]
.Latt_u2_616:
	v_cndmask_b32_e64 v197, v149, v197, s[8:9]
	v_mul_f32_e32 v134, 0xbdd53b94, v197
	v_mov_b32_e32 v135, v134
	v_fmamk_f32 v80, v80, 0x3dd53b94, v134
	v_fmamk_f32 v81, v81, 0x3dd53b94, v134
	v_fmamk_f32 v82, v82, 0x3dd53b94, v134
	v_fmamk_f32 v83, v83, 0x3dd53b94, v134
	v_fmamk_f32 v84, v84, 0x3dd53b94, v134
	v_fmamk_f32 v85, v85, 0x3dd53b94, v134
	v_fmamk_f32 v86, v86, 0x3dd53b94, v134
	v_fmamk_f32 v87, v87, 0x3dd53b94, v134
	v_fmamk_f32 v88, v88, 0x3dd53b94, v134
	v_fmamk_f32 v89, v89, 0x3dd53b94, v134
	v_fmamk_f32 v90, v90, 0x3dd53b94, v134
	v_fmamk_f32 v91, v91, 0x3dd53b94, v134
	v_fmamk_f32 v92, v92, 0x3dd53b94, v134
	v_fmamk_f32 v93, v93, 0x3dd53b94, v134
	v_fmamk_f32 v94, v94, 0x3dd53b94, v134
	v_fmac_f32_e32 v135, 0x3dd53b94, v95
	v_exp_f32_e32 v162, v80
	v_exp_f32_e32 v205, v81
	v_exp_f32_e32 v149, v82
	v_exp_f32_e32 v163, v83
	v_exp_f32_e32 v150, v84
	v_exp_f32_e32 v161, v85
	v_exp_f32_e32 v151, v86
	v_exp_f32_e32 v160, v87
	v_exp_f32_e32 v152, v88
	v_exp_f32_e32 v155, v89
	v_exp_f32_e32 v153, v90
	v_exp_f32_e32 v154, v91
	v_exp_f32_e32 v145, v92
	v_exp_f32_e32 v147, v93
	v_exp_f32_e32 v144, v94
	v_exp_f32_e32 v146, v135
	v_pk_fma_f32 v[140:141], v[64:65], s[36:37], v[134:135] op_sel_hi:[1,0,0]
	v_add_f32_e32 v64, v202, v203
	v_fmac_f32_e32 v64, v194, v167
	v_add_f32_e32 v167, v206, v207
	s_add_i32 s3, s3, 2
	v_pk_fma_f32 v[138:139], v[66:67], s[36:37], v[134:135] op_sel_hi:[1,0,0]
	v_pk_fma_f32 v[132:133], v[68:69], s[36:37], v[134:135] op_sel_hi:[1,0,0]
	v_pk_fma_f32 v[130:131], v[70:71], s[36:37], v[134:135] op_sel_hi:[1,0,0]
	v_pk_fma_f32 v[128:129], v[72:73], s[36:37], v[134:135] op_sel_hi:[1,0,0]
	v_pk_fma_f32 v[142:143], v[74:75], s[36:37], v[134:135] op_sel_hi:[1,0,0]
	v_pk_fma_f32 v[136:137], v[76:77], s[36:37], v[134:135] op_sel_hi:[1,0,0]
	v_pk_fma_f32 v[134:135], v[78:79], s[36:37], v[134:135] op_sel_hi:[1,0,0]
	v_fmac_f32_e32 v167, v64, v204
	s_cmp_gt_u32 s3, 28
	s_waitcnt vmcnt(0)
	s_waitcnt lgkmcnt(0)
	s_barrier
	s_cbranch_scc1 .LBB0_618
	v_mov_b32_e32 v194, v148
	s_branch .LBB0_608
